# static s_setprio 1 for waves 4-7 before each GEMM K-loop, per-phase priority flips removed
# speedup vs baseline: 1.0147x; 1.0040x over previous
; #define PG8_STAGE(bufoff, gbase, voff) do { _Pragma("unroll") for (int _i = 0; _i < 2; ++_i) \
;         __builtin_amdgcn_global_load_lds((const unsigned*)((const char*)(gbase) + (voff)[_i]), (LAS unsigned*)(lds + (bufoff) + ldsw + _i * 8192), 16, 0, 0); } while (0)
; #define PG8_LDA(dst, b, h) do { _Pragma("unroll") for (int m = 0; m < 4; ++m) _Pragma("unroll") for (int k = 0; k < 2; ++k) dst[m][k] = *(const LAS bf16x8*)(lds + PG8_SA(b, h) + aoff + m * 2048 + k * 1024); } while (0)
; #define PG8_LDB(dst, b, h) do { _Pragma("unroll") for (int n = 0; n < 2; ++n) _Pragma("unroll") for (int k = 0; k < 2; ++k) dst[n][k] = *(const LAS bf16x8*)(lds + PG8_SB(b, h) + boff + n * 2048 + k * 1024); } while (0)
; #define PG8_MMA(ai, bj, At, Bt) do { __builtin_amdgcn_s_setprio(1); _Pragma("unroll") for (int m = 0; m < 4; ++m) _Pragma("unroll") for (int n = 0; n < 2; ++n) _Pragma("unroll") for (int k = 0; k < 2; ++k) \
;         acc[ai][bj][m][n] = __builtin_amdgcn_mfma_f32_16x16x32_bf16(Bt[n][k], At[m][k], acc[ai][bj][m][n], 0, 0, 0); __builtin_amdgcn_s_setprio(0); } while (0)
; #define PG8_WAIT_V(n) asm volatile("s_waitcnt vmcnt(" #n ")" ::: "memory")
; #define PG8_WAIT_L(n) asm volatile("s_waitcnt lgkmcnt(" #n ")" ::: "memory")
; template <class Epi>
; DI void gemm_phase(LAS unsigned char* lds, const Gemm g, const StaticOrder& S, const Epi& E) {
;     ...
;         const char* nA = has_next ? (const char*)g.A + (size_t)nxt.pm * tstep : cA; const char* nB = has_next ? (const char*)g.Bt + (size_t)nxt.pn * tstep : cB;
;         for (int t = 0; t < nt; t += 2) {
;             const bool last = (t == nt - 2);
;             const char* a1 = cA + (size_t)(t + 1) * kstep;
;             const char* a2 = last ? nA : cA + (size_t)(t + 2) * kstep; const char* b2 = last ? nB : cB + (size_t)(t + 2) * kstep;
;             const char* a3 = a2 + kstep; const char* b3 = b2 + kstep;
;             PG8_LDB(B0, 0, 0); PG8_LDB(B1, 0, 1); PG8_SCHED; PG8_LDA(At, 0, 0); PG8_STAGE(PG8_SA(1, 1), a1 + hstep, voffA);
;             PG8_WAIT_V(8); PG8_WAIT_L(0); PG8_BAR; PG8_MMA(0, 0, At, B0); PG8_MMA(0, 1, At, B1); PG8_BAR; PG8_SCHED;
;     ...
;         for (int a = 0; a < 2; ++a)
; #pragma unroll
;             for (int b = 0; b < 2; ++b)
; #pragma unroll
;                 for (int m = 0; m < 4; ++m)
; #pragma unroll
;                     for (int n = 0; n < 2; ++n) acc[a][b][m][n] = (f32x4){0.f, 0.f, 0.f, 0.f};
.LBB0_91:
	s_ashr_i32 s55, s54, 31
	s_lshl_b64 s[22:23], s[54:55], 19
	s_add_u32 s56, s24, s22
	s_addc_u32 s57, s25, s23
	s_and_b64 s[22:23], s[4:5], exec
	s_cselect_b32 s7, s57, s65
	s_cselect_b32 s17, s56, s64
	s_ashr_i32 s53, s52, 31
	s_lshl_b64 s[22:23], s[52:53], 19
	s_add_u32 s58, s30, s22
	s_addc_u32 s59, s31, s23
	s_and_b64 s[22:23], s[4:5], exec
	s_cselect_b32 s22, s59, s63
	s_cselect_b32 s23, s58, s62
	s_add_u32 s42, s62, 0x100
	s_addc_u32 s43, s63, 0
	s_add_u32 s62, s64, 0x40080
	v_mov_b32_e32 v2, 0
	s_addc_u32 s63, s65, 0
	s_mov_b32 s53, -2
	v_mov_b32_e32 v3, v2
	v_mov_b32_e32 v4, v2
	v_mov_b32_e32 v5, v2
	v_mov_b32_e32 v6, v2
	v_mov_b32_e32 v7, v2
	v_mov_b32_e32 v8, v2
	v_mov_b32_e32 v9, v2
	v_mov_b32_e32 v18, v2
	v_mov_b32_e32 v19, v2
	v_mov_b32_e32 v20, v2
	v_mov_b32_e32 v21, v2
	v_mov_b32_e32 v22, v2
	v_mov_b32_e32 v23, v2
	v_mov_b32_e32 v24, v2
	v_mov_b32_e32 v25, v2
	v_mov_b32_e32 v34, v2
	v_mov_b32_e32 v35, v2
	v_mov_b32_e32 v36, v2
	v_mov_b32_e32 v37, v2
	v_mov_b32_e32 v38, v2
	v_mov_b32_e32 v39, v2
	v_mov_b32_e32 v40, v2
	v_mov_b32_e32 v41, v2
	v_mov_b32_e32 v50, v2
	v_mov_b32_e32 v51, v2
	v_mov_b32_e32 v52, v2
	v_mov_b32_e32 v53, v2
	v_mov_b32_e32 v54, v2
	v_mov_b32_e32 v55, v2
	v_mov_b32_e32 v56, v2
	v_mov_b32_e32 v57, v2
	v_mov_b32_e32 v10, v2
	v_mov_b32_e32 v11, v2
	v_mov_b32_e32 v12, v2
	v_mov_b32_e32 v13, v2
	v_mov_b32_e32 v14, v2
	v_mov_b32_e32 v15, v2
	v_mov_b32_e32 v16, v2
	v_mov_b32_e32 v17, v2
	v_mov_b32_e32 v26, v2
	v_mov_b32_e32 v27, v2
	v_mov_b32_e32 v28, v2
	v_mov_b32_e32 v29, v2
	v_mov_b32_e32 v30, v2
	v_mov_b32_e32 v31, v2
	v_mov_b32_e32 v32, v2
	v_mov_b32_e32 v33, v2
	v_mov_b32_e32 v42, v2
	v_mov_b32_e32 v43, v2
	v_mov_b32_e32 v44, v2
	v_mov_b32_e32 v45, v2
	v_mov_b32_e32 v46, v2
	v_mov_b32_e32 v47, v2
	v_mov_b32_e32 v48, v2
	v_mov_b32_e32 v49, v2
	v_mov_b32_e32 v58, v2
	v_mov_b32_e32 v59, v2
	v_mov_b32_e32 v60, v2
	v_mov_b32_e32 v61, v2
	v_mov_b32_e32 v62, v2
	v_mov_b32_e32 v63, v2
	v_mov_b32_e32 v64, v2
	v_mov_b32_e32 v65, v2
	s_waitcnt vmcnt(0)
	v_mov_b32_e32 v70, v2
	v_mov_b32_e32 v71, v2
	v_mov_b32_e32 v72, v2
	v_mov_b32_e32 v73, v2
	v_mov_b32_e32 v74, v2
	v_mov_b32_e32 v75, v2
	v_mov_b32_e32 v76, v2
	v_mov_b32_e32 v77, v2
	v_mov_b32_e32 v90, v2
	v_mov_b32_e32 v91, v2
	v_mov_b32_e32 v92, v2
	v_mov_b32_e32 v93, v2
	v_mov_b32_e32 v94, v2
	v_mov_b32_e32 v95, v2
	v_mov_b32_e32 v96, v2
	v_mov_b32_e32 v97, v2
	v_mov_b32_e32 v110, v2
	v_mov_b32_e32 v111, v2
	v_mov_b32_e32 v112, v2
	v_mov_b32_e32 v113, v2
	v_mov_b32_e32 v114, v2
	v_mov_b32_e32 v115, v2
	v_mov_b32_e32 v116, v2
	v_mov_b32_e32 v117, v2
	v_mov_b32_e32 v130, v2
	v_mov_b32_e32 v131, v2
	v_mov_b32_e32 v132, v2
	v_mov_b32_e32 v133, v2
	v_mov_b32_e32 v134, v2
	v_mov_b32_e32 v135, v2
	v_mov_b32_e32 v136, v2
	v_mov_b32_e32 v137, v2
	v_mov_b32_e32 v82, v2
	v_mov_b32_e32 v83, v2
	v_mov_b32_e32 v84, v2
	v_mov_b32_e32 v85, v2
	v_mov_b32_e32 v86, v2
	v_mov_b32_e32 v87, v2
	v_mov_b32_e32 v88, v2
	v_mov_b32_e32 v89, v2
	v_mov_b32_e32 v102, v2
	v_mov_b32_e32 v103, v2
	v_mov_b32_e32 v104, v2
	v_mov_b32_e32 v105, v2
	v_mov_b32_e32 v106, v2
	v_mov_b32_e32 v107, v2
	v_mov_b32_e32 v108, v2
	v_mov_b32_e32 v109, v2
	v_mov_b32_e32 v122, v2
	v_mov_b32_e32 v123, v2
	v_mov_b32_e32 v124, v2
	v_mov_b32_e32 v125, v2
	v_mov_b32_e32 v126, v2
	v_mov_b32_e32 v127, v2
	v_mov_b32_e32 v128, v2
	v_mov_b32_e32 v129, v2
	v_mov_b32_e32 v146, v2
	v_mov_b32_e32 v147, v2
	v_mov_b32_e32 v148, v2
	v_mov_b32_e32 v149, v2
	v_mov_b32_e32 v150, v2
	v_mov_b32_e32 v151, v2
	v_mov_b32_e32 v152, v2
	v_mov_b32_e32 v153, v2
	v_readfirstlane_b32 s101, v242
	s_nop 3
	s_lshr_b32 s101, s101, 8
	s_cmp_eq_u32 s101, 1
	s_cbranch_scc0 .Lsp_5
	s_setprio 1
.Lsp_5:
.LBB0_92:
	s_add_u32 s18, s62, 0xfffc0080
	s_addc_u32 s19, s63, -1
	s_add_i32 s55, 0, 0x10000
	s_cmp_eq_u32 s53, 12
	s_cselect_b32 s67, s7, s19
	s_cselect_b32 s66, s17, s18
	s_cselect_b32 s65, s22, s43
	s_cselect_b32 s64, s23, s42
	s_add_i32 s18, 0, 0x14000
	v_add_u32_e32 v118, s55, v195
	v_add_u32_e32 v158, s18, v195
	ds_read_b128 v[66:69], v118
	ds_read_b128 v[78:81], v118 offset:1024
	ds_read_b128 v[98:101], v118 offset:2048
	ds_read_b128 v[118:121], v118 offset:3072
	ds_read_b128 v[138:141], v158
	ds_read_b128 v[142:145], v158 offset:1024
	ds_read_b128 v[154:157], v158 offset:2048
	ds_read_b128 v[158:161], v158 offset:3072
	v_lshl_add_u64 v[200:201], s[62:63], 0, v[222:223]
	s_add_i32 m0, s37, 0xc000
	ds_read_b128 v[162:165], v246
	ds_read_b128 v[166:169], v246 offset:1024
	ds_read_b128 v[170:173], v246 offset:2048
	ds_read_b128 v[174:177], v246 offset:3072
	ds_read_b128 v[178:181], v246 offset:4096
	ds_read_b128 v[182:185], v246 offset:5120
	ds_read_b128 v[186:189], v246 offset:6144
	ds_read_b128 v[190:193], v246 offset:7168
	global_load_lds_dwordx4 v[200:201], off
	v_lshl_add_u64 v[200:201], s[62:63], 0, v[220:221]
	s_add_i32 m0, s37, 0xe000
	s_nop 0
	global_load_lds_dwordx4 v[200:201], off
	s_waitcnt vmcnt(8)
	s_waitcnt lgkmcnt(0)
	s_barrier
; #define PG8_STAGE(bufoff, gbase, voff) do { _Pragma("unroll") for (int _i = 0; _i < 2; ++_i) \
;         __builtin_amdgcn_global_load_lds((const unsigned*)((const char*)(gbase) + (voff)[_i]), (LAS unsigned*)(lds + (bufoff) + ldsw + _i * 8192), 16, 0, 0); } while (0)
; #define PG8_LDA(dst, b, h) do { _Pragma("unroll") for (int m = 0; m < 4; ++m) _Pragma("unroll") for (int k = 0; k < 2; ++k) dst[m][k] = *(const LAS bf16x8*)(lds + PG8_SA(b, h) + aoff + m * 2048 + k * 1024); } while (0)
; #define PG8_MMA(ai, bj, At, Bt) do { __builtin_amdgcn_s_setprio(1); _Pragma("unroll") for (int m = 0; m < 4; ++m) _Pragma("unroll") for (int n = 0; n < 2; ++n) _Pragma("unroll") for (int k = 0; k < 2; ++k) \
;         acc[ai][bj][m][n] = __builtin_amdgcn_mfma_f32_16x16x32_bf16(Bt[n][k], At[m][k], acc[ai][bj][m][n], 0, 0, 0); __builtin_amdgcn_s_setprio(0); } while (0)
; #define PG8_WAIT_V(n) asm volatile("s_waitcnt vmcnt(" #n ")" ::: "memory")
; #define PG8_WAIT_L(n) asm volatile("s_waitcnt lgkmcnt(" #n ")" ::: "memory")
; #define PG8_BAR __builtin_amdgcn_s_barrier()
; #define PG8_SCHED __builtin_amdgcn_sched_barrier(0)
; template <class Epi>
; DI void gemm_phase(LAS unsigned char* lds, const Gemm g, const StaticOrder& S, const Epi& E) {
;     ...
;             PG8_WAIT_V(8); PG8_WAIT_L(0); PG8_BAR; PG8_MMA(0, 0, At, B0); PG8_MMA(0, 1, At, B1); PG8_BAR; PG8_SCHED;
;             PG8_LDA(At, 0, 1); PG8_STAGE(PG8_SB(0, 0), b2, voffB); PG8_STAGE(PG8_SB(0, 1), b2 + hstep, voffB); PG8_STAGE(PG8_SA(0, 0), a2, voffA);
;             PG8_WAIT_V(8); PG8_WAIT_L(0); PG8_BAR; PG8_MMA(1, 0, At, B0); PG8_MMA(1, 1, At, B1); PG8_BAR; PG8_SCHED;
	s_waitcnt lgkmcnt(0)
	v_mfma_f32_16x16x32_bf16 v[150:153], v[66:69], v[162:165], v[150:153]
	v_mfma_f32_16x16x32_bf16 v[146:149], v[98:101], v[162:165], v[146:149]
	v_mfma_f32_16x16x32_bf16 v[126:129], v[66:69], v[170:173], v[126:129]
	v_mfma_f32_16x16x32_bf16 v[122:125], v[98:101], v[170:173], v[122:125]
	v_mfma_f32_16x16x32_bf16 v[106:109], v[66:69], v[178:181], v[106:109]
	v_mfma_f32_16x16x32_bf16 v[102:105], v[98:101], v[178:181], v[102:105]
	v_mfma_f32_16x16x32_bf16 v[86:89], v[66:69], v[186:189], v[86:89]
	v_mfma_f32_16x16x32_bf16 v[82:85], v[98:101], v[186:189], v[82:85]
	v_mfma_f32_16x16x32_bf16 v[150:153], v[78:81], v[166:169], v[150:153]
	v_mfma_f32_16x16x32_bf16 v[146:149], v[118:121], v[166:169], v[146:149]
	v_mfma_f32_16x16x32_bf16 v[126:129], v[78:81], v[174:177], v[126:129]
	v_mfma_f32_16x16x32_bf16 v[122:125], v[118:121], v[174:177], v[122:125]
	v_mfma_f32_16x16x32_bf16 v[106:109], v[78:81], v[182:185], v[106:109]
	v_mfma_f32_16x16x32_bf16 v[102:105], v[118:121], v[182:185], v[102:105]
	v_mfma_f32_16x16x32_bf16 v[86:89], v[78:81], v[190:193], v[86:89]
	v_mfma_f32_16x16x32_bf16 v[82:85], v[118:121], v[190:193], v[82:85]
	v_mfma_f32_16x16x32_bf16 v[134:137], v[138:141], v[162:165], v[134:137]
	v_mfma_f32_16x16x32_bf16 v[130:133], v[154:157], v[162:165], v[130:133]
	v_mfma_f32_16x16x32_bf16 v[114:117], v[138:141], v[170:173], v[114:117]
	v_mfma_f32_16x16x32_bf16 v[110:113], v[154:157], v[170:173], v[110:113]
	v_mfma_f32_16x16x32_bf16 v[94:97], v[138:141], v[178:181], v[94:97]
	v_mfma_f32_16x16x32_bf16 v[90:93], v[154:157], v[178:181], v[90:93]
	v_mfma_f32_16x16x32_bf16 v[74:77], v[138:141], v[186:189], v[74:77]
	v_mfma_f32_16x16x32_bf16 v[70:73], v[154:157], v[186:189], v[70:73]
	v_mfma_f32_16x16x32_bf16 v[134:137], v[142:145], v[166:169], v[134:137]
	v_mfma_f32_16x16x32_bf16 v[130:133], v[158:161], v[166:169], v[130:133]
	v_mfma_f32_16x16x32_bf16 v[114:117], v[142:145], v[174:177], v[114:117]
	v_mfma_f32_16x16x32_bf16 v[110:113], v[158:161], v[174:177], v[110:113]
	v_mfma_f32_16x16x32_bf16 v[94:97], v[142:145], v[182:185], v[94:97]
	v_mfma_f32_16x16x32_bf16 v[90:93], v[158:161], v[182:185], v[90:93]
	v_mfma_f32_16x16x32_bf16 v[74:77], v[142:145], v[190:193], v[74:77]
	v_mfma_f32_16x16x32_bf16 v[70:73], v[158:161], v[190:193], v[70:73]
	s_barrier
	s_add_i32 s19, s55, s36
	v_lshl_add_u64 v[200:201], s[64:65], 0, v[208:209]
	s_mov_b32 m0, s19
	ds_read_b128 v[162:165], v246 offset:16384
	ds_read_b128 v[166:169], v246 offset:17408
	ds_read_b128 v[170:173], v246 offset:18432
	ds_read_b128 v[174:177], v246 offset:19456
	ds_read_b128 v[178:181], v246 offset:20480
	ds_read_b128 v[182:185], v246 offset:21504
	ds_read_b128 v[186:189], v246 offset:22528
	ds_read_b128 v[190:193], v246 offset:23552
	global_load_lds_dwordx4 v[200:201], off
	s_add_i32 m0, s19, 0x2000
	s_add_u32 s94, s64, 0x40000
	v_lshl_add_u64 v[202:203], s[64:65], 0, v[212:213]
	s_addc_u32 s95, s65, 0
	s_add_i32 s18, s18, s36
	global_load_lds_dwordx4 v[202:203], off
	v_lshl_add_u64 v[224:225], s[94:95], 0, v[208:209]
	s_mov_b32 m0, s18
	v_lshl_add_u64 v[226:227], s[66:67], 0, v[210:211]
	global_load_lds_dwordx4 v[224:225], off
	v_lshl_add_u64 v[224:225], s[94:95], 0, v[212:213]
	s_add_i32 m0, s18, 0x2000
	s_nop 0
	global_load_lds_dwordx4 v[224:225], off
	v_lshl_add_u64 v[224:225], s[66:67], 0, v[206:207]
	s_mov_b32 m0, s37
	s_nop 0
	global_load_lds_dwordx4 v[224:225], off
	s_mov_b32 m0, s61
	s_nop 0
	global_load_lds_dwordx4 v[226:227], off
	s_waitcnt vmcnt(8)
	s_waitcnt lgkmcnt(0)
	s_barrier
	s_waitcnt lgkmcnt(0)
	v_mfma_f32_16x16x32_bf16 v[62:65], v[66:69], v[162:165], v[62:65]
	v_mfma_f32_16x16x32_bf16 v[58:61], v[98:101], v[162:165], v[58:61]
	v_mfma_f32_16x16x32_bf16 v[46:49], v[66:69], v[170:173], v[46:49]
	v_mfma_f32_16x16x32_bf16 v[42:45], v[98:101], v[170:173], v[42:45]
	v_mfma_f32_16x16x32_bf16 v[30:33], v[66:69], v[178:181], v[30:33]
	v_mfma_f32_16x16x32_bf16 v[26:29], v[98:101], v[178:181], v[26:29]
	v_mfma_f32_16x16x32_bf16 v[14:17], v[66:69], v[186:189], v[14:17]
	v_mfma_f32_16x16x32_bf16 v[10:13], v[98:101], v[186:189], v[10:13]
	v_mfma_f32_16x16x32_bf16 v[62:65], v[78:81], v[166:169], v[62:65]
	v_mfma_f32_16x16x32_bf16 v[58:61], v[118:121], v[166:169], v[58:61]
	v_mfma_f32_16x16x32_bf16 v[46:49], v[78:81], v[174:177], v[46:49]
	v_mfma_f32_16x16x32_bf16 v[42:45], v[118:121], v[174:177], v[42:45]
	v_mfma_f32_16x16x32_bf16 v[30:33], v[78:81], v[182:185], v[30:33]
	v_mfma_f32_16x16x32_bf16 v[26:29], v[118:121], v[182:185], v[26:29]
	v_mfma_f32_16x16x32_bf16 v[14:17], v[78:81], v[190:193], v[14:17]
	v_mfma_f32_16x16x32_bf16 v[10:13], v[118:121], v[190:193], v[10:13]
	v_mfma_f32_16x16x32_bf16 v[54:57], v[138:141], v[162:165], v[54:57]
	v_mfma_f32_16x16x32_bf16 v[50:53], v[154:157], v[162:165], v[50:53]
	v_mfma_f32_16x16x32_bf16 v[38:41], v[138:141], v[170:173], v[38:41]
	v_mfma_f32_16x16x32_bf16 v[34:37], v[154:157], v[170:173], v[34:37]
	v_mfma_f32_16x16x32_bf16 v[22:25], v[138:141], v[178:181], v[22:25]
	v_mfma_f32_16x16x32_bf16 v[18:21], v[154:157], v[178:181], v[18:21]
	v_mfma_f32_16x16x32_bf16 v[6:9], v[138:141], v[186:189], v[6:9]
	v_mfma_f32_16x16x32_bf16 v[2:5], v[154:157], v[186:189], v[2:5]
	v_mfma_f32_16x16x32_bf16 v[54:57], v[142:145], v[166:169], v[54:57]
	v_mfma_f32_16x16x32_bf16 v[50:53], v[158:161], v[166:169], v[50:53]
	v_mfma_f32_16x16x32_bf16 v[38:41], v[142:145], v[174:177], v[38:41]
	v_mfma_f32_16x16x32_bf16 v[34:37], v[158:161], v[174:177], v[34:37]
	v_mfma_f32_16x16x32_bf16 v[22:25], v[142:145], v[182:185], v[22:25]
	v_mfma_f32_16x16x32_bf16 v[18:21], v[158:161], v[182:185], v[18:21]
	v_mfma_f32_16x16x32_bf16 v[6:9], v[142:145], v[190:193], v[6:9]
	v_mfma_f32_16x16x32_bf16 v[2:5], v[158:161], v[190:193], v[2:5]
	s_barrier
; #define PG8_STAGE(bufoff, gbase, voff) do { _Pragma("unroll") for (int _i = 0; _i < 2; ++_i) \
;         __builtin_amdgcn_global_load_lds((const unsigned*)((const char*)(gbase) + (voff)[_i]), (LAS unsigned*)(lds + (bufoff) + ldsw + _i * 8192), 16, 0, 0); } while (0)
; #define PG8_LDA(dst, b, h) do { _Pragma("unroll") for (int m = 0; m < 4; ++m) _Pragma("unroll") for (int k = 0; k < 2; ++k) dst[m][k] = *(const LAS bf16x8*)(lds + PG8_SA(b, h) + aoff + m * 2048 + k * 1024); } while (0)
; #define PG8_LDB(dst, b, h) do { _Pragma("unroll") for (int n = 0; n < 2; ++n) _Pragma("unroll") for (int k = 0; k < 2; ++k) dst[n][k] = *(const LAS bf16x8*)(lds + PG8_SB(b, h) + boff + n * 2048 + k * 1024); } while (0)
; #define PG8_MMA(ai, bj, At, Bt) do { __builtin_amdgcn_s_setprio(1); _Pragma("unroll") for (int m = 0; m < 4; ++m) _Pragma("unroll") for (int n = 0; n < 2; ++n) _Pragma("unroll") for (int k = 0; k < 2; ++k) \
;         acc[ai][bj][m][n] = __builtin_amdgcn_mfma_f32_16x16x32_bf16(Bt[n][k], At[m][k], acc[ai][bj][m][n], 0, 0, 0); __builtin_amdgcn_s_setprio(0); } while (0)
; #define PG8_WAIT_V(n) asm volatile("s_waitcnt vmcnt(" #n ")" ::: "memory")
; #define PG8_WAIT_L(n) asm volatile("s_waitcnt lgkmcnt(" #n ")" ::: "memory")
; #define PG8_BAR __builtin_amdgcn_s_barrier()
; #define PG8_SCHED __builtin_amdgcn_sched_barrier(0)
; template <class Epi>
; DI void gemm_phase(LAS unsigned char* lds, const Gemm g, const StaticOrder& S, const Epi& E) {
;     ...
;             PG8_LDB(B0, 1, 0); PG8_LDB(B1, 1, 1); PG8_SCHED; PG8_LDA(At, 1, 0); PG8_STAGE(PG8_SA(0, 1), a2 + hstep, voffA);
;             PG8_WAIT_V(8); PG8_WAIT_L(0); PG8_BAR; PG8_MMA(0, 0, At, B0); PG8_MMA(0, 1, At, B1); PG8_BAR; PG8_SCHED;
	s_add_i32 s18, 0, 0x18000
	s_add_i32 s19, 0, 0x1c000
	v_add_u32_e32 v118, s18, v195
	v_add_u32_e32 v158, s19, v195
	ds_read_b128 v[66:69], v118
	ds_read_b128 v[78:81], v118 offset:1024
	ds_read_b128 v[98:101], v118 offset:2048
	ds_read_b128 v[118:121], v118 offset:3072
	ds_read_b128 v[138:141], v158
	ds_read_b128 v[142:145], v158 offset:1024
	ds_read_b128 v[154:157], v158 offset:2048
	ds_read_b128 v[158:161], v158 offset:3072
	s_add_u32 s66, s66, 0x40000
	s_addc_u32 s67, s67, 0
	s_mov_b32 m0, s68
	v_lshl_add_u64 v[228:229], s[66:67], 0, v[206:207]
	ds_read_b128 v[162:165], v246 offset:32768
	ds_read_b128 v[166:169], v246 offset:33792
	ds_read_b128 v[170:173], v246 offset:34816
	ds_read_b128 v[174:177], v246 offset:35840
	ds_read_b128 v[178:181], v246 offset:36864
	ds_read_b128 v[182:185], v246 offset:37888
	ds_read_b128 v[186:189], v246 offset:38912
	ds_read_b128 v[190:193], v246 offset:39936
	global_load_lds_dwordx4 v[228:229], off
	v_lshl_add_u64 v[228:229], s[66:67], 0, v[210:211]
	s_mov_b32 m0, s69
	s_nop 0
	global_load_lds_dwordx4 v[228:229], off
	s_waitcnt vmcnt(8)
	s_waitcnt lgkmcnt(0)
	s_barrier
	s_waitcnt lgkmcnt(0)
	v_mfma_f32_16x16x32_bf16 v[150:153], v[66:69], v[162:165], v[150:153]
	v_mfma_f32_16x16x32_bf16 v[146:149], v[98:101], v[162:165], v[146:149]
	v_mfma_f32_16x16x32_bf16 v[126:129], v[66:69], v[170:173], v[126:129]
	v_mfma_f32_16x16x32_bf16 v[122:125], v[98:101], v[170:173], v[122:125]
	v_mfma_f32_16x16x32_bf16 v[106:109], v[66:69], v[178:181], v[106:109]
	v_mfma_f32_16x16x32_bf16 v[102:105], v[98:101], v[178:181], v[102:105]
	v_mfma_f32_16x16x32_bf16 v[86:89], v[66:69], v[186:189], v[86:89]
	v_mfma_f32_16x16x32_bf16 v[82:85], v[98:101], v[186:189], v[82:85]
	v_mfma_f32_16x16x32_bf16 v[150:153], v[78:81], v[166:169], v[150:153]
	v_mfma_f32_16x16x32_bf16 v[146:149], v[118:121], v[166:169], v[146:149]
	v_mfma_f32_16x16x32_bf16 v[126:129], v[78:81], v[174:177], v[126:129]
	v_mfma_f32_16x16x32_bf16 v[122:125], v[118:121], v[174:177], v[122:125]
	v_mfma_f32_16x16x32_bf16 v[106:109], v[78:81], v[182:185], v[106:109]
	v_mfma_f32_16x16x32_bf16 v[102:105], v[118:121], v[182:185], v[102:105]
	v_mfma_f32_16x16x32_bf16 v[86:89], v[78:81], v[190:193], v[86:89]
	v_mfma_f32_16x16x32_bf16 v[82:85], v[118:121], v[190:193], v[82:85]
	v_mfma_f32_16x16x32_bf16 v[134:137], v[138:141], v[162:165], v[134:137]
	v_mfma_f32_16x16x32_bf16 v[130:133], v[154:157], v[162:165], v[130:133]
	v_mfma_f32_16x16x32_bf16 v[114:117], v[138:141], v[170:173], v[114:117]
	v_mfma_f32_16x16x32_bf16 v[110:113], v[154:157], v[170:173], v[110:113]
	v_mfma_f32_16x16x32_bf16 v[94:97], v[138:141], v[178:181], v[94:97]
	v_mfma_f32_16x16x32_bf16 v[90:93], v[154:157], v[178:181], v[90:93]
	v_mfma_f32_16x16x32_bf16 v[74:77], v[138:141], v[186:189], v[74:77]
	v_mfma_f32_16x16x32_bf16 v[70:73], v[154:157], v[186:189], v[70:73]
	v_mfma_f32_16x16x32_bf16 v[134:137], v[142:145], v[166:169], v[134:137]
	v_mfma_f32_16x16x32_bf16 v[130:133], v[158:161], v[166:169], v[130:133]
	v_mfma_f32_16x16x32_bf16 v[114:117], v[142:145], v[174:177], v[114:117]
	v_mfma_f32_16x16x32_bf16 v[110:113], v[158:161], v[174:177], v[110:113]
	v_mfma_f32_16x16x32_bf16 v[94:97], v[142:145], v[182:185], v[94:97]
	v_mfma_f32_16x16x32_bf16 v[90:93], v[158:161], v[182:185], v[90:93]
	v_mfma_f32_16x16x32_bf16 v[74:77], v[142:145], v[190:193], v[74:77]
	v_mfma_f32_16x16x32_bf16 v[70:73], v[158:161], v[190:193], v[70:73]
	s_barrier
; #define PG8_STAGE(bufoff, gbase, voff) do { _Pragma("unroll") for (int _i = 0; _i < 2; ++_i) \
;         __builtin_amdgcn_global_load_lds((const unsigned*)((const char*)(gbase) + (voff)[_i]), (LAS unsigned*)(lds + (bufoff) + ldsw + _i * 8192), 16, 0, 0); } while (0)
; #define PG8_LDA(dst, b, h) do { _Pragma("unroll") for (int m = 0; m < 4; ++m) _Pragma("unroll") for (int k = 0; k < 2; ++k) dst[m][k] = *(const LAS bf16x8*)(lds + PG8_SA(b, h) + aoff + m * 2048 + k * 1024); } while (0)
; #define PG8_MMA(ai, bj, At, Bt) do { __builtin_amdgcn_s_setprio(1); _Pragma("unroll") for (int m = 0; m < 4; ++m) _Pragma("unroll") for (int n = 0; n < 2; ++n) _Pragma("unroll") for (int k = 0; k < 2; ++k) \
;         acc[ai][bj][m][n] = __builtin_amdgcn_mfma_f32_16x16x32_bf16(Bt[n][k], At[m][k], acc[ai][bj][m][n], 0, 0, 0); __builtin_amdgcn_s_setprio(0); } while (0)
; #define PG8_WAIT_V(n) asm volatile("s_waitcnt vmcnt(" #n ")" ::: "memory")
; #define PG8_WAIT_L(n) asm volatile("s_waitcnt lgkmcnt(" #n ")" ::: "memory")
; #define PG8_BAR __builtin_amdgcn_s_barrier()
; #define PG8_SCHED __builtin_amdgcn_sched_barrier(0)
; template <class Epi>
; DI void gemm_phase(LAS unsigned char* lds, const Gemm g, const StaticOrder& S, const Epi& E) {
;     ...
;             PG8_LDA(At, 1, 1); PG8_STAGE(PG8_SB(1, 0), b3, voffB); PG8_STAGE(PG8_SB(1, 1), b3 + hstep, voffB); PG8_STAGE(PG8_SA(1, 0), a3, voffA);
;             PG8_WAIT_V(8); PG8_WAIT_L(0); PG8_BAR; PG8_MMA(1, 0, At, B0); PG8_MMA(1, 1, At, B1); PG8_BAR; PG8_SCHED;
;         }
;         if (wr == 0) PG8_BAR;
	s_add_i32 s18, s18, s36
	v_lshl_add_u64 v[200:201], v[200:201], 0, s[20:21]
	s_mov_b32 m0, s18
	ds_read_b128 v[162:165], v246 offset:49152
	ds_read_b128 v[166:169], v246 offset:50176
	ds_read_b128 v[170:173], v246 offset:51200
	ds_read_b128 v[174:177], v246 offset:52224
	ds_read_b128 v[178:181], v246 offset:53248
	ds_read_b128 v[182:185], v246 offset:54272
	ds_read_b128 v[186:189], v246 offset:55296
	ds_read_b128 v[190:193], v246 offset:56320
	global_load_lds_dwordx4 v[200:201], off
	s_add_i32 m0, s18, 0x2000
	s_add_u32 s64, s64, 0x40080
	v_lshl_add_u64 v[200:201], v[202:203], 0, s[20:21]
	s_addc_u32 s65, s65, 0
	s_add_i32 s18, s19, s36
	global_load_lds_dwordx4 v[200:201], off
	v_lshl_add_u64 v[200:201], s[64:65], 0, v[208:209]
	s_mov_b32 m0, s18
	s_nop 0
	global_load_lds_dwordx4 v[200:201], off
	v_lshl_add_u64 v[200:201], s[64:65], 0, v[212:213]
	s_add_i32 m0, s18, 0x2000
	s_nop 0
	global_load_lds_dwordx4 v[200:201], off
	v_lshl_add_u64 v[200:201], v[224:225], 0, s[20:21]
	s_mov_b32 m0, s70
	s_nop 0
	global_load_lds_dwordx4 v[200:201], off
	v_lshl_add_u64 v[200:201], v[226:227], 0, s[20:21]
	s_mov_b32 m0, s71
	s_nop 0
	global_load_lds_dwordx4 v[200:201], off
	s_waitcnt vmcnt(8)
	s_waitcnt lgkmcnt(0)
	s_barrier
	s_waitcnt lgkmcnt(0)
	v_mfma_f32_16x16x32_bf16 v[62:65], v[66:69], v[162:165], v[62:65]
	v_mfma_f32_16x16x32_bf16 v[58:61], v[98:101], v[162:165], v[58:61]
	v_mfma_f32_16x16x32_bf16 v[46:49], v[66:69], v[170:173], v[46:49]
	v_mfma_f32_16x16x32_bf16 v[42:45], v[98:101], v[170:173], v[42:45]
	v_mfma_f32_16x16x32_bf16 v[30:33], v[66:69], v[178:181], v[30:33]
	v_mfma_f32_16x16x32_bf16 v[26:29], v[98:101], v[178:181], v[26:29]
	v_mfma_f32_16x16x32_bf16 v[14:17], v[66:69], v[186:189], v[14:17]
	v_mfma_f32_16x16x32_bf16 v[10:13], v[98:101], v[186:189], v[10:13]
	v_mfma_f32_16x16x32_bf16 v[62:65], v[78:81], v[166:169], v[62:65]
	v_mfma_f32_16x16x32_bf16 v[58:61], v[118:121], v[166:169], v[58:61]
	v_mfma_f32_16x16x32_bf16 v[46:49], v[78:81], v[174:177], v[46:49]
	v_mfma_f32_16x16x32_bf16 v[42:45], v[118:121], v[174:177], v[42:45]
	v_mfma_f32_16x16x32_bf16 v[30:33], v[78:81], v[182:185], v[30:33]
	v_mfma_f32_16x16x32_bf16 v[26:29], v[118:121], v[182:185], v[26:29]
	v_mfma_f32_16x16x32_bf16 v[14:17], v[78:81], v[190:193], v[14:17]
	v_mfma_f32_16x16x32_bf16 v[10:13], v[118:121], v[190:193], v[10:13]
	v_mfma_f32_16x16x32_bf16 v[54:57], v[138:141], v[162:165], v[54:57]
	v_mfma_f32_16x16x32_bf16 v[50:53], v[154:157], v[162:165], v[50:53]
	v_mfma_f32_16x16x32_bf16 v[38:41], v[138:141], v[170:173], v[38:41]
	v_mfma_f32_16x16x32_bf16 v[34:37], v[154:157], v[170:173], v[34:37]
	v_mfma_f32_16x16x32_bf16 v[22:25], v[138:141], v[178:181], v[22:25]
	v_mfma_f32_16x16x32_bf16 v[18:21], v[154:157], v[178:181], v[18:21]
	v_mfma_f32_16x16x32_bf16 v[6:9], v[138:141], v[186:189], v[6:9]
	v_mfma_f32_16x16x32_bf16 v[2:5], v[154:157], v[186:189], v[2:5]
	v_mfma_f32_16x16x32_bf16 v[54:57], v[142:145], v[166:169], v[54:57]
	v_mfma_f32_16x16x32_bf16 v[50:53], v[158:161], v[166:169], v[50:53]
	v_mfma_f32_16x16x32_bf16 v[38:41], v[142:145], v[174:177], v[38:41]
	v_mfma_f32_16x16x32_bf16 v[34:37], v[158:161], v[174:177], v[34:37]
	v_mfma_f32_16x16x32_bf16 v[22:25], v[142:145], v[182:185], v[22:25]
	v_mfma_f32_16x16x32_bf16 v[18:21], v[158:161], v[182:185], v[18:21]
	v_mfma_f32_16x16x32_bf16 v[6:9], v[142:145], v[190:193], v[6:9]
	v_mfma_f32_16x16x32_bf16 v[2:5], v[158:161], v[190:193], v[2:5]
	s_barrier
	s_add_i32 s53, s53, 2
	s_add_u32 s42, s42, 0x100
	s_addc_u32 s43, s43, 0
	s_add_u32 s62, s62, 0x100
	s_addc_u32 s63, s63, 0
	s_cmp_gt_u32 s53, 13
	s_cbranch_scc0 .LBB0_92
	s_setprio 0
	s_and_b64 vcc, exec, s[50:51]
	s_cbranch_vccz .LBB0_95
	s_barrier

; #define PG8_STAGE(bufoff, gbase, voff) do { _Pragma("unroll") for (int _i = 0; _i < 2; ++_i) \
;         __builtin_amdgcn_global_load_lds((const unsigned*)((const char*)(gbase) + (voff)[_i]), (LAS unsigned*)(lds + (bufoff) + ldsw + _i * 8192), 16, 0, 0); } while (0)
; #define PG8_LDA(dst, b, h) do { _Pragma("unroll") for (int m = 0; m < 4; ++m) _Pragma("unroll") for (int k = 0; k < 2; ++k) dst[m][k] = *(const LAS bf16x8*)(lds + PG8_SA(b, h) + aoff + m * 2048 + k * 1024); } while (0)
; #define PG8_LDB(dst, b, h) do { _Pragma("unroll") for (int n = 0; n < 2; ++n) _Pragma("unroll") for (int k = 0; k < 2; ++k) dst[n][k] = *(const LAS bf16x8*)(lds + PG8_SB(b, h) + boff + n * 2048 + k * 1024); } while (0)
; #define PG8_MMA(ai, bj, At, Bt) do { __builtin_amdgcn_s_setprio(1); _Pragma("unroll") for (int m = 0; m < 4; ++m) _Pragma("unroll") for (int n = 0; n < 2; ++n) _Pragma("unroll") for (int k = 0; k < 2; ++k) \
;         acc[ai][bj][m][n] = __builtin_amdgcn_mfma_f32_16x16x32_bf16(Bt[n][k], At[m][k], acc[ai][bj][m][n], 0, 0, 0); __builtin_amdgcn_s_setprio(0); } while (0)
; #define PG8_WAIT_V(n) asm volatile("s_waitcnt vmcnt(" #n ")" ::: "memory")
; #define PG8_WAIT_L(n) asm volatile("s_waitcnt lgkmcnt(" #n ")" ::: "memory")
; template <class Epi>
; DI void gemm_phase(LAS unsigned char* lds, const Gemm g, const StaticOrder& S, const Epi& E) {
;     ...
;         const char* nA = has_next ? (const char*)g.A + (size_t)nxt.pm * tstep : cA; const char* nB = has_next ? (const char*)g.Bt + (size_t)nxt.pn * tstep : cB;
;         for (int t = 0; t < nt; t += 2) {
;             const bool last = (t == nt - 2);
;             const char* a1 = cA + (size_t)(t + 1) * kstep;
;             const char* a2 = last ? nA : cA + (size_t)(t + 2) * kstep; const char* b2 = last ? nB : cB + (size_t)(t + 2) * kstep;
;             const char* a3 = a2 + kstep; const char* b3 = b2 + kstep;
;             PG8_LDB(B0, 0, 0); PG8_LDB(B1, 0, 1); PG8_SCHED; PG8_LDA(At, 0, 0); PG8_STAGE(PG8_SA(1, 1), a1 + hstep, voffA);
;             PG8_WAIT_V(8); PG8_WAIT_L(0); PG8_BAR; PG8_MMA(0, 0, At, B0); PG8_MMA(0, 1, At, B1); PG8_BAR; PG8_SCHED;
;     ...
;         for (int a = 0; a < 2; ++a)
; #pragma unroll
;             for (int b = 0; b < 2; ++b)
; #pragma unroll
;                 for (int m = 0; m < 4; ++m)
; #pragma unroll
;                     for (int n = 0; n < 2; ++n) acc[a][b][m][n] = (f32x4){0.f, 0.f, 0.f, 0.f};
.LBB0_514:
	s_ashr_i32 s57, s56, 31
	s_lshl_b64 s[22:23], s[56:57], 19
	s_add_u32 s58, s72, s22
	s_addc_u32 s59, s73, s23
	s_and_b64 s[22:23], s[4:5], exec
	s_cselect_b32 s22, s59, s67
	s_cselect_b32 s23, s58, s66
	s_ashr_i32 s55, s54, 31
	s_lshl_b64 s[42:43], s[54:55], 19
	s_add_u32 s60, s95, s42
	s_addc_u32 s61, s30, s43
	s_and_b64 s[42:43], s[4:5], exec
	s_cselect_b32 s42, s61, s65
	s_cselect_b32 s43, s60, s64
	s_add_u32 s55, s64, 0x100
	s_addc_u32 s57, s65, 0
	s_add_u32 s64, s66, 0x40080
	v_mov_b32_e32 v2, 0
	s_addc_u32 s65, s67, 0
	s_mov_b32 s63, -2
	v_mov_b32_e32 v3, v2
	v_mov_b32_e32 v4, v2
	v_mov_b32_e32 v5, v2
	v_mov_b32_e32 v6, v2
	v_mov_b32_e32 v7, v2
	v_mov_b32_e32 v8, v2
	v_mov_b32_e32 v9, v2
	v_mov_b32_e32 v18, v2
	v_mov_b32_e32 v19, v2
	v_mov_b32_e32 v20, v2
	v_mov_b32_e32 v21, v2
	v_mov_b32_e32 v22, v2
	v_mov_b32_e32 v23, v2
	v_mov_b32_e32 v24, v2
	v_mov_b32_e32 v25, v2
	v_mov_b32_e32 v34, v2
	v_mov_b32_e32 v35, v2
	v_mov_b32_e32 v36, v2
	v_mov_b32_e32 v37, v2
	v_mov_b32_e32 v38, v2
	v_mov_b32_e32 v39, v2
	v_mov_b32_e32 v40, v2
	v_mov_b32_e32 v41, v2
	v_mov_b32_e32 v66, v2
	v_mov_b32_e32 v67, v2
	v_mov_b32_e32 v68, v2
	v_mov_b32_e32 v69, v2
	v_mov_b32_e32 v70, v2
	v_mov_b32_e32 v71, v2
	v_mov_b32_e32 v72, v2
	v_mov_b32_e32 v73, v2
	v_mov_b32_e32 v10, v2
	v_mov_b32_e32 v11, v2
	v_mov_b32_e32 v12, v2
	v_mov_b32_e32 v13, v2
	v_mov_b32_e32 v14, v2
	v_mov_b32_e32 v15, v2
	v_mov_b32_e32 v16, v2
	v_mov_b32_e32 v17, v2
	v_mov_b32_e32 v26, v2
	v_mov_b32_e32 v27, v2
	v_mov_b32_e32 v28, v2
	v_mov_b32_e32 v29, v2
	v_mov_b32_e32 v30, v2
	v_mov_b32_e32 v31, v2
	v_mov_b32_e32 v32, v2
	v_mov_b32_e32 v33, v2
	v_mov_b32_e32 v50, v2
	v_mov_b32_e32 v51, v2
	v_mov_b32_e32 v52, v2
	v_mov_b32_e32 v53, v2
	v_mov_b32_e32 v54, v2
	v_mov_b32_e32 v55, v2
	v_mov_b32_e32 v56, v2
	v_mov_b32_e32 v57, v2
	v_mov_b32_e32 v74, v2
	v_mov_b32_e32 v75, v2
	v_mov_b32_e32 v76, v2
	v_mov_b32_e32 v77, v2
	v_mov_b32_e32 v78, v2
	v_mov_b32_e32 v79, v2
	v_mov_b32_e32 v80, v2
	v_mov_b32_e32 v81, v2
	v_mov_b32_e32 v82, v2
	v_mov_b32_e32 v83, v2
	v_mov_b32_e32 v84, v2
	v_mov_b32_e32 v85, v2
	v_mov_b32_e32 v86, v2
	v_mov_b32_e32 v87, v2
	v_mov_b32_e32 v88, v2
	v_mov_b32_e32 v89, v2
	v_mov_b32_e32 v98, v2
	v_mov_b32_e32 v99, v2
	v_mov_b32_e32 v100, v2
	v_mov_b32_e32 v101, v2
	v_mov_b32_e32 v102, v2
	v_mov_b32_e32 v103, v2
	v_mov_b32_e32 v104, v2
	v_mov_b32_e32 v105, v2
	v_mov_b32_e32 v114, v2
	v_mov_b32_e32 v115, v2
	v_mov_b32_e32 v116, v2
	v_mov_b32_e32 v117, v2
	v_mov_b32_e32 v118, v2
	v_mov_b32_e32 v119, v2
	v_mov_b32_e32 v120, v2
	v_mov_b32_e32 v121, v2
	v_mov_b32_e32 v130, v2
	v_mov_b32_e32 v131, v2
	v_mov_b32_e32 v132, v2
	v_mov_b32_e32 v133, v2
	v_mov_b32_e32 v134, v2
	v_mov_b32_e32 v135, v2
	v_mov_b32_e32 v136, v2
	v_mov_b32_e32 v137, v2
	v_mov_b32_e32 v90, v2
	v_mov_b32_e32 v91, v2
	v_mov_b32_e32 v92, v2
	v_mov_b32_e32 v93, v2
	v_mov_b32_e32 v94, v2
	v_mov_b32_e32 v95, v2
	v_mov_b32_e32 v96, v2
	v_mov_b32_e32 v97, v2
	v_mov_b32_e32 v106, v2
	v_mov_b32_e32 v107, v2
	v_mov_b32_e32 v108, v2
	v_mov_b32_e32 v109, v2
	v_mov_b32_e32 v110, v2
	v_mov_b32_e32 v111, v2
	v_mov_b32_e32 v112, v2
	v_mov_b32_e32 v113, v2
	v_mov_b32_e32 v122, v2
	v_mov_b32_e32 v123, v2
	v_mov_b32_e32 v124, v2
	v_mov_b32_e32 v125, v2
	v_mov_b32_e32 v126, v2
	v_mov_b32_e32 v127, v2
	v_mov_b32_e32 v128, v2
	v_mov_b32_e32 v129, v2
	v_mov_b32_e32 v146, v2
	v_mov_b32_e32 v147, v2
	v_mov_b32_e32 v148, v2
	v_mov_b32_e32 v149, v2
	v_mov_b32_e32 v150, v2
	v_mov_b32_e32 v151, v2
	v_mov_b32_e32 v152, v2
	v_mov_b32_e32 v153, v2
	v_readfirstlane_b32 s101, v242
	s_nop 3
	s_lshr_b32 s101, s101, 8
	s_cmp_eq_u32 s101, 1
	s_cbranch_scc0 .Lsp_4
	s_setprio 1
.Lsp_4:
.LBB0_515:
	s_add_u32 s18, s64, 0xfffc0080
	s_addc_u32 s19, s65, -1
	s_add_i32 s91, 0, 0x10000
	s_cmp_eq_u32 s63, 12
	s_cselect_b32 s69, s22, s19
	s_cselect_b32 s68, s23, s18
	s_cselect_b32 s67, s42, s57
	s_cselect_b32 s66, s43, s55
	s_add_i32 s18, 0, 0x14000
	v_add_u32_e32 v62, s91, v180
	v_add_u32_e32 v170, s18, v180
	ds_read_b128 v[42:45], v62
	ds_read_b128 v[46:49], v62 offset:1024
	ds_read_b128 v[58:61], v62 offset:2048
	ds_read_b128 v[62:65], v62 offset:3072
	ds_read_b128 v[138:141], v170
	ds_read_b128 v[142:145], v170 offset:1024
	ds_read_b128 v[154:157], v170 offset:2048
	ds_read_b128 v[170:173], v170 offset:3072
	v_lshl_add_u64 v[178:179], s[64:65], 0, v[168:169]
	s_add_i32 m0, s94, 0xc000
	ds_read_b128 v[174:177], v182
	ds_read_b128 v[184:187], v182 offset:1024
	ds_read_b128 v[188:191], v182 offset:2048
	ds_read_b128 v[200:203], v182 offset:3072
	ds_read_b128 v[206:209], v182 offset:4096
	ds_read_b128 v[210:213], v182 offset:5120
	ds_read_b128 v[214:217], v182 offset:6144
	ds_read_b128 v[218:221], v182 offset:7168
	global_load_lds_dwordx4 v[178:179], off
	v_lshl_add_u64 v[178:179], s[64:65], 0, v[166:167]
	s_add_i32 m0, s94, 0xe000
	s_nop 0
	global_load_lds_dwordx4 v[178:179], off
	s_waitcnt vmcnt(8)
	s_waitcnt lgkmcnt(0)
	s_barrier
; #define PG8_STAGE(bufoff, gbase, voff) do { _Pragma("unroll") for (int _i = 0; _i < 2; ++_i) \
;         __builtin_amdgcn_global_load_lds((const unsigned*)((const char*)(gbase) + (voff)[_i]), (LAS unsigned*)(lds + (bufoff) + ldsw + _i * 8192), 16, 0, 0); } while (0)
; #define PG8_LDA(dst, b, h) do { _Pragma("unroll") for (int m = 0; m < 4; ++m) _Pragma("unroll") for (int k = 0; k < 2; ++k) dst[m][k] = *(const LAS bf16x8*)(lds + PG8_SA(b, h) + aoff + m * 2048 + k * 1024); } while (0)
; #define PG8_MMA(ai, bj, At, Bt) do { __builtin_amdgcn_s_setprio(1); _Pragma("unroll") for (int m = 0; m < 4; ++m) _Pragma("unroll") for (int n = 0; n < 2; ++n) _Pragma("unroll") for (int k = 0; k < 2; ++k) \
;         acc[ai][bj][m][n] = __builtin_amdgcn_mfma_f32_16x16x32_bf16(Bt[n][k], At[m][k], acc[ai][bj][m][n], 0, 0, 0); __builtin_amdgcn_s_setprio(0); } while (0)
; #define PG8_WAIT_V(n) asm volatile("s_waitcnt vmcnt(" #n ")" ::: "memory")
; #define PG8_WAIT_L(n) asm volatile("s_waitcnt lgkmcnt(" #n ")" ::: "memory")
; #define PG8_BAR __builtin_amdgcn_s_barrier()
; #define PG8_SCHED __builtin_amdgcn_sched_barrier(0)
; template <class Epi>
; DI void gemm_phase(LAS unsigned char* lds, const Gemm g, const StaticOrder& S, const Epi& E) {
;     ...
;             PG8_WAIT_V(8); PG8_WAIT_L(0); PG8_BAR; PG8_MMA(0, 0, At, B0); PG8_MMA(0, 1, At, B1); PG8_BAR; PG8_SCHED;
;             PG8_LDA(At, 0, 1); PG8_STAGE(PG8_SB(0, 0), b2, voffB); PG8_STAGE(PG8_SB(0, 1), b2 + hstep, voffB); PG8_STAGE(PG8_SA(0, 0), a2, voffA);
;             PG8_WAIT_V(8); PG8_WAIT_L(0); PG8_BAR; PG8_MMA(1, 0, At, B0); PG8_MMA(1, 1, At, B1); PG8_BAR; PG8_SCHED;
	s_waitcnt lgkmcnt(0)
	v_mfma_f32_16x16x32_bf16 v[150:153], v[42:45], v[174:177], v[150:153]
	v_mfma_f32_16x16x32_bf16 v[146:149], v[58:61], v[174:177], v[146:149]
	v_mfma_f32_16x16x32_bf16 v[126:129], v[42:45], v[188:191], v[126:129]
	v_mfma_f32_16x16x32_bf16 v[122:125], v[58:61], v[188:191], v[122:125]
	v_mfma_f32_16x16x32_bf16 v[110:113], v[42:45], v[206:209], v[110:113]
	v_mfma_f32_16x16x32_bf16 v[106:109], v[58:61], v[206:209], v[106:109]
	v_mfma_f32_16x16x32_bf16 v[94:97], v[42:45], v[214:217], v[94:97]
	v_mfma_f32_16x16x32_bf16 v[90:93], v[58:61], v[214:217], v[90:93]
	v_mfma_f32_16x16x32_bf16 v[150:153], v[46:49], v[184:187], v[150:153]
	v_mfma_f32_16x16x32_bf16 v[146:149], v[62:65], v[184:187], v[146:149]
	v_mfma_f32_16x16x32_bf16 v[126:129], v[46:49], v[200:203], v[126:129]
	v_mfma_f32_16x16x32_bf16 v[122:125], v[62:65], v[200:203], v[122:125]
	v_mfma_f32_16x16x32_bf16 v[110:113], v[46:49], v[210:213], v[110:113]
	v_mfma_f32_16x16x32_bf16 v[106:109], v[62:65], v[210:213], v[106:109]
	v_mfma_f32_16x16x32_bf16 v[94:97], v[46:49], v[218:221], v[94:97]
	v_mfma_f32_16x16x32_bf16 v[90:93], v[62:65], v[218:221], v[90:93]
	v_mfma_f32_16x16x32_bf16 v[134:137], v[138:141], v[174:177], v[134:137]
	v_mfma_f32_16x16x32_bf16 v[130:133], v[154:157], v[174:177], v[130:133]
	v_mfma_f32_16x16x32_bf16 v[118:121], v[138:141], v[188:191], v[118:121]
	v_mfma_f32_16x16x32_bf16 v[114:117], v[154:157], v[188:191], v[114:117]
	v_mfma_f32_16x16x32_bf16 v[102:105], v[138:141], v[206:209], v[102:105]
	v_mfma_f32_16x16x32_bf16 v[98:101], v[154:157], v[206:209], v[98:101]
	v_mfma_f32_16x16x32_bf16 v[86:89], v[138:141], v[214:217], v[86:89]
	v_mfma_f32_16x16x32_bf16 v[82:85], v[154:157], v[214:217], v[82:85]
	v_mfma_f32_16x16x32_bf16 v[134:137], v[142:145], v[184:187], v[134:137]
	v_mfma_f32_16x16x32_bf16 v[130:133], v[170:173], v[184:187], v[130:133]
	v_mfma_f32_16x16x32_bf16 v[118:121], v[142:145], v[200:203], v[118:121]
	v_mfma_f32_16x16x32_bf16 v[114:117], v[170:173], v[200:203], v[114:117]
	v_mfma_f32_16x16x32_bf16 v[102:105], v[142:145], v[210:213], v[102:105]
	v_mfma_f32_16x16x32_bf16 v[98:101], v[170:173], v[210:213], v[98:101]
	v_mfma_f32_16x16x32_bf16 v[86:89], v[142:145], v[218:221], v[86:89]
	v_mfma_f32_16x16x32_bf16 v[82:85], v[170:173], v[218:221], v[82:85]
	s_barrier
	s_add_i32 s19, s91, s31
	v_lshl_add_u64 v[178:179], s[66:67], 0, v[160:161]
	s_mov_b32 m0, s19
	ds_read_b128 v[174:177], v182 offset:16384
	ds_read_b128 v[184:187], v182 offset:17408
	ds_read_b128 v[188:191], v182 offset:18432
	ds_read_b128 v[200:203], v182 offset:19456
	ds_read_b128 v[206:209], v182 offset:20480
	ds_read_b128 v[210:213], v182 offset:21504
	ds_read_b128 v[214:217], v182 offset:22528
	ds_read_b128 v[218:221], v182 offset:23552
	global_load_lds_dwordx4 v[178:179], off
	s_add_i32 m0, s19, 0x2000
	s_add_u32 vcc_lo, s66, 0x40000
	v_lshl_add_u64 v[192:193], s[66:67], 0, v[164:165]
	s_addc_u32 vcc_hi, s67, 0
	s_add_i32 s18, s18, s31
	global_load_lds_dwordx4 v[192:193], off
	v_lshl_add_u64 v[204:205], vcc, 0, v[160:161]
	s_mov_b32 m0, s18
	v_lshl_add_u64 v[222:223], s[68:69], 0, v[162:163]
	global_load_lds_dwordx4 v[204:205], off
	v_lshl_add_u64 v[204:205], vcc, 0, v[164:165]
	s_add_i32 m0, s18, 0x2000
	s_nop 0
	global_load_lds_dwordx4 v[204:205], off
	v_lshl_add_u64 v[204:205], s[68:69], 0, v[158:159]
	s_mov_b32 m0, s94
	s_nop 0
	global_load_lds_dwordx4 v[204:205], off
	s_mov_b32 m0, s93
	s_nop 0
	global_load_lds_dwordx4 v[222:223], off
	s_waitcnt vmcnt(8)
	s_waitcnt lgkmcnt(0)
	s_barrier
	s_waitcnt lgkmcnt(0)
	v_mfma_f32_16x16x32_bf16 v[78:81], v[42:45], v[174:177], v[78:81]
	v_mfma_f32_16x16x32_bf16 v[74:77], v[58:61], v[174:177], v[74:77]
	v_mfma_f32_16x16x32_bf16 v[54:57], v[42:45], v[188:191], v[54:57]
	v_mfma_f32_16x16x32_bf16 v[50:53], v[58:61], v[188:191], v[50:53]
	v_mfma_f32_16x16x32_bf16 v[30:33], v[42:45], v[206:209], v[30:33]
	v_mfma_f32_16x16x32_bf16 v[26:29], v[58:61], v[206:209], v[26:29]
	v_mfma_f32_16x16x32_bf16 v[14:17], v[42:45], v[214:217], v[14:17]
	v_mfma_f32_16x16x32_bf16 v[10:13], v[58:61], v[214:217], v[10:13]
	v_mfma_f32_16x16x32_bf16 v[78:81], v[46:49], v[184:187], v[78:81]
	v_mfma_f32_16x16x32_bf16 v[74:77], v[62:65], v[184:187], v[74:77]
	v_mfma_f32_16x16x32_bf16 v[54:57], v[46:49], v[200:203], v[54:57]
	v_mfma_f32_16x16x32_bf16 v[50:53], v[62:65], v[200:203], v[50:53]
	v_mfma_f32_16x16x32_bf16 v[30:33], v[46:49], v[210:213], v[30:33]
	v_mfma_f32_16x16x32_bf16 v[26:29], v[62:65], v[210:213], v[26:29]
	v_mfma_f32_16x16x32_bf16 v[14:17], v[46:49], v[218:221], v[14:17]
	v_mfma_f32_16x16x32_bf16 v[10:13], v[62:65], v[218:221], v[10:13]
	v_mfma_f32_16x16x32_bf16 v[38:41], v[138:141], v[188:191], v[38:41]
	v_mfma_f32_16x16x32_bf16 v[34:37], v[154:157], v[188:191], v[34:37]
	v_mfma_f32_16x16x32_bf16 v[22:25], v[138:141], v[206:209], v[22:25]
	v_mfma_f32_16x16x32_bf16 v[18:21], v[154:157], v[206:209], v[18:21]
	v_mfma_f32_16x16x32_bf16 v[6:9], v[138:141], v[214:217], v[6:9]
	v_mfma_f32_16x16x32_bf16 v[2:5], v[154:157], v[214:217], v[2:5]
	v_mfma_f32_16x16x32_bf16 v[42:45], v[138:141], v[174:177], v[70:73]
	v_mfma_f32_16x16x32_bf16 v[46:49], v[154:157], v[174:177], v[66:69]
	v_mfma_f32_16x16x32_bf16 v[38:41], v[142:145], v[200:203], v[38:41]
	v_mfma_f32_16x16x32_bf16 v[34:37], v[170:173], v[200:203], v[34:37]
	v_mfma_f32_16x16x32_bf16 v[22:25], v[142:145], v[210:213], v[22:25]
	v_mfma_f32_16x16x32_bf16 v[18:21], v[170:173], v[210:213], v[18:21]
	v_mfma_f32_16x16x32_bf16 v[6:9], v[142:145], v[218:221], v[6:9]
	v_mfma_f32_16x16x32_bf16 v[2:5], v[170:173], v[218:221], v[2:5]
	v_mfma_f32_16x16x32_bf16 v[42:45], v[142:145], v[184:187], v[42:45]
	v_mfma_f32_16x16x32_bf16 v[46:49], v[170:173], v[184:187], v[46:49]
	s_barrier
; #define PG8_STAGE(bufoff, gbase, voff) do { _Pragma("unroll") for (int _i = 0; _i < 2; ++_i) \
;         __builtin_amdgcn_global_load_lds((const unsigned*)((const char*)(gbase) + (voff)[_i]), (LAS unsigned*)(lds + (bufoff) + ldsw + _i * 8192), 16, 0, 0); } while (0)
; #define PG8_LDA(dst, b, h) do { _Pragma("unroll") for (int m = 0; m < 4; ++m) _Pragma("unroll") for (int k = 0; k < 2; ++k) dst[m][k] = *(const LAS bf16x8*)(lds + PG8_SA(b, h) + aoff + m * 2048 + k * 1024); } while (0)
; #define PG8_LDB(dst, b, h) do { _Pragma("unroll") for (int n = 0; n < 2; ++n) _Pragma("unroll") for (int k = 0; k < 2; ++k) dst[n][k] = *(const LAS bf16x8*)(lds + PG8_SB(b, h) + boff + n * 2048 + k * 1024); } while (0)
; #define PG8_MMA(ai, bj, At, Bt) do { __builtin_amdgcn_s_setprio(1); _Pragma("unroll") for (int m = 0; m < 4; ++m) _Pragma("unroll") for (int n = 0; n < 2; ++n) _Pragma("unroll") for (int k = 0; k < 2; ++k) \
;         acc[ai][bj][m][n] = __builtin_amdgcn_mfma_f32_16x16x32_bf16(Bt[n][k], At[m][k], acc[ai][bj][m][n], 0, 0, 0); __builtin_amdgcn_s_setprio(0); } while (0)
; #define PG8_WAIT_V(n) asm volatile("s_waitcnt vmcnt(" #n ")" ::: "memory")
; #define PG8_WAIT_L(n) asm volatile("s_waitcnt lgkmcnt(" #n ")" ::: "memory")
; #define PG8_BAR __builtin_amdgcn_s_barrier()
; #define PG8_SCHED __builtin_amdgcn_sched_barrier(0)
; template <class Epi>
; DI void gemm_phase(LAS unsigned char* lds, const Gemm g, const StaticOrder& S, const Epi& E) {
;     ...
;             PG8_LDB(B0, 1, 0); PG8_LDB(B1, 1, 1); PG8_SCHED; PG8_LDA(At, 1, 0); PG8_STAGE(PG8_SA(0, 1), a2 + hstep, voffA);
;             PG8_WAIT_V(8); PG8_WAIT_L(0); PG8_BAR; PG8_MMA(0, 0, At, B0); PG8_MMA(0, 1, At, B1); PG8_BAR; PG8_SCHED;
	s_add_i32 s18, 0, 0x18000
	s_add_i32 s19, 0, 0x1c000
	v_add_u32_e32 v70, s18, v180
	v_add_u32_e32 v170, s19, v180
	ds_read_b128 v[58:61], v70
	ds_read_b128 v[62:65], v70 offset:1024
	ds_read_b128 v[66:69], v70 offset:2048
	ds_read_b128 v[70:73], v70 offset:3072
	ds_read_b128 v[138:141], v170
	ds_read_b128 v[142:145], v170 offset:1024
	ds_read_b128 v[154:157], v170 offset:2048
	ds_read_b128 v[170:173], v170 offset:3072
	s_add_u32 s68, s68, 0x40000
	s_addc_u32 s69, s69, 0
	s_mov_b32 m0, s36
	v_lshl_add_u64 v[224:225], s[68:69], 0, v[158:159]
	ds_read_b128 v[174:177], v182 offset:32768
	ds_read_b128 v[184:187], v182 offset:33792
	ds_read_b128 v[188:191], v182 offset:34816
	ds_read_b128 v[200:203], v182 offset:35840
	ds_read_b128 v[206:209], v182 offset:36864
	ds_read_b128 v[210:213], v182 offset:37888
	ds_read_b128 v[214:217], v182 offset:38912
	ds_read_b128 v[218:221], v182 offset:39936
	global_load_lds_dwordx4 v[224:225], off
	v_lshl_add_u64 v[224:225], s[68:69], 0, v[162:163]
	s_mov_b32 m0, s37
	s_nop 0
	global_load_lds_dwordx4 v[224:225], off
	s_waitcnt vmcnt(8)
	s_waitcnt lgkmcnt(0)
	s_barrier
	s_waitcnt lgkmcnt(0)
	v_mfma_f32_16x16x32_bf16 v[150:153], v[58:61], v[174:177], v[150:153]
	v_mfma_f32_16x16x32_bf16 v[146:149], v[66:69], v[174:177], v[146:149]
	v_mfma_f32_16x16x32_bf16 v[126:129], v[58:61], v[188:191], v[126:129]
	v_mfma_f32_16x16x32_bf16 v[122:125], v[66:69], v[188:191], v[122:125]
	v_mfma_f32_16x16x32_bf16 v[110:113], v[58:61], v[206:209], v[110:113]
	v_mfma_f32_16x16x32_bf16 v[106:109], v[66:69], v[206:209], v[106:109]
	v_mfma_f32_16x16x32_bf16 v[94:97], v[58:61], v[214:217], v[94:97]
	v_mfma_f32_16x16x32_bf16 v[90:93], v[66:69], v[214:217], v[90:93]
	v_mfma_f32_16x16x32_bf16 v[150:153], v[62:65], v[184:187], v[150:153]
	v_mfma_f32_16x16x32_bf16 v[146:149], v[70:73], v[184:187], v[146:149]
	v_mfma_f32_16x16x32_bf16 v[126:129], v[62:65], v[200:203], v[126:129]
	v_mfma_f32_16x16x32_bf16 v[122:125], v[70:73], v[200:203], v[122:125]
	v_mfma_f32_16x16x32_bf16 v[110:113], v[62:65], v[210:213], v[110:113]
	v_mfma_f32_16x16x32_bf16 v[106:109], v[70:73], v[210:213], v[106:109]
	v_mfma_f32_16x16x32_bf16 v[94:97], v[62:65], v[218:221], v[94:97]
	v_mfma_f32_16x16x32_bf16 v[90:93], v[70:73], v[218:221], v[90:93]
	v_mfma_f32_16x16x32_bf16 v[134:137], v[138:141], v[174:177], v[134:137]
	v_mfma_f32_16x16x32_bf16 v[130:133], v[154:157], v[174:177], v[130:133]
	v_mfma_f32_16x16x32_bf16 v[118:121], v[138:141], v[188:191], v[118:121]
	v_mfma_f32_16x16x32_bf16 v[114:117], v[154:157], v[188:191], v[114:117]
	v_mfma_f32_16x16x32_bf16 v[102:105], v[138:141], v[206:209], v[102:105]
	v_mfma_f32_16x16x32_bf16 v[98:101], v[154:157], v[206:209], v[98:101]
	v_mfma_f32_16x16x32_bf16 v[86:89], v[138:141], v[214:217], v[86:89]
	v_mfma_f32_16x16x32_bf16 v[82:85], v[154:157], v[214:217], v[82:85]
	v_mfma_f32_16x16x32_bf16 v[134:137], v[142:145], v[184:187], v[134:137]
	v_mfma_f32_16x16x32_bf16 v[130:133], v[170:173], v[184:187], v[130:133]
	v_mfma_f32_16x16x32_bf16 v[118:121], v[142:145], v[200:203], v[118:121]
	v_mfma_f32_16x16x32_bf16 v[114:117], v[170:173], v[200:203], v[114:117]
	v_mfma_f32_16x16x32_bf16 v[102:105], v[142:145], v[210:213], v[102:105]
	v_mfma_f32_16x16x32_bf16 v[98:101], v[170:173], v[210:213], v[98:101]
	v_mfma_f32_16x16x32_bf16 v[86:89], v[142:145], v[218:221], v[86:89]
	v_mfma_f32_16x16x32_bf16 v[82:85], v[170:173], v[218:221], v[82:85]
	s_barrier
; #define PG8_STAGE(bufoff, gbase, voff) do { _Pragma("unroll") for (int _i = 0; _i < 2; ++_i) \
;         __builtin_amdgcn_global_load_lds((const unsigned*)((const char*)(gbase) + (voff)[_i]), (LAS unsigned*)(lds + (bufoff) + ldsw + _i * 8192), 16, 0, 0); } while (0)
; #define PG8_LDA(dst, b, h) do { _Pragma("unroll") for (int m = 0; m < 4; ++m) _Pragma("unroll") for (int k = 0; k < 2; ++k) dst[m][k] = *(const LAS bf16x8*)(lds + PG8_SA(b, h) + aoff + m * 2048 + k * 1024); } while (0)
; #define PG8_LDB(dst, b, h) do { _Pragma("unroll") for (int n = 0; n < 2; ++n) _Pragma("unroll") for (int k = 0; k < 2; ++k) dst[n][k] = *(const LAS bf16x8*)(lds + PG8_SB(b, h) + boff + n * 2048 + k * 1024); } while (0)
; #define PG8_WAIT_V(n) asm volatile("s_waitcnt vmcnt(" #n ")" ::: "memory")
; #define PG8_BAR __builtin_amdgcn_s_barrier()
; template <class Epi>
; DI void gemm_phase(LAS unsigned char* lds, const Gemm g, const StaticOrder& S, const Epi& E) {
;     ...
;         for (int t = 0; t < nt; t += 2) {
;             const bool last = (t == nt - 2);
;             const char* a1 = cA + (size_t)(t + 1) * kstep;
;             const char* a2 = last ? nA : cA + (size_t)(t + 2) * kstep; const char* b2 = last ? nB : cB + (size_t)(t + 2) * kstep;
;             const char* a3 = a2 + kstep; const char* b3 = b2 + kstep;
;             PG8_LDB(B0, 0, 0); PG8_LDB(B1, 0, 1); PG8_SCHED; PG8_LDA(At, 0, 0); PG8_STAGE(PG8_SA(1, 1), a1 + hstep, voffA);
;             PG8_WAIT_V(8); PG8_WAIT_L(0); PG8_BAR; PG8_MMA(0, 0, At, B0); PG8_MMA(0, 1, At, B1); PG8_BAR; PG8_SCHED;
;             PG8_LDA(At, 0, 1); PG8_STAGE(PG8_SB(0, 0), b2, voffB); PG8_STAGE(PG8_SB(0, 1), b2 + hstep, voffB); PG8_STAGE(PG8_SA(0, 0), a2, voffA);
;             PG8_WAIT_V(8); PG8_WAIT_L(0); PG8_BAR; PG8_MMA(1, 0, At, B0); PG8_MMA(1, 1, At, B1); PG8_BAR; PG8_SCHED;
;             PG8_LDB(B0, 1, 0); PG8_LDB(B1, 1, 1); PG8_SCHED; PG8_LDA(At, 1, 0); PG8_STAGE(PG8_SA(0, 1), a2 + hstep, voffA);
;             PG8_WAIT_V(8); PG8_WAIT_L(0); PG8_BAR; PG8_MMA(0, 0, At, B0); PG8_MMA(0, 1, At, B1); PG8_BAR; PG8_SCHED;
;             PG8_LDA(At, 1, 1); PG8_STAGE(PG8_SB(1, 0), b3, voffB); PG8_STAGE(PG8_SB(1, 1), b3 + hstep, voffB); PG8_STAGE(PG8_SA(1, 0), a3, voffA);
;             PG8_WAIT_V(8); PG8_WAIT_L(0); PG8_BAR; PG8_MMA(1, 0, At, B0); PG8_MMA(1, 1, At, B1); PG8_BAR; PG8_SCHED;
;         }
;         if (wr == 0) PG8_BAR;
	s_add_i32 s18, s18, s31
	v_lshl_add_u64 v[178:179], v[178:179], 0, s[20:21]
	s_mov_b32 m0, s18
	ds_read_b128 v[174:177], v182 offset:49152
	ds_read_b128 v[184:187], v182 offset:50176
	ds_read_b128 v[188:191], v182 offset:51200
	ds_read_b128 v[200:203], v182 offset:52224
	ds_read_b128 v[206:209], v182 offset:53248
	ds_read_b128 v[210:213], v182 offset:54272
	ds_read_b128 v[214:217], v182 offset:55296
	ds_read_b128 v[218:221], v182 offset:56320
	global_load_lds_dwordx4 v[178:179], off
	s_add_i32 m0, s18, 0x2000
	s_add_u32 s66, s66, 0x40080
	v_lshl_add_u64 v[178:179], v[192:193], 0, s[20:21]
	s_addc_u32 s67, s67, 0
	s_add_i32 s18, s19, s31
	global_load_lds_dwordx4 v[178:179], off
	v_lshl_add_u64 v[178:179], s[66:67], 0, v[160:161]
	s_mov_b32 m0, s18
	s_nop 0
	global_load_lds_dwordx4 v[178:179], off
	v_lshl_add_u64 v[178:179], s[66:67], 0, v[164:165]
	s_add_i32 m0, s18, 0x2000
	s_nop 0
	global_load_lds_dwordx4 v[178:179], off
	v_lshl_add_u64 v[178:179], v[204:205], 0, s[20:21]
	s_mov_b32 m0, s24
	s_nop 0
	global_load_lds_dwordx4 v[178:179], off
	v_lshl_add_u64 v[178:179], v[222:223], 0, s[20:21]
	s_mov_b32 m0, s25
	s_nop 0
	global_load_lds_dwordx4 v[178:179], off
	s_waitcnt vmcnt(8)
	s_waitcnt lgkmcnt(0)
	s_barrier
	s_waitcnt lgkmcnt(0)
	v_mfma_f32_16x16x32_bf16 v[78:81], v[58:61], v[174:177], v[78:81]
	v_mfma_f32_16x16x32_bf16 v[74:77], v[66:69], v[174:177], v[74:77]
	v_mfma_f32_16x16x32_bf16 v[54:57], v[58:61], v[188:191], v[54:57]
	v_mfma_f32_16x16x32_bf16 v[50:53], v[66:69], v[188:191], v[50:53]
	v_mfma_f32_16x16x32_bf16 v[30:33], v[58:61], v[206:209], v[30:33]
	v_mfma_f32_16x16x32_bf16 v[26:29], v[66:69], v[206:209], v[26:29]
	v_mfma_f32_16x16x32_bf16 v[14:17], v[58:61], v[214:217], v[14:17]
	v_mfma_f32_16x16x32_bf16 v[10:13], v[66:69], v[214:217], v[10:13]
	v_mfma_f32_16x16x32_bf16 v[78:81], v[62:65], v[184:187], v[78:81]
	v_mfma_f32_16x16x32_bf16 v[74:77], v[70:73], v[184:187], v[74:77]
	v_mfma_f32_16x16x32_bf16 v[54:57], v[62:65], v[200:203], v[54:57]
	v_mfma_f32_16x16x32_bf16 v[50:53], v[70:73], v[200:203], v[50:53]
	v_mfma_f32_16x16x32_bf16 v[30:33], v[62:65], v[210:213], v[30:33]
	v_mfma_f32_16x16x32_bf16 v[26:29], v[70:73], v[210:213], v[26:29]
	v_mfma_f32_16x16x32_bf16 v[14:17], v[62:65], v[218:221], v[14:17]
	v_mfma_f32_16x16x32_bf16 v[10:13], v[70:73], v[218:221], v[10:13]
	v_mfma_f32_16x16x32_bf16 v[42:45], v[138:141], v[174:177], v[42:45]
	v_mfma_f32_16x16x32_bf16 v[70:73], v[142:145], v[184:187], v[42:45]
	v_mfma_f32_16x16x32_bf16 v[42:45], v[154:157], v[174:177], v[46:49]
	v_mfma_f32_16x16x32_bf16 v[38:41], v[138:141], v[188:191], v[38:41]
	v_mfma_f32_16x16x32_bf16 v[34:37], v[154:157], v[188:191], v[34:37]
	v_mfma_f32_16x16x32_bf16 v[22:25], v[138:141], v[206:209], v[22:25]
	v_mfma_f32_16x16x32_bf16 v[18:21], v[154:157], v[206:209], v[18:21]
	v_mfma_f32_16x16x32_bf16 v[6:9], v[138:141], v[214:217], v[6:9]
	v_mfma_f32_16x16x32_bf16 v[2:5], v[154:157], v[214:217], v[2:5]
	v_mfma_f32_16x16x32_bf16 v[66:69], v[170:173], v[184:187], v[42:45]
	v_mfma_f32_16x16x32_bf16 v[38:41], v[142:145], v[200:203], v[38:41]
	v_mfma_f32_16x16x32_bf16 v[34:37], v[170:173], v[200:203], v[34:37]
	v_mfma_f32_16x16x32_bf16 v[22:25], v[142:145], v[210:213], v[22:25]
	v_mfma_f32_16x16x32_bf16 v[18:21], v[170:173], v[210:213], v[18:21]
	v_mfma_f32_16x16x32_bf16 v[6:9], v[142:145], v[218:221], v[6:9]
	v_mfma_f32_16x16x32_bf16 v[2:5], v[170:173], v[218:221], v[2:5]
	s_barrier
	s_add_i32 s63, s63, 2
	s_add_u32 s55, s55, 0x100
	s_addc_u32 s57, s57, 0
	s_add_u32 s64, s64, 0x100
	s_addc_u32 s65, s65, 0
	s_cmp_gt_u32 s63, 13
	s_cbranch_scc0 .LBB0_515
	s_setprio 0
	s_and_b64 vcc, exec, s[52:53]
	s_cbranch_vccz .LBB0_518
	s_barrier

; #define PG8_STAGE(bufoff, gbase, voff) do { _Pragma("unroll") for (int _i = 0; _i < 2; ++_i) \
;         __builtin_amdgcn_global_load_lds((const unsigned*)((const char*)(gbase) + (voff)[_i]), (LAS unsigned*)(lds + (bufoff) + ldsw + _i * 8192), 16, 0, 0); } while (0)
; #define PG8_LDA(dst, b, h) do { _Pragma("unroll") for (int m = 0; m < 4; ++m) _Pragma("unroll") for (int k = 0; k < 2; ++k) dst[m][k] = *(const LAS bf16x8*)(lds + PG8_SA(b, h) + aoff + m * 2048 + k * 1024); } while (0)
; #define PG8_LDB(dst, b, h) do { _Pragma("unroll") for (int n = 0; n < 2; ++n) _Pragma("unroll") for (int k = 0; k < 2; ++k) dst[n][k] = *(const LAS bf16x8*)(lds + PG8_SB(b, h) + boff + n * 2048 + k * 1024); } while (0)
; #define PG8_MMA(ai, bj, At, Bt) do { __builtin_amdgcn_s_setprio(1); _Pragma("unroll") for (int m = 0; m < 4; ++m) _Pragma("unroll") for (int n = 0; n < 2; ++n) _Pragma("unroll") for (int k = 0; k < 2; ++k) \
;         acc[ai][bj][m][n] = __builtin_amdgcn_mfma_f32_16x16x32_bf16(Bt[n][k], At[m][k], acc[ai][bj][m][n], 0, 0, 0); __builtin_amdgcn_s_setprio(0); } while (0)
; #define PG8_WAIT_V(n) asm volatile("s_waitcnt vmcnt(" #n ")" ::: "memory")
; template <class Epi>
; DI void gemm_phase(LAS unsigned char* lds, const Gemm g, const StaticOrder& S, const Epi& E) {
;     ...
;         const bool has_next = S.next(ui + 1, nxt);
;         const char* nA = has_next ? (const char*)g.A + (size_t)nxt.pm * tstep : cA; const char* nB = has_next ? (const char*)g.Bt + (size_t)nxt.pn * tstep : cB;
;         for (int t = 0; t < nt; t += 2) {
;             const bool last = (t == nt - 2);
;             const char* a1 = cA + (size_t)(t + 1) * kstep;
;             const char* a2 = last ? nA : cA + (size_t)(t + 2) * kstep; const char* b2 = last ? nB : cB + (size_t)(t + 2) * kstep;
;             const char* a3 = a2 + kstep; const char* b3 = b2 + kstep;
;             PG8_LDB(B0, 0, 0); PG8_LDB(B1, 0, 1); PG8_SCHED; PG8_LDA(At, 0, 0); PG8_STAGE(PG8_SA(1, 1), a1 + hstep, voffA);
;             PG8_WAIT_V(8); PG8_WAIT_L(0); PG8_BAR; PG8_MMA(0, 0, At, B0); PG8_MMA(0, 1, At, B1); PG8_BAR; PG8_SCHED;
;     ...
;         for (int a = 0; a < 2; ++a)
; #pragma unroll
;             for (int b = 0; b < 2; ++b)
; #pragma unroll
;                 for (int m = 0; m < 4; ++m)
; #pragma unroll
;                     for (int n = 0; n < 2; ++n) acc[a][b][m][n] = (f32x4){0.f, 0.f, 0.f, 0.f};
.LBB0_538:
	s_ashr_i32 s59, s58, 31
	s_lshl_b64 s[60:61], s[58:59], 18
	s_add_u32 s60, s30, s60
	s_addc_u32 s61, s31, s61
	s_and_b64 s[62:63], s[4:5], exec
	s_cselect_b32 s23, s61, s69
	s_cselect_b32 s43, s60, s68
	s_ashr_i32 s57, s56, 31
	s_lshl_b64 s[62:63], s[56:57], 18
	s_add_u32 s62, s36, s62
	s_addc_u32 s63, s37, s63
	s_and_b64 s[70:71], s[4:5], exec
	s_cselect_b32 s57, s63, s67
	s_cselect_b32 s59, s62, s66
	s_add_u32 s94, s66, 0x100
	s_addc_u32 s95, s67, 0
	s_add_u32 s66, s68, 0x20080
	v_mov_b32_e32 v2, 0
	s_addc_u32 s67, s69, 0
	s_mov_b32 vcc_lo, -2
	v_mov_b32_e32 v3, v2
	v_mov_b32_e32 v4, v2
	v_mov_b32_e32 v5, v2
	v_mov_b32_e32 v6, v2
	v_mov_b32_e32 v7, v2
	v_mov_b32_e32 v8, v2
	v_mov_b32_e32 v9, v2
	v_mov_b32_e32 v18, v2
	v_mov_b32_e32 v19, v2
	v_mov_b32_e32 v20, v2
	v_mov_b32_e32 v21, v2
	v_mov_b32_e32 v22, v2
	v_mov_b32_e32 v23, v2
	v_mov_b32_e32 v24, v2
	v_mov_b32_e32 v25, v2
	v_mov_b32_e32 v34, v2
	v_mov_b32_e32 v35, v2
	v_mov_b32_e32 v36, v2
	v_mov_b32_e32 v37, v2
	v_mov_b32_e32 v38, v2
	v_mov_b32_e32 v39, v2
	v_mov_b32_e32 v40, v2
	v_mov_b32_e32 v41, v2
	v_mov_b32_e32 v50, v2
	v_mov_b32_e32 v51, v2
	v_mov_b32_e32 v52, v2
	v_mov_b32_e32 v53, v2
	v_mov_b32_e32 v54, v2
	v_mov_b32_e32 v55, v2
	v_mov_b32_e32 v56, v2
	v_mov_b32_e32 v57, v2
	v_mov_b32_e32 v10, v2
	v_mov_b32_e32 v11, v2
	v_mov_b32_e32 v12, v2
	v_mov_b32_e32 v13, v2
	v_mov_b32_e32 v14, v2
	v_mov_b32_e32 v15, v2
	v_mov_b32_e32 v16, v2
	v_mov_b32_e32 v17, v2
	v_mov_b32_e32 v26, v2
	v_mov_b32_e32 v27, v2
	v_mov_b32_e32 v28, v2
	v_mov_b32_e32 v29, v2
	v_mov_b32_e32 v30, v2
	v_mov_b32_e32 v31, v2
	v_mov_b32_e32 v32, v2
	v_mov_b32_e32 v33, v2
	v_mov_b32_e32 v42, v2
	v_mov_b32_e32 v43, v2
	v_mov_b32_e32 v44, v2
	v_mov_b32_e32 v45, v2
	v_mov_b32_e32 v46, v2
	v_mov_b32_e32 v47, v2
	v_mov_b32_e32 v48, v2
	v_mov_b32_e32 v49, v2
	v_mov_b32_e32 v58, v2
	v_mov_b32_e32 v59, v2
	v_mov_b32_e32 v60, v2
	v_mov_b32_e32 v61, v2
	v_mov_b32_e32 v62, v2
	v_mov_b32_e32 v63, v2
	v_mov_b32_e32 v64, v2
	v_mov_b32_e32 v65, v2
	v_mov_b32_e32 v74, v2
	v_mov_b32_e32 v75, v2
	v_mov_b32_e32 v76, v2
	v_mov_b32_e32 v77, v2
	v_mov_b32_e32 v78, v2
	v_mov_b32_e32 v79, v2
	v_mov_b32_e32 v80, v2
	v_mov_b32_e32 v81, v2
	v_mov_b32_e32 v98, v2
	v_mov_b32_e32 v99, v2
	v_mov_b32_e32 v100, v2
	v_mov_b32_e32 v101, v2
	v_mov_b32_e32 v102, v2
	v_mov_b32_e32 v103, v2
	v_mov_b32_e32 v104, v2
	v_mov_b32_e32 v105, v2
	v_mov_b32_e32 v114, v2
	v_mov_b32_e32 v115, v2
	v_mov_b32_e32 v116, v2
	v_mov_b32_e32 v117, v2
	v_mov_b32_e32 v118, v2
	v_mov_b32_e32 v119, v2
	v_mov_b32_e32 v120, v2
	v_mov_b32_e32 v121, v2
	v_mov_b32_e32 v130, v2
	v_mov_b32_e32 v131, v2
	v_mov_b32_e32 v132, v2
	v_mov_b32_e32 v133, v2
	v_mov_b32_e32 v134, v2
	v_mov_b32_e32 v135, v2
	v_mov_b32_e32 v136, v2
	v_mov_b32_e32 v137, v2
	v_mov_b32_e32 v90, v2
	v_mov_b32_e32 v91, v2
	v_mov_b32_e32 v92, v2
	v_mov_b32_e32 v93, v2
	v_mov_b32_e32 v94, v2
	v_mov_b32_e32 v95, v2
	v_mov_b32_e32 v96, v2
	v_mov_b32_e32 v97, v2
	v_mov_b32_e32 v106, v2
	v_mov_b32_e32 v107, v2
	v_mov_b32_e32 v108, v2
	v_mov_b32_e32 v109, v2
	v_mov_b32_e32 v110, v2
	v_mov_b32_e32 v111, v2
	v_mov_b32_e32 v112, v2
	v_mov_b32_e32 v113, v2
	v_mov_b32_e32 v122, v2
	v_mov_b32_e32 v123, v2
	v_mov_b32_e32 v124, v2
	v_mov_b32_e32 v125, v2
	v_mov_b32_e32 v126, v2
	v_mov_b32_e32 v127, v2
	v_mov_b32_e32 v128, v2
	v_mov_b32_e32 v129, v2
	v_mov_b32_e32 v138, v2
	v_mov_b32_e32 v139, v2
	v_mov_b32_e32 v140, v2
	v_mov_b32_e32 v141, v2
	v_mov_b32_e32 v142, v2
	v_mov_b32_e32 v143, v2
	v_mov_b32_e32 v144, v2
	v_mov_b32_e32 v145, v2
	v_readfirstlane_b32 s101, v242
	s_nop 3
	s_lshr_b32 s101, s101, 8
	s_cmp_eq_u32 s101, 1
	s_cbranch_scc0 .Lsp_3
	s_setprio 1
.Lsp_3:
.LBB0_539:
	s_add_u32 s18, s66, 0xfffe0080
	s_addc_u32 s19, s67, -1
	s_add_i32 vcc_hi, 0, 0x10000
	s_cmp_eq_u32 vcc_lo, 4
	s_cselect_b32 s71, s23, s19
	s_cselect_b32 s70, s43, s18
	s_cselect_b32 s69, s57, s95
	s_cselect_b32 s68, s59, s94
	s_add_i32 s81, 0, 0x14000
	v_add_u32_e32 v86, vcc_hi, v182
	v_add_u32_e32 v158, s81, v182
	ds_read_b128 v[66:69], v86
	ds_read_b128 v[70:73], v86 offset:1024
	ds_read_b128 v[82:85], v86 offset:2048
	ds_read_b128 v[86:89], v86 offset:3072
	ds_read_b128 v[146:149], v158
	ds_read_b128 v[150:153], v158 offset:1024
	ds_read_b128 v[154:157], v158 offset:2048
	ds_read_b128 v[158:161], v158 offset:3072
	v_lshl_add_u64 v[204:205], s[66:67], 0, v[172:173]
	s_add_i32 m0, s65, 0xc000
	ds_read_b128 v[174:177], v184
	ds_read_b128 v[178:181], v184 offset:1024
	ds_read_b128 v[186:189], v184 offset:2048
	ds_read_b128 v[190:193], v184 offset:3072
	ds_read_b128 v[200:203], v184 offset:4096
	ds_read_b128 v[206:209], v184 offset:5120
	ds_read_b128 v[210:213], v184 offset:6144
	ds_read_b128 v[214:217], v184 offset:7168
	global_load_lds_dwordx4 v[204:205], off
	v_lshl_add_u64 v[204:205], s[66:67], 0, v[170:171]
	s_add_i32 m0, s65, 0xe000
	s_nop 0
	global_load_lds_dwordx4 v[204:205], off
	s_waitcnt vmcnt(8)
	s_waitcnt lgkmcnt(0)
	s_barrier
; #define PG8_STAGE(bufoff, gbase, voff) do { _Pragma("unroll") for (int _i = 0; _i < 2; ++_i) \
;         __builtin_amdgcn_global_load_lds((const unsigned*)((const char*)(gbase) + (voff)[_i]), (LAS unsigned*)(lds + (bufoff) + ldsw + _i * 8192), 16, 0, 0); } while (0)
; #define PG8_LDA(dst, b, h) do { _Pragma("unroll") for (int m = 0; m < 4; ++m) _Pragma("unroll") for (int k = 0; k < 2; ++k) dst[m][k] = *(const LAS bf16x8*)(lds + PG8_SA(b, h) + aoff + m * 2048 + k * 1024); } while (0)
; #define PG8_MMA(ai, bj, At, Bt) do { __builtin_amdgcn_s_setprio(1); _Pragma("unroll") for (int m = 0; m < 4; ++m) _Pragma("unroll") for (int n = 0; n < 2; ++n) _Pragma("unroll") for (int k = 0; k < 2; ++k) \
;         acc[ai][bj][m][n] = __builtin_amdgcn_mfma_f32_16x16x32_bf16(Bt[n][k], At[m][k], acc[ai][bj][m][n], 0, 0, 0); __builtin_amdgcn_s_setprio(0); } while (0)
; #define PG8_WAIT_V(n) asm volatile("s_waitcnt vmcnt(" #n ")" ::: "memory")
; #define PG8_WAIT_L(n) asm volatile("s_waitcnt lgkmcnt(" #n ")" ::: "memory")
; #define PG8_BAR __builtin_amdgcn_s_barrier()
; #define PG8_SCHED __builtin_amdgcn_sched_barrier(0)
; template <class Epi>
; DI void gemm_phase(LAS unsigned char* lds, const Gemm g, const StaticOrder& S, const Epi& E) {
;     ...
;             PG8_WAIT_V(8); PG8_WAIT_L(0); PG8_BAR; PG8_MMA(0, 0, At, B0); PG8_MMA(0, 1, At, B1); PG8_BAR; PG8_SCHED;
;             PG8_LDA(At, 0, 1); PG8_STAGE(PG8_SB(0, 0), b2, voffB); PG8_STAGE(PG8_SB(0, 1), b2 + hstep, voffB); PG8_STAGE(PG8_SA(0, 0), a2, voffA);
;             PG8_WAIT_V(8); PG8_WAIT_L(0); PG8_BAR; PG8_MMA(1, 0, At, B0); PG8_MMA(1, 1, At, B1); PG8_BAR; PG8_SCHED;
	s_waitcnt lgkmcnt(0)
	v_mfma_f32_16x16x32_bf16 v[142:145], v[66:69], v[174:177], v[142:145]
	v_mfma_f32_16x16x32_bf16 v[138:141], v[82:85], v[174:177], v[138:141]
	v_mfma_f32_16x16x32_bf16 v[126:129], v[66:69], v[186:189], v[126:129]
	v_mfma_f32_16x16x32_bf16 v[122:125], v[82:85], v[186:189], v[122:125]
	v_mfma_f32_16x16x32_bf16 v[110:113], v[66:69], v[200:203], v[110:113]
	v_mfma_f32_16x16x32_bf16 v[106:109], v[82:85], v[200:203], v[106:109]
	v_mfma_f32_16x16x32_bf16 v[94:97], v[66:69], v[210:213], v[94:97]
	v_mfma_f32_16x16x32_bf16 v[90:93], v[82:85], v[210:213], v[90:93]
	v_mfma_f32_16x16x32_bf16 v[142:145], v[70:73], v[178:181], v[142:145]
	v_mfma_f32_16x16x32_bf16 v[138:141], v[86:89], v[178:181], v[138:141]
	v_mfma_f32_16x16x32_bf16 v[126:129], v[70:73], v[190:193], v[126:129]
	v_mfma_f32_16x16x32_bf16 v[122:125], v[86:89], v[190:193], v[122:125]
	v_mfma_f32_16x16x32_bf16 v[110:113], v[70:73], v[206:209], v[110:113]
	v_mfma_f32_16x16x32_bf16 v[106:109], v[86:89], v[206:209], v[106:109]
	v_mfma_f32_16x16x32_bf16 v[94:97], v[70:73], v[214:217], v[94:97]
	v_mfma_f32_16x16x32_bf16 v[90:93], v[86:89], v[214:217], v[90:93]
	v_mfma_f32_16x16x32_bf16 v[134:137], v[146:149], v[174:177], v[134:137]
	v_mfma_f32_16x16x32_bf16 v[130:133], v[154:157], v[174:177], v[130:133]
	v_mfma_f32_16x16x32_bf16 v[118:121], v[146:149], v[186:189], v[118:121]
	v_mfma_f32_16x16x32_bf16 v[114:117], v[154:157], v[186:189], v[114:117]
	v_mfma_f32_16x16x32_bf16 v[102:105], v[146:149], v[200:203], v[102:105]
	v_mfma_f32_16x16x32_bf16 v[98:101], v[154:157], v[200:203], v[98:101]
	v_mfma_f32_16x16x32_bf16 v[78:81], v[146:149], v[210:213], v[78:81]
	v_mfma_f32_16x16x32_bf16 v[74:77], v[154:157], v[210:213], v[74:77]
	v_mfma_f32_16x16x32_bf16 v[134:137], v[150:153], v[178:181], v[134:137]
	v_mfma_f32_16x16x32_bf16 v[130:133], v[158:161], v[178:181], v[130:133]
	v_mfma_f32_16x16x32_bf16 v[118:121], v[150:153], v[190:193], v[118:121]
	v_mfma_f32_16x16x32_bf16 v[114:117], v[158:161], v[190:193], v[114:117]
	v_mfma_f32_16x16x32_bf16 v[102:105], v[150:153], v[206:209], v[102:105]
	v_mfma_f32_16x16x32_bf16 v[98:101], v[158:161], v[206:209], v[98:101]
	v_mfma_f32_16x16x32_bf16 v[78:81], v[150:153], v[214:217], v[78:81]
	v_mfma_f32_16x16x32_bf16 v[74:77], v[158:161], v[214:217], v[74:77]
	s_barrier
	s_add_i32 s18, vcc_hi, s72
	v_lshl_add_u64 v[204:205], s[68:69], 0, v[164:165]
	s_mov_b32 m0, s18
	ds_read_b128 v[174:177], v184 offset:16384
	ds_read_b128 v[178:181], v184 offset:17408
	ds_read_b128 v[186:189], v184 offset:18432
	ds_read_b128 v[190:193], v184 offset:19456
	ds_read_b128 v[200:203], v184 offset:20480
	ds_read_b128 v[206:209], v184 offset:21504
	ds_read_b128 v[210:213], v184 offset:22528
	ds_read_b128 v[214:217], v184 offset:23552
	global_load_lds_dwordx4 v[204:205], off
	s_add_i32 m0, s18, 0x2000
	s_add_u32 s18, s68, 0x20000
	v_lshl_add_u64 v[218:219], s[68:69], 0, v[168:169]
	s_addc_u32 s19, s69, 0
	s_add_i32 s81, s81, s72
	global_load_lds_dwordx4 v[218:219], off
	v_lshl_add_u64 v[220:221], s[18:19], 0, v[164:165]
	s_mov_b32 m0, s81
	v_lshl_add_u64 v[222:223], s[70:71], 0, v[166:167]
	global_load_lds_dwordx4 v[220:221], off
	v_lshl_add_u64 v[220:221], s[18:19], 0, v[168:169]
	s_add_i32 m0, s81, 0x2000
	s_nop 0
	global_load_lds_dwordx4 v[220:221], off
	v_lshl_add_u64 v[220:221], s[70:71], 0, v[162:163]
	s_mov_b32 m0, s65
	s_nop 0
	global_load_lds_dwordx4 v[220:221], off
	s_mov_b32 m0, s73
	s_nop 0
	global_load_lds_dwordx4 v[222:223], off
	s_waitcnt vmcnt(8)
	s_waitcnt lgkmcnt(0)
	s_barrier
	s_waitcnt lgkmcnt(0)
	v_mfma_f32_16x16x32_bf16 v[62:65], v[66:69], v[174:177], v[62:65]
	v_mfma_f32_16x16x32_bf16 v[58:61], v[82:85], v[174:177], v[58:61]
	v_mfma_f32_16x16x32_bf16 v[46:49], v[66:69], v[186:189], v[46:49]
	v_mfma_f32_16x16x32_bf16 v[42:45], v[82:85], v[186:189], v[42:45]
	v_mfma_f32_16x16x32_bf16 v[30:33], v[66:69], v[200:203], v[30:33]
	v_mfma_f32_16x16x32_bf16 v[26:29], v[82:85], v[200:203], v[26:29]
	v_mfma_f32_16x16x32_bf16 v[14:17], v[66:69], v[210:213], v[14:17]
	v_mfma_f32_16x16x32_bf16 v[10:13], v[82:85], v[210:213], v[10:13]
	v_mfma_f32_16x16x32_bf16 v[62:65], v[70:73], v[178:181], v[62:65]
	v_mfma_f32_16x16x32_bf16 v[58:61], v[86:89], v[178:181], v[58:61]
	v_mfma_f32_16x16x32_bf16 v[46:49], v[70:73], v[190:193], v[46:49]
	v_mfma_f32_16x16x32_bf16 v[42:45], v[86:89], v[190:193], v[42:45]
	v_mfma_f32_16x16x32_bf16 v[30:33], v[70:73], v[206:209], v[30:33]
	v_mfma_f32_16x16x32_bf16 v[26:29], v[86:89], v[206:209], v[26:29]
	v_mfma_f32_16x16x32_bf16 v[14:17], v[70:73], v[214:217], v[14:17]
	v_mfma_f32_16x16x32_bf16 v[10:13], v[86:89], v[214:217], v[10:13]
	v_mfma_f32_16x16x32_bf16 v[54:57], v[146:149], v[174:177], v[54:57]
	v_mfma_f32_16x16x32_bf16 v[50:53], v[154:157], v[174:177], v[50:53]
	v_mfma_f32_16x16x32_bf16 v[38:41], v[146:149], v[186:189], v[38:41]
	v_mfma_f32_16x16x32_bf16 v[34:37], v[154:157], v[186:189], v[34:37]
	v_mfma_f32_16x16x32_bf16 v[22:25], v[146:149], v[200:203], v[22:25]
	v_mfma_f32_16x16x32_bf16 v[18:21], v[154:157], v[200:203], v[18:21]
	v_mfma_f32_16x16x32_bf16 v[6:9], v[146:149], v[210:213], v[6:9]
	v_mfma_f32_16x16x32_bf16 v[2:5], v[154:157], v[210:213], v[2:5]
	v_mfma_f32_16x16x32_bf16 v[54:57], v[150:153], v[178:181], v[54:57]
	v_mfma_f32_16x16x32_bf16 v[50:53], v[158:161], v[178:181], v[50:53]
	v_mfma_f32_16x16x32_bf16 v[38:41], v[150:153], v[190:193], v[38:41]
	v_mfma_f32_16x16x32_bf16 v[34:37], v[158:161], v[190:193], v[34:37]
	v_mfma_f32_16x16x32_bf16 v[22:25], v[150:153], v[206:209], v[22:25]
	v_mfma_f32_16x16x32_bf16 v[18:21], v[158:161], v[206:209], v[18:21]
	v_mfma_f32_16x16x32_bf16 v[6:9], v[150:153], v[214:217], v[6:9]
	v_mfma_f32_16x16x32_bf16 v[2:5], v[158:161], v[214:217], v[2:5]
	s_barrier
; #define PG8_STAGE(bufoff, gbase, voff) do { _Pragma("unroll") for (int _i = 0; _i < 2; ++_i) \
;         __builtin_amdgcn_global_load_lds((const unsigned*)((const char*)(gbase) + (voff)[_i]), (LAS unsigned*)(lds + (bufoff) + ldsw + _i * 8192), 16, 0, 0); } while (0)
; #define PG8_LDA(dst, b, h) do { _Pragma("unroll") for (int m = 0; m < 4; ++m) _Pragma("unroll") for (int k = 0; k < 2; ++k) dst[m][k] = *(const LAS bf16x8*)(lds + PG8_SA(b, h) + aoff + m * 2048 + k * 1024); } while (0)
; #define PG8_LDB(dst, b, h) do { _Pragma("unroll") for (int n = 0; n < 2; ++n) _Pragma("unroll") for (int k = 0; k < 2; ++k) dst[n][k] = *(const LAS bf16x8*)(lds + PG8_SB(b, h) + boff + n * 2048 + k * 1024); } while (0)
; #define PG8_MMA(ai, bj, At, Bt) do { __builtin_amdgcn_s_setprio(1); _Pragma("unroll") for (int m = 0; m < 4; ++m) _Pragma("unroll") for (int n = 0; n < 2; ++n) _Pragma("unroll") for (int k = 0; k < 2; ++k) \
;         acc[ai][bj][m][n] = __builtin_amdgcn_mfma_f32_16x16x32_bf16(Bt[n][k], At[m][k], acc[ai][bj][m][n], 0, 0, 0); __builtin_amdgcn_s_setprio(0); } while (0)
; #define PG8_WAIT_V(n) asm volatile("s_waitcnt vmcnt(" #n ")" ::: "memory")
; #define PG8_WAIT_L(n) asm volatile("s_waitcnt lgkmcnt(" #n ")" ::: "memory")
; #define PG8_BAR __builtin_amdgcn_s_barrier()
; #define PG8_SCHED __builtin_amdgcn_sched_barrier(0)
; template <class Epi>
; DI void gemm_phase(LAS unsigned char* lds, const Gemm g, const StaticOrder& S, const Epi& E) {
;     ...
;             PG8_LDB(B0, 1, 0); PG8_LDB(B1, 1, 1); PG8_SCHED; PG8_LDA(At, 1, 0); PG8_STAGE(PG8_SA(0, 1), a2 + hstep, voffA);
;             PG8_WAIT_V(8); PG8_WAIT_L(0); PG8_BAR; PG8_MMA(0, 0, At, B0); PG8_MMA(0, 1, At, B1); PG8_BAR; PG8_SCHED;
	s_add_i32 s81, 0, 0x18000
	s_add_i32 vcc_hi, 0, 0x1c000
	v_add_u32_e32 v86, s81, v182
	v_add_u32_e32 v158, vcc_hi, v182
	ds_read_b128 v[66:69], v86
	ds_read_b128 v[70:73], v86 offset:1024
	ds_read_b128 v[82:85], v86 offset:2048
	ds_read_b128 v[86:89], v86 offset:3072
	ds_read_b128 v[146:149], v158
	ds_read_b128 v[150:153], v158 offset:1024
	ds_read_b128 v[154:157], v158 offset:2048
	ds_read_b128 v[158:161], v158 offset:3072
	s_add_u32 s18, s70, 0x20000
	s_addc_u32 s19, s71, 0
	s_mov_b32 m0, s91
	v_lshl_add_u64 v[224:225], s[18:19], 0, v[162:163]
	ds_read_b128 v[174:177], v184 offset:32768
	ds_read_b128 v[178:181], v184 offset:33792
	ds_read_b128 v[186:189], v184 offset:34816
	ds_read_b128 v[190:193], v184 offset:35840
	ds_read_b128 v[200:203], v184 offset:36864
	ds_read_b128 v[206:209], v184 offset:37888
	ds_read_b128 v[210:213], v184 offset:38912
	ds_read_b128 v[214:217], v184 offset:39936
	global_load_lds_dwordx4 v[224:225], off
	v_lshl_add_u64 v[224:225], s[18:19], 0, v[166:167]
	s_mov_b32 m0, s93
	s_nop 0
	global_load_lds_dwordx4 v[224:225], off
	s_waitcnt vmcnt(8)
	s_waitcnt lgkmcnt(0)
	s_barrier
	s_waitcnt lgkmcnt(0)
	v_mfma_f32_16x16x32_bf16 v[142:145], v[66:69], v[174:177], v[142:145]
	v_mfma_f32_16x16x32_bf16 v[138:141], v[82:85], v[174:177], v[138:141]
	v_mfma_f32_16x16x32_bf16 v[126:129], v[66:69], v[186:189], v[126:129]
	v_mfma_f32_16x16x32_bf16 v[122:125], v[82:85], v[186:189], v[122:125]
	v_mfma_f32_16x16x32_bf16 v[110:113], v[66:69], v[200:203], v[110:113]
	v_mfma_f32_16x16x32_bf16 v[106:109], v[82:85], v[200:203], v[106:109]
	v_mfma_f32_16x16x32_bf16 v[94:97], v[66:69], v[210:213], v[94:97]
	v_mfma_f32_16x16x32_bf16 v[90:93], v[82:85], v[210:213], v[90:93]
	v_mfma_f32_16x16x32_bf16 v[142:145], v[70:73], v[178:181], v[142:145]
	v_mfma_f32_16x16x32_bf16 v[138:141], v[86:89], v[178:181], v[138:141]
	v_mfma_f32_16x16x32_bf16 v[126:129], v[70:73], v[190:193], v[126:129]
	v_mfma_f32_16x16x32_bf16 v[122:125], v[86:89], v[190:193], v[122:125]
	v_mfma_f32_16x16x32_bf16 v[110:113], v[70:73], v[206:209], v[110:113]
	v_mfma_f32_16x16x32_bf16 v[106:109], v[86:89], v[206:209], v[106:109]
	v_mfma_f32_16x16x32_bf16 v[94:97], v[70:73], v[214:217], v[94:97]
	v_mfma_f32_16x16x32_bf16 v[90:93], v[86:89], v[214:217], v[90:93]
	v_mfma_f32_16x16x32_bf16 v[134:137], v[146:149], v[174:177], v[134:137]
	v_mfma_f32_16x16x32_bf16 v[130:133], v[154:157], v[174:177], v[130:133]
	v_mfma_f32_16x16x32_bf16 v[118:121], v[146:149], v[186:189], v[118:121]
	v_mfma_f32_16x16x32_bf16 v[114:117], v[154:157], v[186:189], v[114:117]
	v_mfma_f32_16x16x32_bf16 v[102:105], v[146:149], v[200:203], v[102:105]
	v_mfma_f32_16x16x32_bf16 v[98:101], v[154:157], v[200:203], v[98:101]
	v_mfma_f32_16x16x32_bf16 v[78:81], v[146:149], v[210:213], v[78:81]
	v_mfma_f32_16x16x32_bf16 v[74:77], v[154:157], v[210:213], v[74:77]
	v_mfma_f32_16x16x32_bf16 v[134:137], v[150:153], v[178:181], v[134:137]
	v_mfma_f32_16x16x32_bf16 v[130:133], v[158:161], v[178:181], v[130:133]
	v_mfma_f32_16x16x32_bf16 v[118:121], v[150:153], v[190:193], v[118:121]
	v_mfma_f32_16x16x32_bf16 v[114:117], v[158:161], v[190:193], v[114:117]
	v_mfma_f32_16x16x32_bf16 v[102:105], v[150:153], v[206:209], v[102:105]
	v_mfma_f32_16x16x32_bf16 v[98:101], v[158:161], v[206:209], v[98:101]
	v_mfma_f32_16x16x32_bf16 v[78:81], v[150:153], v[214:217], v[78:81]
	v_mfma_f32_16x16x32_bf16 v[74:77], v[158:161], v[214:217], v[74:77]
	s_barrier
; #define PG8_STAGE(bufoff, gbase, voff) do { _Pragma("unroll") for (int _i = 0; _i < 2; ++_i) \
;         __builtin_amdgcn_global_load_lds((const unsigned*)((const char*)(gbase) + (voff)[_i]), (LAS unsigned*)(lds + (bufoff) + ldsw + _i * 8192), 16, 0, 0); } while (0)
; #define PG8_LDA(dst, b, h) do { _Pragma("unroll") for (int m = 0; m < 4; ++m) _Pragma("unroll") for (int k = 0; k < 2; ++k) dst[m][k] = *(const LAS bf16x8*)(lds + PG8_SA(b, h) + aoff + m * 2048 + k * 1024); } while (0)
; #define PG8_LDB(dst, b, h) do { _Pragma("unroll") for (int n = 0; n < 2; ++n) _Pragma("unroll") for (int k = 0; k < 2; ++k) dst[n][k] = *(const LAS bf16x8*)(lds + PG8_SB(b, h) + boff + n * 2048 + k * 1024); } while (0)
; #define PG8_WAIT_V(n) asm volatile("s_waitcnt vmcnt(" #n ")" ::: "memory")
; #define PG8_BAR __builtin_amdgcn_s_barrier()
; template <class Epi>
; DI void gemm_phase(LAS unsigned char* lds, const Gemm g, const StaticOrder& S, const Epi& E) {
;     ...
;         for (int t = 0; t < nt; t += 2) {
;             const bool last = (t == nt - 2);
;             const char* a1 = cA + (size_t)(t + 1) * kstep;
;             const char* a2 = last ? nA : cA + (size_t)(t + 2) * kstep; const char* b2 = last ? nB : cB + (size_t)(t + 2) * kstep;
;             const char* a3 = a2 + kstep; const char* b3 = b2 + kstep;
;             PG8_LDB(B0, 0, 0); PG8_LDB(B1, 0, 1); PG8_SCHED; PG8_LDA(At, 0, 0); PG8_STAGE(PG8_SA(1, 1), a1 + hstep, voffA);
;             PG8_WAIT_V(8); PG8_WAIT_L(0); PG8_BAR; PG8_MMA(0, 0, At, B0); PG8_MMA(0, 1, At, B1); PG8_BAR; PG8_SCHED;
;             PG8_LDA(At, 0, 1); PG8_STAGE(PG8_SB(0, 0), b2, voffB); PG8_STAGE(PG8_SB(0, 1), b2 + hstep, voffB); PG8_STAGE(PG8_SA(0, 0), a2, voffA);
;             PG8_WAIT_V(8); PG8_WAIT_L(0); PG8_BAR; PG8_MMA(1, 0, At, B0); PG8_MMA(1, 1, At, B1); PG8_BAR; PG8_SCHED;
;             PG8_LDB(B0, 1, 0); PG8_LDB(B1, 1, 1); PG8_SCHED; PG8_LDA(At, 1, 0); PG8_STAGE(PG8_SA(0, 1), a2 + hstep, voffA);
;             PG8_WAIT_V(8); PG8_WAIT_L(0); PG8_BAR; PG8_MMA(0, 0, At, B0); PG8_MMA(0, 1, At, B1); PG8_BAR; PG8_SCHED;
;             PG8_LDA(At, 1, 1); PG8_STAGE(PG8_SB(1, 0), b3, voffB); PG8_STAGE(PG8_SB(1, 1), b3 + hstep, voffB); PG8_STAGE(PG8_SA(1, 0), a3, voffA);
;             PG8_WAIT_V(8); PG8_WAIT_L(0); PG8_BAR; PG8_MMA(1, 0, At, B0); PG8_MMA(1, 1, At, B1); PG8_BAR; PG8_SCHED;
;         }
;         if (wr == 0) PG8_BAR;
	s_add_i32 s18, s81, s72
	v_lshl_add_u64 v[204:205], v[204:205], 0, s[20:21]
	s_mov_b32 m0, s18
	ds_read_b128 v[174:177], v184 offset:49152
	ds_read_b128 v[178:181], v184 offset:50176
	ds_read_b128 v[186:189], v184 offset:51200
	ds_read_b128 v[190:193], v184 offset:52224
	ds_read_b128 v[200:203], v184 offset:53248
	ds_read_b128 v[206:209], v184 offset:54272
	ds_read_b128 v[210:213], v184 offset:55296
	ds_read_b128 v[214:217], v184 offset:56320
	global_load_lds_dwordx4 v[204:205], off
	s_add_i32 m0, s18, 0x2000
	s_add_u32 s18, s68, 0x20080
	v_lshl_add_u64 v[204:205], v[218:219], 0, s[20:21]
	s_addc_u32 s19, s69, 0
	s_add_i32 s68, vcc_hi, s72
	global_load_lds_dwordx4 v[204:205], off
	v_lshl_add_u64 v[204:205], s[18:19], 0, v[164:165]
	s_mov_b32 m0, s68
	s_nop 0
	global_load_lds_dwordx4 v[204:205], off
	v_lshl_add_u64 v[204:205], s[18:19], 0, v[168:169]
	s_add_i32 m0, s68, 0x2000
	s_nop 0
	global_load_lds_dwordx4 v[204:205], off
	v_lshl_add_u64 v[204:205], v[220:221], 0, s[20:21]
	s_mov_b32 m0, s17
	s_nop 0
	global_load_lds_dwordx4 v[204:205], off
	v_lshl_add_u64 v[204:205], v[222:223], 0, s[20:21]
	s_mov_b32 m0, s42
	s_nop 0
	global_load_lds_dwordx4 v[204:205], off
	s_waitcnt vmcnt(8)
	s_waitcnt lgkmcnt(0)
	s_barrier
	s_waitcnt lgkmcnt(0)
	v_mfma_f32_16x16x32_bf16 v[62:65], v[66:69], v[174:177], v[62:65]
	v_mfma_f32_16x16x32_bf16 v[58:61], v[82:85], v[174:177], v[58:61]
	v_mfma_f32_16x16x32_bf16 v[46:49], v[66:69], v[186:189], v[46:49]
	v_mfma_f32_16x16x32_bf16 v[42:45], v[82:85], v[186:189], v[42:45]
	v_mfma_f32_16x16x32_bf16 v[30:33], v[66:69], v[200:203], v[30:33]
	v_mfma_f32_16x16x32_bf16 v[26:29], v[82:85], v[200:203], v[26:29]
	v_mfma_f32_16x16x32_bf16 v[14:17], v[66:69], v[210:213], v[14:17]
	v_mfma_f32_16x16x32_bf16 v[10:13], v[82:85], v[210:213], v[10:13]
	v_mfma_f32_16x16x32_bf16 v[62:65], v[70:73], v[178:181], v[62:65]
	v_mfma_f32_16x16x32_bf16 v[58:61], v[86:89], v[178:181], v[58:61]
	v_mfma_f32_16x16x32_bf16 v[46:49], v[70:73], v[190:193], v[46:49]
	v_mfma_f32_16x16x32_bf16 v[42:45], v[86:89], v[190:193], v[42:45]
	v_mfma_f32_16x16x32_bf16 v[30:33], v[70:73], v[206:209], v[30:33]
	v_mfma_f32_16x16x32_bf16 v[26:29], v[86:89], v[206:209], v[26:29]
	v_mfma_f32_16x16x32_bf16 v[14:17], v[70:73], v[214:217], v[14:17]
	v_mfma_f32_16x16x32_bf16 v[10:13], v[86:89], v[214:217], v[10:13]
	v_mfma_f32_16x16x32_bf16 v[54:57], v[146:149], v[174:177], v[54:57]
	v_mfma_f32_16x16x32_bf16 v[50:53], v[154:157], v[174:177], v[50:53]
	v_mfma_f32_16x16x32_bf16 v[38:41], v[146:149], v[186:189], v[38:41]
	v_mfma_f32_16x16x32_bf16 v[34:37], v[154:157], v[186:189], v[34:37]
	v_mfma_f32_16x16x32_bf16 v[22:25], v[146:149], v[200:203], v[22:25]
	v_mfma_f32_16x16x32_bf16 v[18:21], v[154:157], v[200:203], v[18:21]
	v_mfma_f32_16x16x32_bf16 v[6:9], v[146:149], v[210:213], v[6:9]
	v_mfma_f32_16x16x32_bf16 v[2:5], v[154:157], v[210:213], v[2:5]
	v_mfma_f32_16x16x32_bf16 v[54:57], v[150:153], v[178:181], v[54:57]
	v_mfma_f32_16x16x32_bf16 v[50:53], v[158:161], v[178:181], v[50:53]
	v_mfma_f32_16x16x32_bf16 v[38:41], v[150:153], v[190:193], v[38:41]
	v_mfma_f32_16x16x32_bf16 v[34:37], v[158:161], v[190:193], v[34:37]
	v_mfma_f32_16x16x32_bf16 v[22:25], v[150:153], v[206:209], v[22:25]
	v_mfma_f32_16x16x32_bf16 v[18:21], v[158:161], v[206:209], v[18:21]
	v_mfma_f32_16x16x32_bf16 v[6:9], v[150:153], v[214:217], v[6:9]
	v_mfma_f32_16x16x32_bf16 v[2:5], v[158:161], v[214:217], v[2:5]
	s_barrier
	s_add_i32 vcc_lo, vcc_lo, 2
	s_add_u32 s94, s94, 0x100
	s_addc_u32 s95, s95, 0
	s_add_u32 s66, s66, 0x100
	s_addc_u32 s67, s67, 0
	s_cmp_gt_u32 vcc_lo, 5
	s_cbranch_scc0 .LBB0_539
	s_setprio 0
	s_and_b64 vcc, exec, s[54:55]
	s_cbranch_vccz .LBB0_542
	s_barrier

; #define PG8_STAGE(bufoff, gbase, voff) do { _Pragma("unroll") for (int _i = 0; _i < 2; ++_i) \
;         __builtin_amdgcn_global_load_lds((const unsigned*)((const char*)(gbase) + (voff)[_i]), (LAS unsigned*)(lds + (bufoff) + ldsw + _i * 8192), 16, 0, 0); } while (0)
; #define PG8_LDA(dst, b, h) do { _Pragma("unroll") for (int m = 0; m < 4; ++m) _Pragma("unroll") for (int k = 0; k < 2; ++k) dst[m][k] = *(const LAS bf16x8*)(lds + PG8_SA(b, h) + aoff + m * 2048 + k * 1024); } while (0)
; #define PG8_LDB(dst, b, h) do { _Pragma("unroll") for (int n = 0; n < 2; ++n) _Pragma("unroll") for (int k = 0; k < 2; ++k) dst[n][k] = *(const LAS bf16x8*)(lds + PG8_SB(b, h) + boff + n * 2048 + k * 1024); } while (0)
; #define PG8_MMA(ai, bj, At, Bt) do { __builtin_amdgcn_s_setprio(1); _Pragma("unroll") for (int m = 0; m < 4; ++m) _Pragma("unroll") for (int n = 0; n < 2; ++n) _Pragma("unroll") for (int k = 0; k < 2; ++k) \
;         acc[ai][bj][m][n] = __builtin_amdgcn_mfma_f32_16x16x32_bf16(Bt[n][k], At[m][k], acc[ai][bj][m][n], 0, 0, 0); __builtin_amdgcn_s_setprio(0); } while (0)
; #define PG8_WAIT_V(n) asm volatile("s_waitcnt vmcnt(" #n ")" ::: "memory")
; template <class Epi>
; DI void gemm_phase(LAS unsigned char* lds, const Gemm g, const StaticOrder& S, const Epi& E) {
;     ...
;         const bool has_next = S.next(ui + 1, nxt);
;         const char* nA = has_next ? (const char*)g.A + (size_t)nxt.pm * tstep : cA; const char* nB = has_next ? (const char*)g.Bt + (size_t)nxt.pn * tstep : cB;
;         for (int t = 0; t < nt; t += 2) {
;             const bool last = (t == nt - 2);
;             const char* a1 = cA + (size_t)(t + 1) * kstep;
;             const char* a2 = last ? nA : cA + (size_t)(t + 2) * kstep; const char* b2 = last ? nB : cB + (size_t)(t + 2) * kstep;
;             const char* a3 = a2 + kstep; const char* b3 = b2 + kstep;
;             PG8_LDB(B0, 0, 0); PG8_LDB(B1, 0, 1); PG8_SCHED; PG8_LDA(At, 0, 0); PG8_STAGE(PG8_SA(1, 1), a1 + hstep, voffA);
;             PG8_WAIT_V(8); PG8_WAIT_L(0); PG8_BAR; PG8_MMA(0, 0, At, B0); PG8_MMA(0, 1, At, B1); PG8_BAR; PG8_SCHED;
;     ...
;         for (int a = 0; a < 2; ++a)
; #pragma unroll
;             for (int b = 0; b < 2; ++b)
; #pragma unroll
;                 for (int m = 0; m < 4; ++m)
; #pragma unroll
;                     for (int n = 0; n < 2; ++n) acc[a][b][m][n] = (f32x4){0.f, 0.f, 0.f, 0.f};
.LBB0_616:
	s_ashr_i32 s57, s56, 31
	s_lshl_b64 s[18:19], s[56:57], 19
	s_add_u32 s58, s25, s18
	s_addc_u32 s59, s30, s19
	s_and_b64 s[18:19], s[6:7], exec
	s_cselect_b32 s12, s59, s67
	s_cselect_b32 s23, s58, s66
	s_ashr_i32 s55, s54, 31
	s_lshl_b64 s[18:19], s[54:55], 19
	s_add_u32 s60, s31, s18
	s_addc_u32 s61, s36, s19
	s_and_b64 s[18:19], s[6:7], exec
	s_cselect_b32 s55, s61, s69
	s_cselect_b32 s57, s60, s68
	s_add_u32 s63, s68, 0x100
	v_mov_b32_e32 v2, 0
	s_addc_u32 s65, s69, 0
	s_mov_b32 vcc_lo, -2
	s_waitcnt lgkmcnt(0)
	v_mov_b32_e32 v3, v2
	v_mov_b32_e32 v4, v2
	v_mov_b32_e32 v5, v2
	v_mov_b32_e32 v6, v2
	v_mov_b32_e32 v7, v2
	v_mov_b32_e32 v8, v2
	v_mov_b32_e32 v9, v2
	v_mov_b32_e32 v18, v2
	v_mov_b32_e32 v19, v2
	v_mov_b32_e32 v20, v2
	v_mov_b32_e32 v21, v2
	v_mov_b32_e32 v22, v2
	v_mov_b32_e32 v23, v2
	v_mov_b32_e32 v24, v2
	v_mov_b32_e32 v25, v2
	v_mov_b32_e32 v34, v2
	v_mov_b32_e32 v35, v2
	v_mov_b32_e32 v36, v2
	v_mov_b32_e32 v37, v2
	v_mov_b32_e32 v38, v2
	v_mov_b32_e32 v39, v2
	v_mov_b32_e32 v40, v2
	v_mov_b32_e32 v41, v2
	v_mov_b32_e32 v50, v2
	v_mov_b32_e32 v51, v2
	v_mov_b32_e32 v52, v2
	v_mov_b32_e32 v53, v2
	v_mov_b32_e32 v54, v2
	v_mov_b32_e32 v55, v2
	v_mov_b32_e32 v56, v2
	v_mov_b32_e32 v57, v2
	v_mov_b32_e32 v10, v2
	v_mov_b32_e32 v11, v2
	v_mov_b32_e32 v12, v2
	v_mov_b32_e32 v13, v2
	v_mov_b32_e32 v14, v2
	v_mov_b32_e32 v15, v2
	v_mov_b32_e32 v16, v2
	v_mov_b32_e32 v17, v2
	v_mov_b32_e32 v26, v2
	v_mov_b32_e32 v27, v2
	v_mov_b32_e32 v28, v2
	v_mov_b32_e32 v29, v2
	v_mov_b32_e32 v30, v2
	v_mov_b32_e32 v31, v2
	v_mov_b32_e32 v32, v2
	v_mov_b32_e32 v33, v2
	v_mov_b32_e32 v42, v2
	v_mov_b32_e32 v43, v2
	v_mov_b32_e32 v44, v2
	v_mov_b32_e32 v45, v2
	v_mov_b32_e32 v46, v2
	v_mov_b32_e32 v47, v2
	v_mov_b32_e32 v48, v2
	v_mov_b32_e32 v49, v2
	v_mov_b32_e32 v58, v2
	v_mov_b32_e32 v59, v2
	v_mov_b32_e32 v60, v2
	v_mov_b32_e32 v61, v2
	v_mov_b32_e32 v62, v2
	v_mov_b32_e32 v63, v2
	v_mov_b32_e32 v64, v2
	v_mov_b32_e32 v65, v2
	v_mov_b32_e32 v66, v2
	v_mov_b32_e32 v67, v2
	v_mov_b32_e32 v68, v2
	v_mov_b32_e32 v69, v2
	v_mov_b32_e32 v70, v2
	v_mov_b32_e32 v71, v2
	v_mov_b32_e32 v72, v2
	v_mov_b32_e32 v73, v2
	v_mov_b32_e32 v82, v2
	v_mov_b32_e32 v83, v2
	v_mov_b32_e32 v84, v2
	v_mov_b32_e32 v85, v2
	v_mov_b32_e32 v86, v2
	v_mov_b32_e32 v87, v2
	v_mov_b32_e32 v88, v2
	v_mov_b32_e32 v89, v2
	v_mov_b32_e32 v98, v2
	v_mov_b32_e32 v99, v2
	v_mov_b32_e32 v100, v2
	v_mov_b32_e32 v101, v2
	v_mov_b32_e32 v102, v2
	v_mov_b32_e32 v103, v2
	v_mov_b32_e32 v104, v2
	v_mov_b32_e32 v105, v2
	v_mov_b32_e32 v130, v2
	v_mov_b32_e32 v131, v2
	v_mov_b32_e32 v132, v2
	v_mov_b32_e32 v133, v2
	v_mov_b32_e32 v142, v2
	v_mov_b32_e32 v143, v2
	v_mov_b32_e32 v144, v2
	v_mov_b32_e32 v145, v2
	v_mov_b32_e32 v74, v2
	v_mov_b32_e32 v75, v2
	v_mov_b32_e32 v76, v2
	v_mov_b32_e32 v77, v2
	v_mov_b32_e32 v78, v2
	v_mov_b32_e32 v79, v2
	v_mov_b32_e32 v80, v2
	v_mov_b32_e32 v81, v2
	v_mov_b32_e32 v90, v2
	v_mov_b32_e32 v91, v2
	v_mov_b32_e32 v92, v2
	v_mov_b32_e32 v93, v2
	v_mov_b32_e32 v94, v2
	v_mov_b32_e32 v95, v2
	v_mov_b32_e32 v96, v2
	v_mov_b32_e32 v97, v2
	v_mov_b32_e32 v106, v2
	v_mov_b32_e32 v107, v2
	v_mov_b32_e32 v108, v2
	v_mov_b32_e32 v109, v2
	v_mov_b32_e32 v110, v2
	v_mov_b32_e32 v111, v2
	v_mov_b32_e32 v112, v2
	v_mov_b32_e32 v113, v2
	v_mov_b32_e32 v150, v2
	v_mov_b32_e32 v151, v2
	v_mov_b32_e32 v152, v2
	v_mov_b32_e32 v153, v2
	v_mov_b32_e32 v158, v2
	v_mov_b32_e32 v159, v2
	v_mov_b32_e32 v160, v2
	v_mov_b32_e32 v161, v2
	v_readfirstlane_b32 s101, v242
	s_nop 3
	s_lshr_b32 s101, s101, 8
	s_cmp_eq_u32 s101, 1
	s_cbranch_scc0 .Lsp_2
	s_setprio 1
.Lsp_2:
.LBB0_617:
	s_add_u32 s68, s66, 0x100
	s_addc_u32 s69, s67, 0
	s_add_i32 s18, 0, 0x10000
	s_cmp_eq_u32 vcc_lo, 12
	s_cselect_b32 s73, s12, s69
	s_cselect_b32 s72, s23, s68
	s_cselect_b32 s71, s55, s65
	s_cselect_b32 s70, s57, s63
	s_add_i32 s81, 0, 0x14000
	v_add_u32_e32 v126, s18, v195
	v_add_u32_e32 v154, s81, v195
	ds_read_b128 v[114:117], v126
	ds_read_b128 v[118:121], v126 offset:1024
	ds_read_b128 v[122:125], v126 offset:2048
	ds_read_b128 v[126:129], v126 offset:3072
	ds_read_b128 v[134:137], v154
	ds_read_b128 v[138:141], v154 offset:1024
	ds_read_b128 v[146:149], v154 offset:2048
	ds_read_b128 v[154:157], v154 offset:3072
	v_lshl_add_u64 v[204:205], s[66:67], 0, v[184:185]
	s_add_i32 m0, s93, 0xc000
	ds_read_b128 v[162:165], v217
	ds_read_b128 v[166:169], v217 offset:1024
	ds_read_b128 v[170:173], v217 offset:2048
	ds_read_b128 v[174:177], v217 offset:3072
	ds_read_b128 v[186:189], v217 offset:4096
	ds_read_b128 v[190:193], v217 offset:5120
	ds_read_b128 v[200:203], v217 offset:6144
	ds_read_b128 v[206:209], v217 offset:7168
	global_load_lds_dwordx4 v[204:205], off
	v_lshl_add_u64 v[204:205], s[66:67], 0, v[182:183]
	s_add_i32 m0, s93, 0xe000
	s_nop 0
	global_load_lds_dwordx4 v[204:205], off
	s_waitcnt vmcnt(8)
	s_waitcnt lgkmcnt(0)
	s_barrier
; #define PG8_STAGE(bufoff, gbase, voff) do { _Pragma("unroll") for (int _i = 0; _i < 2; ++_i) \
;         __builtin_amdgcn_global_load_lds((const unsigned*)((const char*)(gbase) + (voff)[_i]), (LAS unsigned*)(lds + (bufoff) + ldsw + _i * 8192), 16, 0, 0); } while (0)
; #define PG8_LDA(dst, b, h) do { _Pragma("unroll") for (int m = 0; m < 4; ++m) _Pragma("unroll") for (int k = 0; k < 2; ++k) dst[m][k] = *(const LAS bf16x8*)(lds + PG8_SA(b, h) + aoff + m * 2048 + k * 1024); } while (0)
; #define PG8_MMA(ai, bj, At, Bt) do { __builtin_amdgcn_s_setprio(1); _Pragma("unroll") for (int m = 0; m < 4; ++m) _Pragma("unroll") for (int n = 0; n < 2; ++n) _Pragma("unroll") for (int k = 0; k < 2; ++k) \
;         acc[ai][bj][m][n] = __builtin_amdgcn_mfma_f32_16x16x32_bf16(Bt[n][k], At[m][k], acc[ai][bj][m][n], 0, 0, 0); __builtin_amdgcn_s_setprio(0); } while (0)
; #define PG8_WAIT_V(n) asm volatile("s_waitcnt vmcnt(" #n ")" ::: "memory")
; #define PG8_WAIT_L(n) asm volatile("s_waitcnt lgkmcnt(" #n ")" ::: "memory")
; #define PG8_BAR __builtin_amdgcn_s_barrier()
; #define PG8_SCHED __builtin_amdgcn_sched_barrier(0)
; template <class Epi>
; DI void gemm_phase(LAS unsigned char* lds, const Gemm g, const StaticOrder& S, const Epi& E) {
;     ...
;             PG8_WAIT_V(8); PG8_WAIT_L(0); PG8_BAR; PG8_MMA(0, 0, At, B0); PG8_MMA(0, 1, At, B1); PG8_BAR; PG8_SCHED;
;             PG8_LDA(At, 0, 1); PG8_STAGE(PG8_SB(0, 0), b2, voffB); PG8_STAGE(PG8_SB(0, 1), b2 + hstep, voffB); PG8_STAGE(PG8_SA(0, 0), a2, voffA);
;             PG8_WAIT_V(8); PG8_WAIT_L(0); PG8_BAR; PG8_MMA(1, 0, At, B0); PG8_MMA(1, 1, At, B1); PG8_BAR; PG8_SCHED;
	s_waitcnt lgkmcnt(0)
	v_mfma_f32_16x16x32_bf16 v[158:161], v[114:117], v[162:165], v[158:161]
	v_mfma_f32_16x16x32_bf16 v[150:153], v[122:125], v[162:165], v[150:153]
	v_mfma_f32_16x16x32_bf16 v[110:113], v[114:117], v[170:173], v[110:113]
	v_mfma_f32_16x16x32_bf16 v[106:109], v[122:125], v[170:173], v[106:109]
	v_mfma_f32_16x16x32_bf16 v[94:97], v[114:117], v[186:189], v[94:97]
	v_mfma_f32_16x16x32_bf16 v[90:93], v[122:125], v[186:189], v[90:93]
	v_mfma_f32_16x16x32_bf16 v[78:81], v[114:117], v[200:203], v[78:81]
	v_mfma_f32_16x16x32_bf16 v[74:77], v[122:125], v[200:203], v[74:77]
	v_mfma_f32_16x16x32_bf16 v[158:161], v[118:121], v[166:169], v[158:161]
	v_mfma_f32_16x16x32_bf16 v[150:153], v[126:129], v[166:169], v[150:153]
	v_mfma_f32_16x16x32_bf16 v[110:113], v[118:121], v[174:177], v[110:113]
	v_mfma_f32_16x16x32_bf16 v[106:109], v[126:129], v[174:177], v[106:109]
	v_mfma_f32_16x16x32_bf16 v[94:97], v[118:121], v[190:193], v[94:97]
	v_mfma_f32_16x16x32_bf16 v[90:93], v[126:129], v[190:193], v[90:93]
	v_mfma_f32_16x16x32_bf16 v[78:81], v[118:121], v[206:209], v[78:81]
	v_mfma_f32_16x16x32_bf16 v[74:77], v[126:129], v[206:209], v[74:77]
	v_mfma_f32_16x16x32_bf16 v[142:145], v[134:137], v[162:165], v[142:145]
	v_mfma_f32_16x16x32_bf16 v[130:133], v[146:149], v[162:165], v[130:133]
	v_mfma_f32_16x16x32_bf16 v[102:105], v[134:137], v[170:173], v[102:105]
	v_mfma_f32_16x16x32_bf16 v[98:101], v[146:149], v[170:173], v[98:101]
	v_mfma_f32_16x16x32_bf16 v[86:89], v[134:137], v[186:189], v[86:89]
	v_mfma_f32_16x16x32_bf16 v[82:85], v[146:149], v[186:189], v[82:85]
	v_mfma_f32_16x16x32_bf16 v[70:73], v[134:137], v[200:203], v[70:73]
	v_mfma_f32_16x16x32_bf16 v[66:69], v[146:149], v[200:203], v[66:69]
	v_mfma_f32_16x16x32_bf16 v[142:145], v[138:141], v[166:169], v[142:145]
	v_mfma_f32_16x16x32_bf16 v[130:133], v[154:157], v[166:169], v[130:133]
	v_mfma_f32_16x16x32_bf16 v[102:105], v[138:141], v[174:177], v[102:105]
	v_mfma_f32_16x16x32_bf16 v[98:101], v[154:157], v[174:177], v[98:101]
	v_mfma_f32_16x16x32_bf16 v[86:89], v[138:141], v[190:193], v[86:89]
	v_mfma_f32_16x16x32_bf16 v[82:85], v[154:157], v[190:193], v[82:85]
	v_mfma_f32_16x16x32_bf16 v[70:73], v[138:141], v[206:209], v[70:73]
	v_mfma_f32_16x16x32_bf16 v[66:69], v[154:157], v[206:209], v[66:69]
	s_barrier
	s_add_i32 s18, s18, s37
	v_lshl_add_u64 v[204:205], s[70:71], 0, v[178:179]
	s_mov_b32 m0, s18
	ds_read_b128 v[162:165], v217 offset:16384
	ds_read_b128 v[166:169], v217 offset:17408
	ds_read_b128 v[170:173], v217 offset:18432
	ds_read_b128 v[174:177], v217 offset:19456
	ds_read_b128 v[186:189], v217 offset:20480
	ds_read_b128 v[190:193], v217 offset:21504
	ds_read_b128 v[200:203], v217 offset:22528
	ds_read_b128 v[206:209], v217 offset:23552
	global_load_lds_dwordx4 v[204:205], off
	s_add_i32 m0, s18, 0x2000
	s_add_u32 s18, s70, 0x40000
	v_lshl_add_u64 v[210:211], s[70:71], 0, v[180:181]
	s_addc_u32 s19, s71, 0
	s_add_i32 s66, s81, s37
	global_load_lds_dwordx4 v[210:211], off
	v_lshl_add_u64 v[212:213], s[18:19], 0, v[178:179]
	s_mov_b32 m0, s66
	v_lshl_add_u64 v[214:215], s[72:73], 0, v[180:181]
	global_load_lds_dwordx4 v[212:213], off
	v_lshl_add_u64 v[212:213], s[18:19], 0, v[180:181]
	s_add_i32 m0, s66, 0x2000
	s_nop 0
	global_load_lds_dwordx4 v[212:213], off
	v_lshl_add_u64 v[212:213], s[72:73], 0, v[178:179]
	s_mov_b32 m0, s93
	s_nop 0
	global_load_lds_dwordx4 v[212:213], off
	s_mov_b32 m0, s94
	s_nop 0
	global_load_lds_dwordx4 v[214:215], off
	s_waitcnt vmcnt(8)
	s_waitcnt lgkmcnt(0)
	s_barrier
	s_waitcnt lgkmcnt(0)
	v_mfma_f32_16x16x32_bf16 v[62:65], v[114:117], v[162:165], v[62:65]
	v_mfma_f32_16x16x32_bf16 v[58:61], v[122:125], v[162:165], v[58:61]
	v_mfma_f32_16x16x32_bf16 v[46:49], v[114:117], v[170:173], v[46:49]
	v_mfma_f32_16x16x32_bf16 v[42:45], v[122:125], v[170:173], v[42:45]
	v_mfma_f32_16x16x32_bf16 v[30:33], v[114:117], v[186:189], v[30:33]
	v_mfma_f32_16x16x32_bf16 v[26:29], v[122:125], v[186:189], v[26:29]
	v_mfma_f32_16x16x32_bf16 v[14:17], v[114:117], v[200:203], v[14:17]
	v_mfma_f32_16x16x32_bf16 v[10:13], v[122:125], v[200:203], v[10:13]
	v_mfma_f32_16x16x32_bf16 v[62:65], v[118:121], v[166:169], v[62:65]
	v_mfma_f32_16x16x32_bf16 v[58:61], v[126:129], v[166:169], v[58:61]
	v_mfma_f32_16x16x32_bf16 v[46:49], v[118:121], v[174:177], v[46:49]
	v_mfma_f32_16x16x32_bf16 v[42:45], v[126:129], v[174:177], v[42:45]
	v_mfma_f32_16x16x32_bf16 v[30:33], v[118:121], v[190:193], v[30:33]
	v_mfma_f32_16x16x32_bf16 v[26:29], v[126:129], v[190:193], v[26:29]
	v_mfma_f32_16x16x32_bf16 v[14:17], v[118:121], v[206:209], v[14:17]
	v_mfma_f32_16x16x32_bf16 v[10:13], v[126:129], v[206:209], v[10:13]
	v_mfma_f32_16x16x32_bf16 v[54:57], v[134:137], v[162:165], v[54:57]
	v_mfma_f32_16x16x32_bf16 v[50:53], v[146:149], v[162:165], v[50:53]
	v_mfma_f32_16x16x32_bf16 v[38:41], v[134:137], v[170:173], v[38:41]
	v_mfma_f32_16x16x32_bf16 v[34:37], v[146:149], v[170:173], v[34:37]
	v_mfma_f32_16x16x32_bf16 v[22:25], v[134:137], v[186:189], v[22:25]
	v_mfma_f32_16x16x32_bf16 v[18:21], v[146:149], v[186:189], v[18:21]
	v_mfma_f32_16x16x32_bf16 v[6:9], v[134:137], v[200:203], v[6:9]
	v_mfma_f32_16x16x32_bf16 v[2:5], v[146:149], v[200:203], v[2:5]
	v_mfma_f32_16x16x32_bf16 v[54:57], v[138:141], v[166:169], v[54:57]
	v_mfma_f32_16x16x32_bf16 v[50:53], v[154:157], v[166:169], v[50:53]
	v_mfma_f32_16x16x32_bf16 v[38:41], v[138:141], v[174:177], v[38:41]
	v_mfma_f32_16x16x32_bf16 v[34:37], v[154:157], v[174:177], v[34:37]
	v_mfma_f32_16x16x32_bf16 v[22:25], v[138:141], v[190:193], v[22:25]
	v_mfma_f32_16x16x32_bf16 v[18:21], v[154:157], v[190:193], v[18:21]
	v_mfma_f32_16x16x32_bf16 v[6:9], v[138:141], v[206:209], v[6:9]
	v_mfma_f32_16x16x32_bf16 v[2:5], v[154:157], v[206:209], v[2:5]
	s_barrier
; #define PG8_STAGE(bufoff, gbase, voff) do { _Pragma("unroll") for (int _i = 0; _i < 2; ++_i) \
;         __builtin_amdgcn_global_load_lds((const unsigned*)((const char*)(gbase) + (voff)[_i]), (LAS unsigned*)(lds + (bufoff) + ldsw + _i * 8192), 16, 0, 0); } while (0)
; #define PG8_LDA(dst, b, h) do { _Pragma("unroll") for (int m = 0; m < 4; ++m) _Pragma("unroll") for (int k = 0; k < 2; ++k) dst[m][k] = *(const LAS bf16x8*)(lds + PG8_SA(b, h) + aoff + m * 2048 + k * 1024); } while (0)
; #define PG8_LDB(dst, b, h) do { _Pragma("unroll") for (int n = 0; n < 2; ++n) _Pragma("unroll") for (int k = 0; k < 2; ++k) dst[n][k] = *(const LAS bf16x8*)(lds + PG8_SB(b, h) + boff + n * 2048 + k * 1024); } while (0)
; #define PG8_MMA(ai, bj, At, Bt) do { __builtin_amdgcn_s_setprio(1); _Pragma("unroll") for (int m = 0; m < 4; ++m) _Pragma("unroll") for (int n = 0; n < 2; ++n) _Pragma("unroll") for (int k = 0; k < 2; ++k) \
;         acc[ai][bj][m][n] = __builtin_amdgcn_mfma_f32_16x16x32_bf16(Bt[n][k], At[m][k], acc[ai][bj][m][n], 0, 0, 0); __builtin_amdgcn_s_setprio(0); } while (0)
; #define PG8_WAIT_V(n) asm volatile("s_waitcnt vmcnt(" #n ")" ::: "memory")
; #define PG8_WAIT_L(n) asm volatile("s_waitcnt lgkmcnt(" #n ")" ::: "memory")
; #define PG8_BAR __builtin_amdgcn_s_barrier()
; #define PG8_SCHED __builtin_amdgcn_sched_barrier(0)
; template <class Epi>
; DI void gemm_phase(LAS unsigned char* lds, const Gemm g, const StaticOrder& S, const Epi& E) {
;     ...
;             PG8_LDB(B0, 1, 0); PG8_LDB(B1, 1, 1); PG8_SCHED; PG8_LDA(At, 1, 0); PG8_STAGE(PG8_SA(0, 1), a2 + hstep, voffA);
;             PG8_WAIT_V(8); PG8_WAIT_L(0); PG8_BAR; PG8_MMA(0, 0, At, B0); PG8_MMA(0, 1, At, B1); PG8_BAR; PG8_SCHED;
	s_add_i32 s66, 0, 0x18000
	s_add_i32 s67, 0, 0x1c000
	v_add_u32_e32 v126, s66, v195
	v_add_u32_e32 v154, s67, v195
	ds_read_b128 v[114:117], v126
	ds_read_b128 v[118:121], v126 offset:1024
	ds_read_b128 v[122:125], v126 offset:2048
	ds_read_b128 v[126:129], v126 offset:3072
	ds_read_b128 v[134:137], v154
	ds_read_b128 v[138:141], v154 offset:1024
	ds_read_b128 v[146:149], v154 offset:2048
	ds_read_b128 v[154:157], v154 offset:3072
	s_add_u32 s18, s72, 0x40000
	s_addc_u32 s19, s73, 0
	s_mov_b32 m0, s95
	v_lshl_add_u64 v[218:219], s[18:19], 0, v[178:179]
	ds_read_b128 v[162:165], v217 offset:32768
	ds_read_b128 v[166:169], v217 offset:33792
	ds_read_b128 v[170:173], v217 offset:34816
	ds_read_b128 v[174:177], v217 offset:35840
	ds_read_b128 v[186:189], v217 offset:36864
	ds_read_b128 v[190:193], v217 offset:37888
	ds_read_b128 v[200:203], v217 offset:38912
	ds_read_b128 v[206:209], v217 offset:39936
	global_load_lds_dwordx4 v[218:219], off
	v_lshl_add_u64 v[218:219], s[18:19], 0, v[180:181]
	s_mov_b32 m0, s91
	s_nop 0
	global_load_lds_dwordx4 v[218:219], off
	s_waitcnt vmcnt(8)
	s_waitcnt lgkmcnt(0)
	s_barrier
	s_waitcnt lgkmcnt(0)
	v_mfma_f32_16x16x32_bf16 v[158:161], v[114:117], v[162:165], v[158:161]
	v_mfma_f32_16x16x32_bf16 v[150:153], v[122:125], v[162:165], v[150:153]
	v_mfma_f32_16x16x32_bf16 v[110:113], v[114:117], v[170:173], v[110:113]
	v_mfma_f32_16x16x32_bf16 v[106:109], v[122:125], v[170:173], v[106:109]
	v_mfma_f32_16x16x32_bf16 v[94:97], v[114:117], v[186:189], v[94:97]
	v_mfma_f32_16x16x32_bf16 v[90:93], v[122:125], v[186:189], v[90:93]
	v_mfma_f32_16x16x32_bf16 v[78:81], v[114:117], v[200:203], v[78:81]
	v_mfma_f32_16x16x32_bf16 v[74:77], v[122:125], v[200:203], v[74:77]
	v_mfma_f32_16x16x32_bf16 v[158:161], v[118:121], v[166:169], v[158:161]
	v_mfma_f32_16x16x32_bf16 v[150:153], v[126:129], v[166:169], v[150:153]
	v_mfma_f32_16x16x32_bf16 v[110:113], v[118:121], v[174:177], v[110:113]
	v_mfma_f32_16x16x32_bf16 v[106:109], v[126:129], v[174:177], v[106:109]
	v_mfma_f32_16x16x32_bf16 v[94:97], v[118:121], v[190:193], v[94:97]
	v_mfma_f32_16x16x32_bf16 v[90:93], v[126:129], v[190:193], v[90:93]
	v_mfma_f32_16x16x32_bf16 v[78:81], v[118:121], v[206:209], v[78:81]
	v_mfma_f32_16x16x32_bf16 v[74:77], v[126:129], v[206:209], v[74:77]
	v_mfma_f32_16x16x32_bf16 v[142:145], v[134:137], v[162:165], v[142:145]
	v_mfma_f32_16x16x32_bf16 v[130:133], v[146:149], v[162:165], v[130:133]
	v_mfma_f32_16x16x32_bf16 v[102:105], v[134:137], v[170:173], v[102:105]
	v_mfma_f32_16x16x32_bf16 v[98:101], v[146:149], v[170:173], v[98:101]
	v_mfma_f32_16x16x32_bf16 v[86:89], v[134:137], v[186:189], v[86:89]
	v_mfma_f32_16x16x32_bf16 v[82:85], v[146:149], v[186:189], v[82:85]
	v_mfma_f32_16x16x32_bf16 v[70:73], v[134:137], v[200:203], v[70:73]
	v_mfma_f32_16x16x32_bf16 v[66:69], v[146:149], v[200:203], v[66:69]
	v_mfma_f32_16x16x32_bf16 v[142:145], v[138:141], v[166:169], v[142:145]
	v_mfma_f32_16x16x32_bf16 v[130:133], v[154:157], v[166:169], v[130:133]
	v_mfma_f32_16x16x32_bf16 v[102:105], v[138:141], v[174:177], v[102:105]
	v_mfma_f32_16x16x32_bf16 v[98:101], v[154:157], v[174:177], v[98:101]
	v_mfma_f32_16x16x32_bf16 v[86:89], v[138:141], v[190:193], v[86:89]
	v_mfma_f32_16x16x32_bf16 v[82:85], v[154:157], v[190:193], v[82:85]
	v_mfma_f32_16x16x32_bf16 v[70:73], v[138:141], v[206:209], v[70:73]
	v_mfma_f32_16x16x32_bf16 v[66:69], v[154:157], v[206:209], v[66:69]
	s_barrier
; #define PG8_STAGE(bufoff, gbase, voff) do { _Pragma("unroll") for (int _i = 0; _i < 2; ++_i) \
;         __builtin_amdgcn_global_load_lds((const unsigned*)((const char*)(gbase) + (voff)[_i]), (LAS unsigned*)(lds + (bufoff) + ldsw + _i * 8192), 16, 0, 0); } while (0)
; #define PG8_LDA(dst, b, h) do { _Pragma("unroll") for (int m = 0; m < 4; ++m) _Pragma("unroll") for (int k = 0; k < 2; ++k) dst[m][k] = *(const LAS bf16x8*)(lds + PG8_SA(b, h) + aoff + m * 2048 + k * 1024); } while (0)
; #define PG8_LDB(dst, b, h) do { _Pragma("unroll") for (int n = 0; n < 2; ++n) _Pragma("unroll") for (int k = 0; k < 2; ++k) dst[n][k] = *(const LAS bf16x8*)(lds + PG8_SB(b, h) + boff + n * 2048 + k * 1024); } while (0)
; #define PG8_WAIT_V(n) asm volatile("s_waitcnt vmcnt(" #n ")" ::: "memory")
; #define PG8_BAR __builtin_amdgcn_s_barrier()
; template <class Epi>
; DI void gemm_phase(LAS unsigned char* lds, const Gemm g, const StaticOrder& S, const Epi& E) {
;     ...
;         for (int t = 0; t < nt; t += 2) {
;             const bool last = (t == nt - 2);
;             const char* a1 = cA + (size_t)(t + 1) * kstep;
;             const char* a2 = last ? nA : cA + (size_t)(t + 2) * kstep; const char* b2 = last ? nB : cB + (size_t)(t + 2) * kstep;
;             const char* a3 = a2 + kstep; const char* b3 = b2 + kstep;
;             PG8_LDB(B0, 0, 0); PG8_LDB(B1, 0, 1); PG8_SCHED; PG8_LDA(At, 0, 0); PG8_STAGE(PG8_SA(1, 1), a1 + hstep, voffA);
;             PG8_WAIT_V(8); PG8_WAIT_L(0); PG8_BAR; PG8_MMA(0, 0, At, B0); PG8_MMA(0, 1, At, B1); PG8_BAR; PG8_SCHED;
;             PG8_LDA(At, 0, 1); PG8_STAGE(PG8_SB(0, 0), b2, voffB); PG8_STAGE(PG8_SB(0, 1), b2 + hstep, voffB); PG8_STAGE(PG8_SA(0, 0), a2, voffA);
;             PG8_WAIT_V(8); PG8_WAIT_L(0); PG8_BAR; PG8_MMA(1, 0, At, B0); PG8_MMA(1, 1, At, B1); PG8_BAR; PG8_SCHED;
;             PG8_LDB(B0, 1, 0); PG8_LDB(B1, 1, 1); PG8_SCHED; PG8_LDA(At, 1, 0); PG8_STAGE(PG8_SA(0, 1), a2 + hstep, voffA);
;             PG8_WAIT_V(8); PG8_WAIT_L(0); PG8_BAR; PG8_MMA(0, 0, At, B0); PG8_MMA(0, 1, At, B1); PG8_BAR; PG8_SCHED;
;             PG8_LDA(At, 1, 1); PG8_STAGE(PG8_SB(1, 0), b3, voffB); PG8_STAGE(PG8_SB(1, 1), b3 + hstep, voffB); PG8_STAGE(PG8_SA(1, 0), a3, voffA);
;             PG8_WAIT_V(8); PG8_WAIT_L(0); PG8_BAR; PG8_MMA(1, 0, At, B0); PG8_MMA(1, 1, At, B1); PG8_BAR; PG8_SCHED;
;         }
;         if (wr == 0) PG8_BAR;
	s_add_i32 s18, s66, s37
	v_lshl_add_u64 v[204:205], v[204:205], 0, s[20:21]
	s_mov_b32 m0, s18
	ds_read_b128 v[162:165], v217 offset:49152
	ds_read_b128 v[166:169], v217 offset:50176
	ds_read_b128 v[170:173], v217 offset:51200
	ds_read_b128 v[174:177], v217 offset:52224
	ds_read_b128 v[186:189], v217 offset:53248
	ds_read_b128 v[190:193], v217 offset:54272
	ds_read_b128 v[200:203], v217 offset:55296
	ds_read_b128 v[206:209], v217 offset:56320
	global_load_lds_dwordx4 v[204:205], off
	s_add_i32 m0, s18, 0x2000
	s_add_u32 s18, s70, 0x40080
	v_lshl_add_u64 v[204:205], v[210:211], 0, s[20:21]
	s_addc_u32 s19, s71, 0
	s_add_i32 s66, s67, s37
	global_load_lds_dwordx4 v[204:205], off
	v_lshl_add_u64 v[204:205], s[18:19], 0, v[178:179]
	s_mov_b32 m0, s66
	s_nop 0
	global_load_lds_dwordx4 v[204:205], off
	v_lshl_add_u64 v[204:205], s[18:19], 0, v[180:181]
	s_add_i32 m0, s66, 0x2000
	s_nop 0
	global_load_lds_dwordx4 v[204:205], off
	v_lshl_add_u64 v[204:205], v[212:213], 0, s[20:21]
	s_mov_b32 m0, s17
	s_nop 0
	global_load_lds_dwordx4 v[204:205], off
	v_lshl_add_u64 v[204:205], v[214:215], 0, s[20:21]
	s_mov_b32 m0, s42
	s_nop 0
	global_load_lds_dwordx4 v[204:205], off
	s_waitcnt vmcnt(8)
	s_waitcnt lgkmcnt(0)
	s_barrier
	s_waitcnt lgkmcnt(0)
	v_mfma_f32_16x16x32_bf16 v[62:65], v[114:117], v[162:165], v[62:65]
	v_mfma_f32_16x16x32_bf16 v[58:61], v[122:125], v[162:165], v[58:61]
	v_mfma_f32_16x16x32_bf16 v[46:49], v[114:117], v[170:173], v[46:49]
	v_mfma_f32_16x16x32_bf16 v[42:45], v[122:125], v[170:173], v[42:45]
	v_mfma_f32_16x16x32_bf16 v[30:33], v[114:117], v[186:189], v[30:33]
	v_mfma_f32_16x16x32_bf16 v[26:29], v[122:125], v[186:189], v[26:29]
	v_mfma_f32_16x16x32_bf16 v[14:17], v[114:117], v[200:203], v[14:17]
	v_mfma_f32_16x16x32_bf16 v[10:13], v[122:125], v[200:203], v[10:13]
	v_mfma_f32_16x16x32_bf16 v[62:65], v[118:121], v[166:169], v[62:65]
	v_mfma_f32_16x16x32_bf16 v[58:61], v[126:129], v[166:169], v[58:61]
	v_mfma_f32_16x16x32_bf16 v[46:49], v[118:121], v[174:177], v[46:49]
	v_mfma_f32_16x16x32_bf16 v[42:45], v[126:129], v[174:177], v[42:45]
	v_mfma_f32_16x16x32_bf16 v[30:33], v[118:121], v[190:193], v[30:33]
	v_mfma_f32_16x16x32_bf16 v[26:29], v[126:129], v[190:193], v[26:29]
	v_mfma_f32_16x16x32_bf16 v[14:17], v[118:121], v[206:209], v[14:17]
	v_mfma_f32_16x16x32_bf16 v[10:13], v[126:129], v[206:209], v[10:13]
	v_mfma_f32_16x16x32_bf16 v[54:57], v[134:137], v[162:165], v[54:57]
	v_mfma_f32_16x16x32_bf16 v[50:53], v[146:149], v[162:165], v[50:53]
	v_mfma_f32_16x16x32_bf16 v[38:41], v[134:137], v[170:173], v[38:41]
	v_mfma_f32_16x16x32_bf16 v[34:37], v[146:149], v[170:173], v[34:37]
	v_mfma_f32_16x16x32_bf16 v[22:25], v[134:137], v[186:189], v[22:25]
	v_mfma_f32_16x16x32_bf16 v[18:21], v[146:149], v[186:189], v[18:21]
	v_mfma_f32_16x16x32_bf16 v[6:9], v[134:137], v[200:203], v[6:9]
	v_mfma_f32_16x16x32_bf16 v[2:5], v[146:149], v[200:203], v[2:5]
	v_mfma_f32_16x16x32_bf16 v[54:57], v[138:141], v[166:169], v[54:57]
	v_mfma_f32_16x16x32_bf16 v[50:53], v[154:157], v[166:169], v[50:53]
	v_mfma_f32_16x16x32_bf16 v[38:41], v[138:141], v[174:177], v[38:41]
	v_mfma_f32_16x16x32_bf16 v[34:37], v[154:157], v[174:177], v[34:37]
	v_mfma_f32_16x16x32_bf16 v[22:25], v[138:141], v[190:193], v[22:25]
	v_mfma_f32_16x16x32_bf16 v[18:21], v[154:157], v[190:193], v[18:21]
	v_mfma_f32_16x16x32_bf16 v[6:9], v[138:141], v[206:209], v[6:9]
	v_mfma_f32_16x16x32_bf16 v[2:5], v[154:157], v[206:209], v[2:5]
	s_barrier
	s_add_i32 vcc_lo, vcc_lo, 2
	s_add_u32 s63, s63, 0x100
	s_addc_u32 s65, s65, 0
	s_cmp_gt_u32 vcc_lo, 13
	s_mov_b64 s[66:67], s[68:69]
	s_cbranch_scc0 .LBB0_617
	s_setprio 0
	s_and_b64 vcc, exec, s[52:53]
	s_cbranch_vccz .LBB0_620
	s_barrier

; #define PG8_STAGE(bufoff, gbase, voff) do { _Pragma("unroll") for (int _i = 0; _i < 2; ++_i) \
;         __builtin_amdgcn_global_load_lds((const unsigned*)((const char*)(gbase) + (voff)[_i]), (LAS unsigned*)(lds + (bufoff) + ldsw + _i * 8192), 16, 0, 0); } while (0)
; #define PG8_LDA(dst, b, h) do { _Pragma("unroll") for (int m = 0; m < 4; ++m) _Pragma("unroll") for (int k = 0; k < 2; ++k) dst[m][k] = *(const LAS bf16x8*)(lds + PG8_SA(b, h) + aoff + m * 2048 + k * 1024); } while (0)
; #define PG8_LDB(dst, b, h) do { _Pragma("unroll") for (int n = 0; n < 2; ++n) _Pragma("unroll") for (int k = 0; k < 2; ++k) dst[n][k] = *(const LAS bf16x8*)(lds + PG8_SB(b, h) + boff + n * 2048 + k * 1024); } while (0)
; #define PG8_MMA(ai, bj, At, Bt) do { __builtin_amdgcn_s_setprio(1); _Pragma("unroll") for (int m = 0; m < 4; ++m) _Pragma("unroll") for (int n = 0; n < 2; ++n) _Pragma("unroll") for (int k = 0; k < 2; ++k) \
;         acc[ai][bj][m][n] = __builtin_amdgcn_mfma_f32_16x16x32_bf16(Bt[n][k], At[m][k], acc[ai][bj][m][n], 0, 0, 0); __builtin_amdgcn_s_setprio(0); } while (0)
; #define PG8_WAIT_V(n) asm volatile("s_waitcnt vmcnt(" #n ")" ::: "memory")
; template <class Epi>
; DI void gemm_phase(LAS unsigned char* lds, const Gemm g, const StaticOrder& S, const Epi& E) {
;     ...
;         const bool has_next = S.next(ui + 1, nxt);
;         const char* nA = has_next ? (const char*)g.A + (size_t)nxt.pm * tstep : cA; const char* nB = has_next ? (const char*)g.Bt + (size_t)nxt.pn * tstep : cB;
;         for (int t = 0; t < nt; t += 2) {
;             const bool last = (t == nt - 2);
;             const char* a1 = cA + (size_t)(t + 1) * kstep;
;             const char* a2 = last ? nA : cA + (size_t)(t + 2) * kstep; const char* b2 = last ? nB : cB + (size_t)(t + 2) * kstep;
;             const char* a3 = a2 + kstep; const char* b3 = b2 + kstep;
;             PG8_LDB(B0, 0, 0); PG8_LDB(B1, 0, 1); PG8_SCHED; PG8_LDA(At, 0, 0); PG8_STAGE(PG8_SA(1, 1), a1 + hstep, voffA);
;             PG8_WAIT_V(8); PG8_WAIT_L(0); PG8_BAR; PG8_MMA(0, 0, At, B0); PG8_MMA(0, 1, At, B1); PG8_BAR; PG8_SCHED;
;     ...
;         for (int a = 0; a < 2; ++a)
; #pragma unroll
;             for (int b = 0; b < 2; ++b)
; #pragma unroll
;                 for (int m = 0; m < 4; ++m)
; #pragma unroll
;                     for (int n = 0; n < 2; ++n) acc[a][b][m][n] = (f32x4){0.f, 0.f, 0.f, 0.f};
.LBB0_700:
	s_ashr_i32 s49, s48, 31
	s_lshl_b64 s[18:19], s[48:49], 19
	s_add_u32 s50, s25, s18
	s_addc_u32 s51, s30, s19
	s_and_b64 s[18:19], s[4:5], exec
	s_cselect_b32 s22, s51, s59
	s_cselect_b32 s23, s50, s58
	s_ashr_i32 s47, s46, 31
	s_lshl_b64 s[18:19], s[46:47], 19
	s_add_u32 s52, s31, s18
	s_addc_u32 s53, s36, s19
	s_and_b64 s[18:19], s[4:5], exec
	s_cselect_b32 s42, s53, s57
	s_cselect_b32 s43, s52, s56
	s_add_u32 s47, s56, 0x100
	s_addc_u32 s49, s57, 0
	s_add_u32 s56, s58, 0x40080
	v_mov_b32_e32 v2, 0
	s_addc_u32 s57, s59, 0
	s_mov_b32 s68, -2
	v_mov_b32_e32 v3, v2
	v_mov_b32_e32 v4, v2
	v_mov_b32_e32 v5, v2
	v_mov_b32_e32 v10, v2
	v_mov_b32_e32 v11, v2
	v_mov_b32_e32 v12, v2
	v_mov_b32_e32 v13, v2
	v_mov_b32_e32 v18, v2
	v_mov_b32_e32 v19, v2
	v_mov_b32_e32 v20, v2
	v_mov_b32_e32 v21, v2
	v_mov_b32_e32 v26, v2
	v_mov_b32_e32 v27, v2
	v_mov_b32_e32 v28, v2
	v_mov_b32_e32 v29, v2
	v_mov_b32_e32 v34, v2
	v_mov_b32_e32 v35, v2
	v_mov_b32_e32 v36, v2
	v_mov_b32_e32 v37, v2
	v_mov_b32_e32 v42, v2
	v_mov_b32_e32 v43, v2
	v_mov_b32_e32 v44, v2
	v_mov_b32_e32 v45, v2
	v_mov_b32_e32 v50, v2
	v_mov_b32_e32 v51, v2
	v_mov_b32_e32 v52, v2
	v_mov_b32_e32 v53, v2
	v_mov_b32_e32 v58, v2
	v_mov_b32_e32 v59, v2
	v_mov_b32_e32 v60, v2
	v_mov_b32_e32 v61, v2
	v_mov_b32_e32 v6, v2
	v_mov_b32_e32 v7, v2
	v_mov_b32_e32 v8, v2
	v_mov_b32_e32 v9, v2
	v_mov_b32_e32 v14, v2
	v_mov_b32_e32 v15, v2
	v_mov_b32_e32 v16, v2
	v_mov_b32_e32 v17, v2
	v_mov_b32_e32 v22, v2
	v_mov_b32_e32 v23, v2
	v_mov_b32_e32 v24, v2
	v_mov_b32_e32 v25, v2
	v_mov_b32_e32 v30, v2
	v_mov_b32_e32 v31, v2
	v_mov_b32_e32 v32, v2
	v_mov_b32_e32 v33, v2
	v_mov_b32_e32 v38, v2
	v_mov_b32_e32 v39, v2
	v_mov_b32_e32 v40, v2
	v_mov_b32_e32 v41, v2
	v_mov_b32_e32 v46, v2
	v_mov_b32_e32 v47, v2
	v_mov_b32_e32 v48, v2
	v_mov_b32_e32 v49, v2
	v_mov_b32_e32 v54, v2
	v_mov_b32_e32 v55, v2
	v_mov_b32_e32 v56, v2
	v_mov_b32_e32 v57, v2
	v_mov_b32_e32 v62, v2
	v_mov_b32_e32 v63, v2
	v_mov_b32_e32 v64, v2
	v_mov_b32_e32 v65, v2
	v_mov_b32_e32 v66, v2
	v_mov_b32_e32 v67, v2
	v_mov_b32_e32 v68, v2
	v_mov_b32_e32 v69, v2
	v_mov_b32_e32 v74, v2
	v_mov_b32_e32 v75, v2
	v_mov_b32_e32 v76, v2
	v_mov_b32_e32 v77, v2
	v_mov_b32_e32 v86, v2
	v_mov_b32_e32 v87, v2
	v_mov_b32_e32 v88, v2
	v_mov_b32_e32 v89, v2
	v_mov_b32_e32 v94, v2
	v_mov_b32_e32 v95, v2
	v_mov_b32_e32 v96, v2
	v_mov_b32_e32 v97, v2
	v_mov_b32_e32 v106, v2
	v_mov_b32_e32 v107, v2
	v_mov_b32_e32 v108, v2
	v_mov_b32_e32 v109, v2
	v_mov_b32_e32 v114, v2
	v_mov_b32_e32 v115, v2
	v_mov_b32_e32 v116, v2
	v_mov_b32_e32 v117, v2
	v_mov_b32_e32 v124, v2
	v_mov_b32_e32 v125, v2
	v_mov_b32_e32 v126, v2
	v_mov_b32_e32 v127, v2
	v_mov_b32_e32 v82, v2
	v_mov_b32_e32 v83, v2
	v_mov_b32_e32 v84, v2
	v_mov_b32_e32 v85, v2
	v_mov_b32_e32 v70, v2
	v_mov_b32_e32 v71, v2
	v_mov_b32_e32 v72, v2
	v_mov_b32_e32 v73, v2
	v_mov_b32_e32 v78, v2
	v_mov_b32_e32 v79, v2
	v_mov_b32_e32 v80, v2
	v_mov_b32_e32 v81, v2
	v_mov_b32_e32 v90, v2
	v_mov_b32_e32 v91, v2
	v_mov_b32_e32 v92, v2
	v_mov_b32_e32 v93, v2
	v_mov_b32_e32 v98, v2
	v_mov_b32_e32 v99, v2
	v_mov_b32_e32 v100, v2
	v_mov_b32_e32 v101, v2
	v_mov_b32_e32 v110, v2
	v_mov_b32_e32 v111, v2
	v_mov_b32_e32 v112, v2
	v_mov_b32_e32 v113, v2
	v_mov_b32_e32 v118, v2
	v_mov_b32_e32 v119, v2
	v_mov_b32_e32 v120, v2
	v_mov_b32_e32 v121, v2
	v_mov_b32_e32 v128, v2
	v_mov_b32_e32 v129, v2
	v_mov_b32_e32 v130, v2
	v_mov_b32_e32 v131, v2
	v_mov_b32_e32 v136, v2
	v_mov_b32_e32 v137, v2
	v_mov_b32_e32 v138, v2
	v_mov_b32_e32 v139, v2
	v_readfirstlane_b32 s101, v242
	s_nop 3
	s_lshr_b32 s101, s101, 8
	s_cmp_eq_u32 s101, 1
	s_cbranch_scc0 .Lsp_1
	s_setprio 1
.Lsp_1:
.LBB0_701:
	s_add_u32 s18, s56, 0xfffc0080
	s_addc_u32 s19, s57, -1
	s_add_i32 s69, 0, 0x10000
	s_cmp_eq_u32 s68, 12
	s_cselect_b32 s61, s22, s19
	s_cselect_b32 s60, s23, s18
	v_add_u32_e32 v122, s69, v184
	s_cselect_b32 s59, s42, s49
	s_cselect_b32 s58, s43, s47
	s_add_i32 s70, 0, 0x14000
	ds_read_b128 v[102:105], v122
	ds_read_b128 v[132:135], v122 offset:1024
	ds_read_b128 v[140:143], v122 offset:2048
	ds_read_b128 v[144:147], v122 offset:3072
	v_add_u32_e32 v122, s70, v184
	ds_read_b128 v[148:151], v122
	ds_read_b128 v[166:169], v122 offset:1024
	ds_read_b128 v[170:173], v122 offset:2048
	ds_read_b128 v[174:177], v122 offset:3072
	v_lshl_add_u64 v[122:123], s[56:57], 0, v[164:165]
	s_add_i32 m0, s55, 0xc000
	ds_read_b128 v[178:181], v186
	ds_read_b128 v[188:191], v186 offset:1024
	ds_read_b128 v[200:203], v186 offset:2048
	ds_read_b128 v[206:209], v186 offset:3072
	ds_read_b128 v[210:213], v186 offset:4096
	ds_read_b128 v[214:217], v186 offset:5120
	ds_read_b128 v[218:221], v186 offset:6144
	ds_read_b128 v[222:225], v186 offset:7168
	global_load_lds_dwordx4 v[122:123], off
	v_lshl_add_u64 v[122:123], s[56:57], 0, v[162:163]
	s_add_i32 m0, s55, 0xe000
	s_nop 0
	global_load_lds_dwordx4 v[122:123], off
	s_waitcnt vmcnt(8)
	s_waitcnt lgkmcnt(0)
	s_barrier
; #define PG8_STAGE(bufoff, gbase, voff) do { _Pragma("unroll") for (int _i = 0; _i < 2; ++_i) \
;         __builtin_amdgcn_global_load_lds((const unsigned*)((const char*)(gbase) + (voff)[_i]), (LAS unsigned*)(lds + (bufoff) + ldsw + _i * 8192), 16, 0, 0); } while (0)
; #define PG8_LDA(dst, b, h) do { _Pragma("unroll") for (int m = 0; m < 4; ++m) _Pragma("unroll") for (int k = 0; k < 2; ++k) dst[m][k] = *(const LAS bf16x8*)(lds + PG8_SA(b, h) + aoff + m * 2048 + k * 1024); } while (0)
; #define PG8_MMA(ai, bj, At, Bt) do { __builtin_amdgcn_s_setprio(1); _Pragma("unroll") for (int m = 0; m < 4; ++m) _Pragma("unroll") for (int n = 0; n < 2; ++n) _Pragma("unroll") for (int k = 0; k < 2; ++k) \
;         acc[ai][bj][m][n] = __builtin_amdgcn_mfma_f32_16x16x32_bf16(Bt[n][k], At[m][k], acc[ai][bj][m][n], 0, 0, 0); __builtin_amdgcn_s_setprio(0); } while (0)
; #define PG8_WAIT_V(n) asm volatile("s_waitcnt vmcnt(" #n ")" ::: "memory")
; #define PG8_WAIT_L(n) asm volatile("s_waitcnt lgkmcnt(" #n ")" ::: "memory")
; #define PG8_BAR __builtin_amdgcn_s_barrier()
; #define PG8_SCHED __builtin_amdgcn_sched_barrier(0)
; template <class Epi>
; DI void gemm_phase(LAS unsigned char* lds, const Gemm g, const StaticOrder& S, const Epi& E) {
;     ...
;             PG8_WAIT_V(8); PG8_WAIT_L(0); PG8_BAR; PG8_MMA(0, 0, At, B0); PG8_MMA(0, 1, At, B1); PG8_BAR; PG8_SCHED;
;             PG8_LDA(At, 0, 1); PG8_STAGE(PG8_SB(0, 0), b2, voffB); PG8_STAGE(PG8_SB(0, 1), b2 + hstep, voffB); PG8_STAGE(PG8_SA(0, 0), a2, voffA);
;             PG8_WAIT_V(8); PG8_WAIT_L(0); PG8_BAR; PG8_MMA(1, 0, At, B0); PG8_MMA(1, 1, At, B1); PG8_BAR; PG8_SCHED;
	s_waitcnt lgkmcnt(0)
	v_mfma_f32_16x16x32_bf16 v[136:139], v[102:105], v[178:181], v[136:139]
	v_mfma_f32_16x16x32_bf16 v[128:131], v[140:143], v[178:181], v[128:131]
	v_mfma_f32_16x16x32_bf16 v[118:121], v[102:105], v[200:203], v[118:121]
	v_mfma_f32_16x16x32_bf16 v[110:113], v[140:143], v[200:203], v[110:113]
	v_mfma_f32_16x16x32_bf16 v[98:101], v[102:105], v[210:213], v[98:101]
	v_mfma_f32_16x16x32_bf16 v[90:93], v[140:143], v[210:213], v[90:93]
	v_mfma_f32_16x16x32_bf16 v[78:81], v[102:105], v[218:221], v[78:81]
	v_mfma_f32_16x16x32_bf16 v[70:73], v[140:143], v[218:221], v[70:73]
	v_mfma_f32_16x16x32_bf16 v[136:139], v[132:135], v[188:191], v[136:139]
	v_mfma_f32_16x16x32_bf16 v[128:131], v[144:147], v[188:191], v[128:131]
	v_mfma_f32_16x16x32_bf16 v[118:121], v[132:135], v[206:209], v[118:121]
	v_mfma_f32_16x16x32_bf16 v[110:113], v[144:147], v[206:209], v[110:113]
	v_mfma_f32_16x16x32_bf16 v[98:101], v[132:135], v[214:217], v[98:101]
	v_mfma_f32_16x16x32_bf16 v[90:93], v[144:147], v[214:217], v[90:93]
	v_mfma_f32_16x16x32_bf16 v[78:81], v[132:135], v[222:225], v[78:81]
	v_mfma_f32_16x16x32_bf16 v[70:73], v[144:147], v[222:225], v[70:73]
	v_mfma_f32_16x16x32_bf16 v[82:85], v[148:151], v[178:181], v[82:85]
	v_mfma_f32_16x16x32_bf16 v[122:125], v[170:173], v[178:181], v[124:127]
	v_mfma_f32_16x16x32_bf16 v[114:117], v[148:151], v[200:203], v[114:117]
	v_mfma_f32_16x16x32_bf16 v[106:109], v[170:173], v[200:203], v[106:109]
	v_mfma_f32_16x16x32_bf16 v[94:97], v[148:151], v[210:213], v[94:97]
	v_mfma_f32_16x16x32_bf16 v[86:89], v[170:173], v[210:213], v[86:89]
	v_mfma_f32_16x16x32_bf16 v[74:77], v[148:151], v[218:221], v[74:77]
	v_mfma_f32_16x16x32_bf16 v[66:69], v[170:173], v[218:221], v[66:69]
	v_mfma_f32_16x16x32_bf16 v[82:85], v[166:169], v[188:191], v[82:85]
	v_mfma_f32_16x16x32_bf16 v[122:125], v[174:177], v[188:191], v[122:125]
	v_mfma_f32_16x16x32_bf16 v[114:117], v[166:169], v[206:209], v[114:117]
	v_mfma_f32_16x16x32_bf16 v[106:109], v[174:177], v[206:209], v[106:109]
	v_mfma_f32_16x16x32_bf16 v[94:97], v[166:169], v[214:217], v[94:97]
	v_mfma_f32_16x16x32_bf16 v[86:89], v[174:177], v[214:217], v[86:89]
	v_mfma_f32_16x16x32_bf16 v[74:77], v[166:169], v[222:225], v[74:77]
	v_mfma_f32_16x16x32_bf16 v[66:69], v[174:177], v[222:225], v[66:69]
	s_barrier
	s_add_i32 s18, s69, s37
	v_lshl_add_u64 v[182:183], s[58:59], 0, v[156:157]
	s_mov_b32 m0, s18
	ds_read_b128 v[178:181], v186 offset:16384
	ds_read_b128 v[188:191], v186 offset:17408
	ds_read_b128 v[200:203], v186 offset:18432
	ds_read_b128 v[206:209], v186 offset:19456
	ds_read_b128 v[210:213], v186 offset:20480
	ds_read_b128 v[214:217], v186 offset:21504
	ds_read_b128 v[218:221], v186 offset:22528
	ds_read_b128 v[222:225], v186 offset:23552
	global_load_lds_dwordx4 v[182:183], off
	s_add_i32 m0, s18, 0x2000
	s_add_u32 s18, s58, 0x40000
	v_lshl_add_u64 v[192:193], s[58:59], 0, v[152:153]
	s_addc_u32 s19, s59, 0
	s_add_i32 s69, s70, s37
	global_load_lds_dwordx4 v[192:193], off
	v_lshl_add_u64 v[126:127], s[18:19], 0, v[156:157]
	s_mov_b32 m0, s69
	v_lshl_add_u64 v[204:205], s[60:61], 0, v[158:159]
	global_load_lds_dwordx4 v[126:127], off
	v_lshl_add_u64 v[126:127], s[18:19], 0, v[152:153]
	s_add_i32 m0, s69, 0x2000
	v_lshl_add_u64 v[226:227], s[60:61], 0, v[154:155]
	global_load_lds_dwordx4 v[126:127], off
	s_mov_b32 m0, s55
	s_nop 0
	global_load_lds_dwordx4 v[204:205], off
	s_mov_b32 m0, s63
	s_nop 0
	global_load_lds_dwordx4 v[226:227], off
	s_waitcnt vmcnt(8)
	s_waitcnt lgkmcnt(0)
	s_barrier
	s_waitcnt lgkmcnt(0)
	v_mfma_f32_16x16x32_bf16 v[62:65], v[102:105], v[178:181], v[62:65]
	v_mfma_f32_16x16x32_bf16 v[54:57], v[140:143], v[178:181], v[54:57]
	v_mfma_f32_16x16x32_bf16 v[46:49], v[102:105], v[200:203], v[46:49]
	v_mfma_f32_16x16x32_bf16 v[38:41], v[140:143], v[200:203], v[38:41]
	v_mfma_f32_16x16x32_bf16 v[30:33], v[102:105], v[210:213], v[30:33]
	v_mfma_f32_16x16x32_bf16 v[22:25], v[140:143], v[210:213], v[22:25]
	v_mfma_f32_16x16x32_bf16 v[14:17], v[102:105], v[218:221], v[14:17]
	v_mfma_f32_16x16x32_bf16 v[6:9], v[140:143], v[218:221], v[6:9]
	v_mfma_f32_16x16x32_bf16 v[62:65], v[132:135], v[188:191], v[62:65]
	v_mfma_f32_16x16x32_bf16 v[54:57], v[144:147], v[188:191], v[54:57]
	v_mfma_f32_16x16x32_bf16 v[46:49], v[132:135], v[206:209], v[46:49]
	v_mfma_f32_16x16x32_bf16 v[38:41], v[144:147], v[206:209], v[38:41]
	v_mfma_f32_16x16x32_bf16 v[30:33], v[132:135], v[214:217], v[30:33]
	v_mfma_f32_16x16x32_bf16 v[22:25], v[144:147], v[214:217], v[22:25]
	v_mfma_f32_16x16x32_bf16 v[14:17], v[132:135], v[222:225], v[14:17]
	v_mfma_f32_16x16x32_bf16 v[6:9], v[144:147], v[222:225], v[6:9]
	v_mfma_f32_16x16x32_bf16 v[58:61], v[148:151], v[178:181], v[58:61]
	v_mfma_f32_16x16x32_bf16 v[50:53], v[170:173], v[178:181], v[50:53]
	v_mfma_f32_16x16x32_bf16 v[42:45], v[148:151], v[200:203], v[42:45]
	v_mfma_f32_16x16x32_bf16 v[34:37], v[170:173], v[200:203], v[34:37]
	v_mfma_f32_16x16x32_bf16 v[26:29], v[148:151], v[210:213], v[26:29]
	v_mfma_f32_16x16x32_bf16 v[18:21], v[170:173], v[210:213], v[18:21]
	v_mfma_f32_16x16x32_bf16 v[10:13], v[148:151], v[218:221], v[10:13]
	v_mfma_f32_16x16x32_bf16 v[2:5], v[170:173], v[218:221], v[2:5]
	v_mfma_f32_16x16x32_bf16 v[58:61], v[166:169], v[188:191], v[58:61]
	v_mfma_f32_16x16x32_bf16 v[50:53], v[174:177], v[188:191], v[50:53]
	v_mfma_f32_16x16x32_bf16 v[42:45], v[166:169], v[206:209], v[42:45]
	v_mfma_f32_16x16x32_bf16 v[34:37], v[174:177], v[206:209], v[34:37]
	v_mfma_f32_16x16x32_bf16 v[26:29], v[166:169], v[214:217], v[26:29]
	v_mfma_f32_16x16x32_bf16 v[18:21], v[174:177], v[214:217], v[18:21]
	v_mfma_f32_16x16x32_bf16 v[10:13], v[166:169], v[222:225], v[10:13]
	v_mfma_f32_16x16x32_bf16 v[2:5], v[174:177], v[222:225], v[2:5]
	s_barrier
; #define PG8_STAGE(bufoff, gbase, voff) do { _Pragma("unroll") for (int _i = 0; _i < 2; ++_i) \
;         __builtin_amdgcn_global_load_lds((const unsigned*)((const char*)(gbase) + (voff)[_i]), (LAS unsigned*)(lds + (bufoff) + ldsw + _i * 8192), 16, 0, 0); } while (0)
; #define PG8_LDA(dst, b, h) do { _Pragma("unroll") for (int m = 0; m < 4; ++m) _Pragma("unroll") for (int k = 0; k < 2; ++k) dst[m][k] = *(const LAS bf16x8*)(lds + PG8_SA(b, h) + aoff + m * 2048 + k * 1024); } while (0)
; #define PG8_LDB(dst, b, h) do { _Pragma("unroll") for (int n = 0; n < 2; ++n) _Pragma("unroll") for (int k = 0; k < 2; ++k) dst[n][k] = *(const LAS bf16x8*)(lds + PG8_SB(b, h) + boff + n * 2048 + k * 1024); } while (0)
; #define PG8_MMA(ai, bj, At, Bt) do { __builtin_amdgcn_s_setprio(1); _Pragma("unroll") for (int m = 0; m < 4; ++m) _Pragma("unroll") for (int n = 0; n < 2; ++n) _Pragma("unroll") for (int k = 0; k < 2; ++k) \
;         acc[ai][bj][m][n] = __builtin_amdgcn_mfma_f32_16x16x32_bf16(Bt[n][k], At[m][k], acc[ai][bj][m][n], 0, 0, 0); __builtin_amdgcn_s_setprio(0); } while (0)
; #define PG8_WAIT_V(n) asm volatile("s_waitcnt vmcnt(" #n ")" ::: "memory")
; #define PG8_WAIT_L(n) asm volatile("s_waitcnt lgkmcnt(" #n ")" ::: "memory")
; #define PG8_BAR __builtin_amdgcn_s_barrier()
; #define PG8_SCHED __builtin_amdgcn_sched_barrier(0)
; template <class Epi>
; DI void gemm_phase(LAS unsigned char* lds, const Gemm g, const StaticOrder& S, const Epi& E) {
;     ...
;             PG8_LDB(B0, 1, 0); PG8_LDB(B1, 1, 1); PG8_SCHED; PG8_LDA(At, 1, 0); PG8_STAGE(PG8_SA(0, 1), a2 + hstep, voffA);
;             PG8_WAIT_V(8); PG8_WAIT_L(0); PG8_BAR; PG8_MMA(0, 0, At, B0); PG8_MMA(0, 1, At, B1); PG8_BAR; PG8_SCHED;
	s_add_i32 s69, 0, 0x18000
	v_add_u32_e32 v126, s69, v184
	s_add_i32 s70, 0, 0x1c000
	ds_read_b128 v[102:105], v126
	ds_read_b128 v[132:135], v126 offset:1024
	ds_read_b128 v[140:143], v126 offset:2048
	ds_read_b128 v[144:147], v126 offset:3072
	v_add_u32_e32 v126, s70, v184
	ds_read_b128 v[148:151], v126
	ds_read_b128 v[166:169], v126 offset:1024
	ds_read_b128 v[170:173], v126 offset:2048
	ds_read_b128 v[174:177], v126 offset:3072
	s_add_u32 s18, s60, 0x40000
	s_addc_u32 s19, s61, 0
	s_mov_b32 m0, s64
	v_lshl_add_u64 v[126:127], s[18:19], 0, v[158:159]
	ds_read_b128 v[178:181], v186 offset:32768
	ds_read_b128 v[188:191], v186 offset:33792
	ds_read_b128 v[200:203], v186 offset:34816
	ds_read_b128 v[206:209], v186 offset:35840
	ds_read_b128 v[210:213], v186 offset:36864
	ds_read_b128 v[214:217], v186 offset:37888
	ds_read_b128 v[218:221], v186 offset:38912
	ds_read_b128 v[222:225], v186 offset:39936
	global_load_lds_dwordx4 v[126:127], off
	v_lshl_add_u64 v[126:127], s[18:19], 0, v[154:155]
	s_mov_b32 m0, s65
	s_nop 0
	global_load_lds_dwordx4 v[126:127], off
	s_waitcnt vmcnt(8)
	s_waitcnt lgkmcnt(0)
	s_barrier
	s_waitcnt lgkmcnt(0)
	v_mfma_f32_16x16x32_bf16 v[136:139], v[102:105], v[178:181], v[136:139]
	v_mfma_f32_16x16x32_bf16 v[126:129], v[140:143], v[178:181], v[128:131]
	v_mfma_f32_16x16x32_bf16 v[118:121], v[102:105], v[200:203], v[118:121]
	v_mfma_f32_16x16x32_bf16 v[110:113], v[140:143], v[200:203], v[110:113]
	v_mfma_f32_16x16x32_bf16 v[98:101], v[102:105], v[210:213], v[98:101]
	v_mfma_f32_16x16x32_bf16 v[90:93], v[140:143], v[210:213], v[90:93]
	v_mfma_f32_16x16x32_bf16 v[78:81], v[102:105], v[218:221], v[78:81]
	v_mfma_f32_16x16x32_bf16 v[70:73], v[140:143], v[218:221], v[70:73]
	v_mfma_f32_16x16x32_bf16 v[136:139], v[132:135], v[188:191], v[136:139]
	v_mfma_f32_16x16x32_bf16 v[128:131], v[144:147], v[188:191], v[126:129]
	v_mfma_f32_16x16x32_bf16 v[118:121], v[132:135], v[206:209], v[118:121]
	v_mfma_f32_16x16x32_bf16 v[110:113], v[144:147], v[206:209], v[110:113]
	v_mfma_f32_16x16x32_bf16 v[98:101], v[132:135], v[214:217], v[98:101]
	v_mfma_f32_16x16x32_bf16 v[90:93], v[144:147], v[214:217], v[90:93]
	v_mfma_f32_16x16x32_bf16 v[78:81], v[132:135], v[222:225], v[78:81]
	v_mfma_f32_16x16x32_bf16 v[70:73], v[144:147], v[222:225], v[70:73]
	v_mfma_f32_16x16x32_bf16 v[82:85], v[148:151], v[178:181], v[82:85]
	v_mfma_f32_16x16x32_bf16 v[122:125], v[170:173], v[178:181], v[122:125]
	v_mfma_f32_16x16x32_bf16 v[114:117], v[148:151], v[200:203], v[114:117]
	v_mfma_f32_16x16x32_bf16 v[106:109], v[170:173], v[200:203], v[106:109]
	v_mfma_f32_16x16x32_bf16 v[94:97], v[148:151], v[210:213], v[94:97]
	v_mfma_f32_16x16x32_bf16 v[86:89], v[170:173], v[210:213], v[86:89]
	v_mfma_f32_16x16x32_bf16 v[74:77], v[148:151], v[218:221], v[74:77]
	v_mfma_f32_16x16x32_bf16 v[66:69], v[170:173], v[218:221], v[66:69]
	v_mfma_f32_16x16x32_bf16 v[82:85], v[166:169], v[188:191], v[82:85]
	v_mfma_f32_16x16x32_bf16 v[124:127], v[174:177], v[188:191], v[122:125]
	v_mfma_f32_16x16x32_bf16 v[114:117], v[166:169], v[206:209], v[114:117]
	v_mfma_f32_16x16x32_bf16 v[106:109], v[174:177], v[206:209], v[106:109]
	v_mfma_f32_16x16x32_bf16 v[94:97], v[166:169], v[214:217], v[94:97]
	v_mfma_f32_16x16x32_bf16 v[86:89], v[174:177], v[214:217], v[86:89]
	v_mfma_f32_16x16x32_bf16 v[74:77], v[166:169], v[222:225], v[74:77]
	v_mfma_f32_16x16x32_bf16 v[66:69], v[174:177], v[222:225], v[66:69]
	s_barrier
; #define PG8_STAGE(bufoff, gbase, voff) do { _Pragma("unroll") for (int _i = 0; _i < 2; ++_i) \
;         __builtin_amdgcn_global_load_lds((const unsigned*)((const char*)(gbase) + (voff)[_i]), (LAS unsigned*)(lds + (bufoff) + ldsw + _i * 8192), 16, 0, 0); } while (0)
; #define PG8_LDA(dst, b, h) do { _Pragma("unroll") for (int m = 0; m < 4; ++m) _Pragma("unroll") for (int k = 0; k < 2; ++k) dst[m][k] = *(const LAS bf16x8*)(lds + PG8_SA(b, h) + aoff + m * 2048 + k * 1024); } while (0)
; #define PG8_LDB(dst, b, h) do { _Pragma("unroll") for (int n = 0; n < 2; ++n) _Pragma("unroll") for (int k = 0; k < 2; ++k) dst[n][k] = *(const LAS bf16x8*)(lds + PG8_SB(b, h) + boff + n * 2048 + k * 1024); } while (0)
; #define PG8_WAIT_V(n) asm volatile("s_waitcnt vmcnt(" #n ")" ::: "memory")
; #define PG8_BAR __builtin_amdgcn_s_barrier()
; template <class Epi>
; DI void gemm_phase(LAS unsigned char* lds, const Gemm g, const StaticOrder& S, const Epi& E) {
;     ...
;         for (int t = 0; t < nt; t += 2) {
;             const bool last = (t == nt - 2);
;             const char* a1 = cA + (size_t)(t + 1) * kstep;
;             const char* a2 = last ? nA : cA + (size_t)(t + 2) * kstep; const char* b2 = last ? nB : cB + (size_t)(t + 2) * kstep;
;             const char* a3 = a2 + kstep; const char* b3 = b2 + kstep;
;             PG8_LDB(B0, 0, 0); PG8_LDB(B1, 0, 1); PG8_SCHED; PG8_LDA(At, 0, 0); PG8_STAGE(PG8_SA(1, 1), a1 + hstep, voffA);
;             PG8_WAIT_V(8); PG8_WAIT_L(0); PG8_BAR; PG8_MMA(0, 0, At, B0); PG8_MMA(0, 1, At, B1); PG8_BAR; PG8_SCHED;
;             PG8_LDA(At, 0, 1); PG8_STAGE(PG8_SB(0, 0), b2, voffB); PG8_STAGE(PG8_SB(0, 1), b2 + hstep, voffB); PG8_STAGE(PG8_SA(0, 0), a2, voffA);
;             PG8_WAIT_V(8); PG8_WAIT_L(0); PG8_BAR; PG8_MMA(1, 0, At, B0); PG8_MMA(1, 1, At, B1); PG8_BAR; PG8_SCHED;
;             PG8_LDB(B0, 1, 0); PG8_LDB(B1, 1, 1); PG8_SCHED; PG8_LDA(At, 1, 0); PG8_STAGE(PG8_SA(0, 1), a2 + hstep, voffA);
;             PG8_WAIT_V(8); PG8_WAIT_L(0); PG8_BAR; PG8_MMA(0, 0, At, B0); PG8_MMA(0, 1, At, B1); PG8_BAR; PG8_SCHED;
;             PG8_LDA(At, 1, 1); PG8_STAGE(PG8_SB(1, 0), b3, voffB); PG8_STAGE(PG8_SB(1, 1), b3 + hstep, voffB); PG8_STAGE(PG8_SA(1, 0), a3, voffA);
;             PG8_WAIT_V(8); PG8_WAIT_L(0); PG8_BAR; PG8_MMA(1, 0, At, B0); PG8_MMA(1, 1, At, B1); PG8_BAR; PG8_SCHED;
;         }
;         if (wr == 0) PG8_BAR;
	s_add_i32 s18, s69, s37
	v_lshl_add_u64 v[122:123], v[182:183], 0, s[20:21]
	s_mov_b32 m0, s18
	ds_read_b128 v[178:181], v186 offset:49152
	ds_read_b128 v[188:191], v186 offset:50176
	ds_read_b128 v[200:203], v186 offset:51200
	ds_read_b128 v[206:209], v186 offset:52224
	ds_read_b128 v[210:213], v186 offset:53248
	ds_read_b128 v[214:217], v186 offset:54272
	ds_read_b128 v[218:221], v186 offset:55296
	ds_read_b128 v[222:225], v186 offset:56320
	global_load_lds_dwordx4 v[122:123], off
	s_add_i32 m0, s18, 0x2000
	s_add_u32 s18, s58, 0x40080
	v_lshl_add_u64 v[122:123], v[192:193], 0, s[20:21]
	s_addc_u32 s19, s59, 0
	s_add_i32 s58, s70, s37
	global_load_lds_dwordx4 v[122:123], off
	v_lshl_add_u64 v[122:123], s[18:19], 0, v[156:157]
	s_mov_b32 m0, s58
	s_nop 0
	global_load_lds_dwordx4 v[122:123], off
	v_lshl_add_u64 v[122:123], s[18:19], 0, v[152:153]
	s_add_i32 m0, s58, 0x2000
	s_nop 0
	global_load_lds_dwordx4 v[122:123], off
	v_lshl_add_u64 v[122:123], v[204:205], 0, s[20:21]
	s_mov_b32 m0, s66
	s_nop 0
	global_load_lds_dwordx4 v[122:123], off
	v_lshl_add_u64 v[122:123], v[226:227], 0, s[20:21]
	s_mov_b32 m0, s67
	s_nop 0
	global_load_lds_dwordx4 v[122:123], off
	s_waitcnt vmcnt(8)
	s_waitcnt lgkmcnt(0)
	s_barrier
	s_waitcnt lgkmcnt(0)
	v_mfma_f32_16x16x32_bf16 v[62:65], v[102:105], v[178:181], v[62:65]
	v_mfma_f32_16x16x32_bf16 v[54:57], v[140:143], v[178:181], v[54:57]
	v_mfma_f32_16x16x32_bf16 v[46:49], v[102:105], v[200:203], v[46:49]
	v_mfma_f32_16x16x32_bf16 v[38:41], v[140:143], v[200:203], v[38:41]
	v_mfma_f32_16x16x32_bf16 v[30:33], v[102:105], v[210:213], v[30:33]
	v_mfma_f32_16x16x32_bf16 v[22:25], v[140:143], v[210:213], v[22:25]
	v_mfma_f32_16x16x32_bf16 v[14:17], v[102:105], v[218:221], v[14:17]
	v_mfma_f32_16x16x32_bf16 v[6:9], v[140:143], v[218:221], v[6:9]
	v_mfma_f32_16x16x32_bf16 v[62:65], v[132:135], v[188:191], v[62:65]
	v_mfma_f32_16x16x32_bf16 v[54:57], v[144:147], v[188:191], v[54:57]
	v_mfma_f32_16x16x32_bf16 v[46:49], v[132:135], v[206:209], v[46:49]
	v_mfma_f32_16x16x32_bf16 v[38:41], v[144:147], v[206:209], v[38:41]
	v_mfma_f32_16x16x32_bf16 v[30:33], v[132:135], v[214:217], v[30:33]
	v_mfma_f32_16x16x32_bf16 v[22:25], v[144:147], v[214:217], v[22:25]
	v_mfma_f32_16x16x32_bf16 v[14:17], v[132:135], v[222:225], v[14:17]
	v_mfma_f32_16x16x32_bf16 v[6:9], v[144:147], v[222:225], v[6:9]
	v_mfma_f32_16x16x32_bf16 v[58:61], v[148:151], v[178:181], v[58:61]
	v_mfma_f32_16x16x32_bf16 v[50:53], v[170:173], v[178:181], v[50:53]
	v_mfma_f32_16x16x32_bf16 v[42:45], v[148:151], v[200:203], v[42:45]
	v_mfma_f32_16x16x32_bf16 v[34:37], v[170:173], v[200:203], v[34:37]
	v_mfma_f32_16x16x32_bf16 v[26:29], v[148:151], v[210:213], v[26:29]
	v_mfma_f32_16x16x32_bf16 v[18:21], v[170:173], v[210:213], v[18:21]
	v_mfma_f32_16x16x32_bf16 v[10:13], v[148:151], v[218:221], v[10:13]
	v_mfma_f32_16x16x32_bf16 v[2:5], v[170:173], v[218:221], v[2:5]
	v_mfma_f32_16x16x32_bf16 v[58:61], v[166:169], v[188:191], v[58:61]
	v_mfma_f32_16x16x32_bf16 v[50:53], v[174:177], v[188:191], v[50:53]
	v_mfma_f32_16x16x32_bf16 v[42:45], v[166:169], v[206:209], v[42:45]
	v_mfma_f32_16x16x32_bf16 v[34:37], v[174:177], v[206:209], v[34:37]
	v_mfma_f32_16x16x32_bf16 v[26:29], v[166:169], v[214:217], v[26:29]
	v_mfma_f32_16x16x32_bf16 v[18:21], v[174:177], v[214:217], v[18:21]
	v_mfma_f32_16x16x32_bf16 v[10:13], v[166:169], v[222:225], v[10:13]
	v_mfma_f32_16x16x32_bf16 v[2:5], v[174:177], v[222:225], v[2:5]
	s_barrier
	s_add_i32 s68, s68, 2
	s_add_u32 s47, s47, 0x100
	s_addc_u32 s49, s49, 0
	s_add_u32 s56, s56, 0x100
	s_addc_u32 s57, s57, 0
	s_cmp_gt_u32 s68, 13
	s_cbranch_scc0 .LBB0_701
	s_setprio 0
	s_and_b64 vcc, exec, s[44:45]
	s_cbranch_vccz .LBB0_704
	s_barrier

; #define PG8_STAGE(bufoff, gbase, voff) do { _Pragma("unroll") for (int _i = 0; _i < 2; ++_i) \
;         __builtin_amdgcn_global_load_lds((const unsigned*)((const char*)(gbase) + (voff)[_i]), (LAS unsigned*)(lds + (bufoff) + ldsw + _i * 8192), 16, 0, 0); } while (0)
; #define PG8_LDA(dst, b, h) do { _Pragma("unroll") for (int m = 0; m < 4; ++m) _Pragma("unroll") for (int k = 0; k < 2; ++k) dst[m][k] = *(const LAS bf16x8*)(lds + PG8_SA(b, h) + aoff + m * 2048 + k * 1024); } while (0)
; #define PG8_LDB(dst, b, h) do { _Pragma("unroll") for (int n = 0; n < 2; ++n) _Pragma("unroll") for (int k = 0; k < 2; ++k) dst[n][k] = *(const LAS bf16x8*)(lds + PG8_SB(b, h) + boff + n * 2048 + k * 1024); } while (0)
; #define PG8_MMA(ai, bj, At, Bt) do { __builtin_amdgcn_s_setprio(1); _Pragma("unroll") for (int m = 0; m < 4; ++m) _Pragma("unroll") for (int n = 0; n < 2; ++n) _Pragma("unroll") for (int k = 0; k < 2; ++k) \
;         acc[ai][bj][m][n] = __builtin_amdgcn_mfma_f32_16x16x32_bf16(Bt[n][k], At[m][k], acc[ai][bj][m][n], 0, 0, 0); __builtin_amdgcn_s_setprio(0); } while (0)
; #define PG8_WAIT_V(n) asm volatile("s_waitcnt vmcnt(" #n ")" ::: "memory")
; template <class Epi>
; DI void gemm_phase(LAS unsigned char* lds, const Gemm g, const StaticOrder& S, const Epi& E) {
;     ...
;         const bool has_next = S.next(ui + 1, nxt);
;         const char* nA = has_next ? (const char*)g.A + (size_t)nxt.pm * tstep : cA; const char* nB = has_next ? (const char*)g.Bt + (size_t)nxt.pn * tstep : cB;
;         for (int t = 0; t < nt; t += 2) {
;             const bool last = (t == nt - 2);
;             const char* a1 = cA + (size_t)(t + 1) * kstep;
;             const char* a2 = last ? nA : cA + (size_t)(t + 2) * kstep; const char* b2 = last ? nB : cB + (size_t)(t + 2) * kstep;
;             const char* a3 = a2 + kstep; const char* b3 = b2 + kstep;
;             PG8_LDB(B0, 0, 0); PG8_LDB(B1, 0, 1); PG8_SCHED; PG8_LDA(At, 0, 0); PG8_STAGE(PG8_SA(1, 1), a1 + hstep, voffA);
;             PG8_WAIT_V(8); PG8_WAIT_L(0); PG8_BAR; PG8_MMA(0, 0, At, B0); PG8_MMA(0, 1, At, B1); PG8_BAR; PG8_SCHED;
;     ...
;         for (int a = 0; a < 2; ++a)
; #pragma unroll
;             for (int b = 0; b < 2; ++b)
; #pragma unroll
;                 for (int m = 0; m < 4; ++m)
; #pragma unroll
;                     for (int n = 0; n < 2; ++n) acc[a][b][m][n] = (f32x4){0.f, 0.f, 0.f, 0.f};
.LBB0_782:
	s_add_u32 s73, s60, 0x100
	v_mov_b32_e32 v2, 0
	s_addc_u32 s91, s61, 0
	s_mov_b32 s93, -2
	v_mov_b32_e32 v3, v2
	v_mov_b32_e32 v4, v2
	v_mov_b32_e32 v5, v2
	v_mov_b32_e32 v6, v2
	v_mov_b32_e32 v7, v2
	v_mov_b32_e32 v8, v2
	v_mov_b32_e32 v9, v2
	v_mov_b32_e32 v18, v2
	v_mov_b32_e32 v19, v2
	v_mov_b32_e32 v20, v2
	v_mov_b32_e32 v21, v2
	v_mov_b32_e32 v22, v2
	v_mov_b32_e32 v23, v2
	v_mov_b32_e32 v24, v2
	v_mov_b32_e32 v25, v2
	v_mov_b32_e32 v34, v2
	v_mov_b32_e32 v35, v2
	v_mov_b32_e32 v36, v2
	v_mov_b32_e32 v37, v2
	v_mov_b32_e32 v38, v2
	v_mov_b32_e32 v39, v2
	v_mov_b32_e32 v40, v2
	v_mov_b32_e32 v41, v2
	v_mov_b32_e32 v50, v2
	v_mov_b32_e32 v51, v2
	v_mov_b32_e32 v52, v2
	v_mov_b32_e32 v53, v2
	v_mov_b32_e32 v54, v2
	v_mov_b32_e32 v55, v2
	v_mov_b32_e32 v56, v2
	v_mov_b32_e32 v57, v2
	v_mov_b32_e32 v10, v2
	v_mov_b32_e32 v11, v2
	v_mov_b32_e32 v12, v2
	v_mov_b32_e32 v13, v2
	v_mov_b32_e32 v14, v2
	v_mov_b32_e32 v15, v2
	v_mov_b32_e32 v16, v2
	v_mov_b32_e32 v17, v2
	v_mov_b32_e32 v26, v2
	v_mov_b32_e32 v27, v2
	v_mov_b32_e32 v28, v2
	v_mov_b32_e32 v29, v2
	v_mov_b32_e32 v30, v2
	v_mov_b32_e32 v31, v2
	v_mov_b32_e32 v32, v2
	v_mov_b32_e32 v33, v2
	v_mov_b32_e32 v42, v2
	v_mov_b32_e32 v43, v2
	v_mov_b32_e32 v44, v2
	v_mov_b32_e32 v45, v2
	v_mov_b32_e32 v46, v2
	v_mov_b32_e32 v47, v2
	v_mov_b32_e32 v48, v2
	v_mov_b32_e32 v49, v2
	v_mov_b32_e32 v58, v2
	v_mov_b32_e32 v59, v2
	v_mov_b32_e32 v60, v2
	v_mov_b32_e32 v61, v2
	v_mov_b32_e32 v62, v2
	v_mov_b32_e32 v63, v2
	v_mov_b32_e32 v64, v2
	v_mov_b32_e32 v65, v2
	v_mov_b32_e32 v66, v2
	v_mov_b32_e32 v67, v2
	v_mov_b32_e32 v68, v2
	v_mov_b32_e32 v69, v2
	v_mov_b32_e32 v70, v2
	v_mov_b32_e32 v71, v2
	v_mov_b32_e32 v72, v2
	v_mov_b32_e32 v73, v2
	v_mov_b32_e32 v82, v2
	v_mov_b32_e32 v83, v2
	v_mov_b32_e32 v84, v2
	v_mov_b32_e32 v85, v2
	v_mov_b32_e32 v86, v2
	v_mov_b32_e32 v87, v2
	v_mov_b32_e32 v88, v2
	v_mov_b32_e32 v89, v2
	v_mov_b32_e32 v98, v2
	v_mov_b32_e32 v99, v2
	v_mov_b32_e32 v100, v2
	v_mov_b32_e32 v101, v2
	v_mov_b32_e32 v102, v2
	v_mov_b32_e32 v103, v2
	v_mov_b32_e32 v104, v2
	v_mov_b32_e32 v105, v2
	v_mov_b32_e32 v130, v2
	v_mov_b32_e32 v131, v2
	v_mov_b32_e32 v132, v2
	v_mov_b32_e32 v133, v2
	v_mov_b32_e32 v142, v2
	v_mov_b32_e32 v143, v2
	v_mov_b32_e32 v144, v2
	v_mov_b32_e32 v145, v2
	v_mov_b32_e32 v74, v2
	v_mov_b32_e32 v75, v2
	v_mov_b32_e32 v76, v2
	v_mov_b32_e32 v77, v2
	v_mov_b32_e32 v78, v2
	v_mov_b32_e32 v79, v2
	v_mov_b32_e32 v80, v2
	v_mov_b32_e32 v81, v2
	v_mov_b32_e32 v90, v2
	v_mov_b32_e32 v91, v2
	v_mov_b32_e32 v92, v2
	v_mov_b32_e32 v93, v2
	v_mov_b32_e32 v94, v2
	v_mov_b32_e32 v95, v2
	v_mov_b32_e32 v96, v2
	v_mov_b32_e32 v97, v2
	v_mov_b32_e32 v106, v2
	v_mov_b32_e32 v107, v2
	v_mov_b32_e32 v108, v2
	v_mov_b32_e32 v109, v2
	v_mov_b32_e32 v110, v2
	v_mov_b32_e32 v111, v2
	v_mov_b32_e32 v112, v2
	v_mov_b32_e32 v113, v2
	v_mov_b32_e32 v150, v2
	v_mov_b32_e32 v151, v2
	v_mov_b32_e32 v152, v2
	v_mov_b32_e32 v153, v2
	v_mov_b32_e32 v158, v2
	v_mov_b32_e32 v159, v2
	v_mov_b32_e32 v160, v2
	v_mov_b32_e32 v161, v2
	v_readfirstlane_b32 s101, v242
	s_nop 3
	s_lshr_b32 s101, s101, 8
	s_cmp_eq_u32 s101, 1
	s_cbranch_scc0 .Lsp_0
	s_setprio 1
.Lsp_0:
.LBB0_783:
	s_add_u32 s60, s58, 0x100
	s_addc_u32 s61, s59, 0
	s_add_i32 s18, 0, 0x10000
	s_cmp_eq_u32 s93, 40
	s_cselect_b32 s65, s9, s61
	s_cselect_b32 s64, s8, s60
	s_cselect_b32 s63, s57, s91
	s_cselect_b32 s62, s56, s73
	s_add_i32 s81, 0, 0x14000
	v_add_u32_e32 v126, s18, v195
	v_add_u32_e32 v154, s81, v195
	ds_read_b128 v[114:117], v126
	ds_read_b128 v[118:121], v126 offset:1024
	ds_read_b128 v[122:125], v126 offset:2048
	ds_read_b128 v[126:129], v126 offset:3072
	ds_read_b128 v[134:137], v154
	ds_read_b128 v[138:141], v154 offset:1024
	ds_read_b128 v[146:149], v154 offset:2048
	ds_read_b128 v[154:157], v154 offset:3072
	v_lshl_add_u64 v[204:205], s[58:59], 0, v[184:185]
	s_add_i32 m0, s66, 0xc000
	ds_read_b128 v[162:165], v217
	ds_read_b128 v[166:169], v217 offset:1024
	ds_read_b128 v[170:173], v217 offset:2048
	ds_read_b128 v[174:177], v217 offset:3072
	ds_read_b128 v[186:189], v217 offset:4096
	ds_read_b128 v[190:193], v217 offset:5120
	ds_read_b128 v[200:203], v217 offset:6144
	ds_read_b128 v[206:209], v217 offset:7168
	global_load_lds_dwordx4 v[204:205], off
	v_lshl_add_u64 v[204:205], s[58:59], 0, v[182:183]
	s_add_i32 m0, s66, 0xe000
	s_nop 0
	global_load_lds_dwordx4 v[204:205], off
	s_waitcnt vmcnt(8)
	s_waitcnt lgkmcnt(0)
	s_barrier
	s_waitcnt lgkmcnt(0)
	v_mfma_f32_16x16x32_bf16 v[158:161], v[114:117], v[162:165], v[158:161]
	v_mfma_f32_16x16x32_bf16 v[150:153], v[122:125], v[162:165], v[150:153]
	v_mfma_f32_16x16x32_bf16 v[110:113], v[114:117], v[170:173], v[110:113]
	v_mfma_f32_16x16x32_bf16 v[106:109], v[122:125], v[170:173], v[106:109]
	v_mfma_f32_16x16x32_bf16 v[94:97], v[114:117], v[186:189], v[94:97]
	v_mfma_f32_16x16x32_bf16 v[90:93], v[122:125], v[186:189], v[90:93]
	v_mfma_f32_16x16x32_bf16 v[78:81], v[114:117], v[200:203], v[78:81]
	v_mfma_f32_16x16x32_bf16 v[74:77], v[122:125], v[200:203], v[74:77]
	v_mfma_f32_16x16x32_bf16 v[158:161], v[118:121], v[166:169], v[158:161]
	v_mfma_f32_16x16x32_bf16 v[150:153], v[126:129], v[166:169], v[150:153]
	v_mfma_f32_16x16x32_bf16 v[110:113], v[118:121], v[174:177], v[110:113]
	v_mfma_f32_16x16x32_bf16 v[106:109], v[126:129], v[174:177], v[106:109]
	v_mfma_f32_16x16x32_bf16 v[94:97], v[118:121], v[190:193], v[94:97]
	v_mfma_f32_16x16x32_bf16 v[90:93], v[126:129], v[190:193], v[90:93]
	v_mfma_f32_16x16x32_bf16 v[78:81], v[118:121], v[206:209], v[78:81]
	v_mfma_f32_16x16x32_bf16 v[74:77], v[126:129], v[206:209], v[74:77]
	v_mfma_f32_16x16x32_bf16 v[142:145], v[134:137], v[162:165], v[142:145]
	v_mfma_f32_16x16x32_bf16 v[130:133], v[146:149], v[162:165], v[130:133]
	v_mfma_f32_16x16x32_bf16 v[102:105], v[134:137], v[170:173], v[102:105]
	v_mfma_f32_16x16x32_bf16 v[98:101], v[146:149], v[170:173], v[98:101]
	v_mfma_f32_16x16x32_bf16 v[86:89], v[134:137], v[186:189], v[86:89]
	v_mfma_f32_16x16x32_bf16 v[82:85], v[146:149], v[186:189], v[82:85]
	v_mfma_f32_16x16x32_bf16 v[70:73], v[134:137], v[200:203], v[70:73]
	v_mfma_f32_16x16x32_bf16 v[66:69], v[146:149], v[200:203], v[66:69]
	v_mfma_f32_16x16x32_bf16 v[142:145], v[138:141], v[166:169], v[142:145]
	v_mfma_f32_16x16x32_bf16 v[130:133], v[154:157], v[166:169], v[130:133]
	v_mfma_f32_16x16x32_bf16 v[102:105], v[138:141], v[174:177], v[102:105]
	v_mfma_f32_16x16x32_bf16 v[98:101], v[154:157], v[174:177], v[98:101]
	v_mfma_f32_16x16x32_bf16 v[86:89], v[138:141], v[190:193], v[86:89]
	v_mfma_f32_16x16x32_bf16 v[82:85], v[154:157], v[190:193], v[82:85]
	v_mfma_f32_16x16x32_bf16 v[70:73], v[138:141], v[206:209], v[70:73]
	v_mfma_f32_16x16x32_bf16 v[66:69], v[154:157], v[206:209], v[66:69]
	s_barrier
; #define PG8_STAGE(bufoff, gbase, voff) do { _Pragma("unroll") for (int _i = 0; _i < 2; ++_i) \
;         __builtin_amdgcn_global_load_lds((const unsigned*)((const char*)(gbase) + (voff)[_i]), (LAS unsigned*)(lds + (bufoff) + ldsw + _i * 8192), 16, 0, 0); } while (0)
; #define PG8_LDA(dst, b, h) do { _Pragma("unroll") for (int m = 0; m < 4; ++m) _Pragma("unroll") for (int k = 0; k < 2; ++k) dst[m][k] = *(const LAS bf16x8*)(lds + PG8_SA(b, h) + aoff + m * 2048 + k * 1024); } while (0)
; #define PG8_LDB(dst, b, h) do { _Pragma("unroll") for (int n = 0; n < 2; ++n) _Pragma("unroll") for (int k = 0; k < 2; ++k) dst[n][k] = *(const LAS bf16x8*)(lds + PG8_SB(b, h) + boff + n * 2048 + k * 1024); } while (0)
; #define PG8_MMA(ai, bj, At, Bt) do { __builtin_amdgcn_s_setprio(1); _Pragma("unroll") for (int m = 0; m < 4; ++m) _Pragma("unroll") for (int n = 0; n < 2; ++n) _Pragma("unroll") for (int k = 0; k < 2; ++k) \
;         acc[ai][bj][m][n] = __builtin_amdgcn_mfma_f32_16x16x32_bf16(Bt[n][k], At[m][k], acc[ai][bj][m][n], 0, 0, 0); __builtin_amdgcn_s_setprio(0); } while (0)
; #define PG8_WAIT_V(n) asm volatile("s_waitcnt vmcnt(" #n ")" ::: "memory")
; #define PG8_WAIT_L(n) asm volatile("s_waitcnt lgkmcnt(" #n ")" ::: "memory")
; #define PG8_BAR __builtin_amdgcn_s_barrier()
; #define PG8_SCHED __builtin_amdgcn_sched_barrier(0)
; template <class Epi>
; DI void gemm_phase(LAS unsigned char* lds, const Gemm g, const StaticOrder& S, const Epi& E) {
;     ...
;             PG8_LDA(At, 0, 1); PG8_STAGE(PG8_SB(0, 0), b2, voffB); PG8_STAGE(PG8_SB(0, 1), b2 + hstep, voffB); PG8_STAGE(PG8_SA(0, 0), a2, voffA);
;             PG8_WAIT_V(8); PG8_WAIT_L(0); PG8_BAR; PG8_MMA(1, 0, At, B0); PG8_MMA(1, 1, At, B1); PG8_BAR; PG8_SCHED;
;             PG8_LDB(B0, 1, 0); PG8_LDB(B1, 1, 1); PG8_SCHED; PG8_LDA(At, 1, 0); PG8_STAGE(PG8_SA(0, 1), a2 + hstep, voffA);
;             PG8_WAIT_V(8); PG8_WAIT_L(0); PG8_BAR; PG8_MMA(0, 0, At, B0); PG8_MMA(0, 1, At, B1); PG8_BAR; PG8_SCHED;
	s_add_i32 s18, s18, s37
	v_lshl_add_u64 v[204:205], s[62:63], 0, v[178:179]
	s_mov_b32 m0, s18
	ds_read_b128 v[162:165], v217 offset:16384
	ds_read_b128 v[166:169], v217 offset:17408
	ds_read_b128 v[170:173], v217 offset:18432
	ds_read_b128 v[174:177], v217 offset:19456
	ds_read_b128 v[186:189], v217 offset:20480
	ds_read_b128 v[190:193], v217 offset:21504
	ds_read_b128 v[200:203], v217 offset:22528
	ds_read_b128 v[206:209], v217 offset:23552
	global_load_lds_dwordx4 v[204:205], off
	s_add_i32 m0, s18, 0x2000
	s_add_u32 s18, s62, 0xb0000
	v_lshl_add_u64 v[210:211], s[62:63], 0, v[180:181]
	s_addc_u32 s19, s63, 0
	s_add_i32 s58, s81, s37
	global_load_lds_dwordx4 v[210:211], off
	v_lshl_add_u64 v[212:213], s[18:19], 0, v[178:179]
	s_mov_b32 m0, s58
	v_lshl_add_u64 v[214:215], s[64:65], 0, v[180:181]
	global_load_lds_dwordx4 v[212:213], off
	v_lshl_add_u64 v[212:213], s[18:19], 0, v[180:181]
	s_add_i32 m0, s58, 0x2000
	s_nop 0
	global_load_lds_dwordx4 v[212:213], off
	v_lshl_add_u64 v[212:213], s[64:65], 0, v[178:179]
	s_mov_b32 m0, s66
	s_nop 0
	global_load_lds_dwordx4 v[212:213], off
	s_mov_b32 m0, s67
	s_nop 0
	global_load_lds_dwordx4 v[214:215], off
	s_waitcnt vmcnt(8)
	s_waitcnt lgkmcnt(0)
	s_barrier
	s_waitcnt lgkmcnt(0)
	v_mfma_f32_16x16x32_bf16 v[62:65], v[114:117], v[162:165], v[62:65]
	v_mfma_f32_16x16x32_bf16 v[58:61], v[122:125], v[162:165], v[58:61]
	v_mfma_f32_16x16x32_bf16 v[46:49], v[114:117], v[170:173], v[46:49]
	v_mfma_f32_16x16x32_bf16 v[42:45], v[122:125], v[170:173], v[42:45]
	v_mfma_f32_16x16x32_bf16 v[30:33], v[114:117], v[186:189], v[30:33]
	v_mfma_f32_16x16x32_bf16 v[26:29], v[122:125], v[186:189], v[26:29]
	v_mfma_f32_16x16x32_bf16 v[14:17], v[114:117], v[200:203], v[14:17]
	v_mfma_f32_16x16x32_bf16 v[10:13], v[122:125], v[200:203], v[10:13]
	v_mfma_f32_16x16x32_bf16 v[62:65], v[118:121], v[166:169], v[62:65]
	v_mfma_f32_16x16x32_bf16 v[58:61], v[126:129], v[166:169], v[58:61]
	v_mfma_f32_16x16x32_bf16 v[46:49], v[118:121], v[174:177], v[46:49]
	v_mfma_f32_16x16x32_bf16 v[42:45], v[126:129], v[174:177], v[42:45]
	v_mfma_f32_16x16x32_bf16 v[30:33], v[118:121], v[190:193], v[30:33]
	v_mfma_f32_16x16x32_bf16 v[26:29], v[126:129], v[190:193], v[26:29]
	v_mfma_f32_16x16x32_bf16 v[14:17], v[118:121], v[206:209], v[14:17]
	v_mfma_f32_16x16x32_bf16 v[10:13], v[126:129], v[206:209], v[10:13]
	v_mfma_f32_16x16x32_bf16 v[54:57], v[134:137], v[162:165], v[54:57]
	v_mfma_f32_16x16x32_bf16 v[50:53], v[146:149], v[162:165], v[50:53]
	v_mfma_f32_16x16x32_bf16 v[38:41], v[134:137], v[170:173], v[38:41]
	v_mfma_f32_16x16x32_bf16 v[34:37], v[146:149], v[170:173], v[34:37]
	v_mfma_f32_16x16x32_bf16 v[22:25], v[134:137], v[186:189], v[22:25]
	v_mfma_f32_16x16x32_bf16 v[18:21], v[146:149], v[186:189], v[18:21]
	v_mfma_f32_16x16x32_bf16 v[6:9], v[134:137], v[200:203], v[6:9]
	v_mfma_f32_16x16x32_bf16 v[2:5], v[146:149], v[200:203], v[2:5]
	v_mfma_f32_16x16x32_bf16 v[54:57], v[138:141], v[166:169], v[54:57]
	v_mfma_f32_16x16x32_bf16 v[50:53], v[154:157], v[166:169], v[50:53]
	v_mfma_f32_16x16x32_bf16 v[38:41], v[138:141], v[174:177], v[38:41]
	v_mfma_f32_16x16x32_bf16 v[34:37], v[154:157], v[174:177], v[34:37]
	v_mfma_f32_16x16x32_bf16 v[22:25], v[138:141], v[190:193], v[22:25]
	v_mfma_f32_16x16x32_bf16 v[18:21], v[154:157], v[190:193], v[18:21]
	v_mfma_f32_16x16x32_bf16 v[6:9], v[138:141], v[206:209], v[6:9]
	v_mfma_f32_16x16x32_bf16 v[2:5], v[154:157], v[206:209], v[2:5]
	s_barrier
	s_add_i32 s58, 0, 0x18000
	s_add_i32 s59, 0, 0x1c000
	v_add_u32_e32 v126, s58, v195
	v_add_u32_e32 v154, s59, v195
	ds_read_b128 v[114:117], v126
	ds_read_b128 v[118:121], v126 offset:1024
	ds_read_b128 v[122:125], v126 offset:2048
	ds_read_b128 v[126:129], v126 offset:3072
	ds_read_b128 v[134:137], v154
	ds_read_b128 v[138:141], v154 offset:1024
	ds_read_b128 v[146:149], v154 offset:2048
	ds_read_b128 v[154:157], v154 offset:3072
	s_add_u32 s18, s64, 0xb0000
	s_addc_u32 s19, s65, 0
	s_mov_b32 m0, s68
	v_lshl_add_u64 v[218:219], s[18:19], 0, v[178:179]
	ds_read_b128 v[162:165], v217 offset:32768
	ds_read_b128 v[166:169], v217 offset:33792
	ds_read_b128 v[170:173], v217 offset:34816
	ds_read_b128 v[174:177], v217 offset:35840
	ds_read_b128 v[186:189], v217 offset:36864
	ds_read_b128 v[190:193], v217 offset:37888
	ds_read_b128 v[200:203], v217 offset:38912
	ds_read_b128 v[206:209], v217 offset:39936
	global_load_lds_dwordx4 v[218:219], off
	v_lshl_add_u64 v[218:219], s[18:19], 0, v[180:181]
	s_mov_b32 m0, s69
	s_nop 0
	global_load_lds_dwordx4 v[218:219], off
	s_waitcnt vmcnt(8)
	s_waitcnt lgkmcnt(0)
	s_barrier
; #define PG8_STAGE(bufoff, gbase, voff) do { _Pragma("unroll") for (int _i = 0; _i < 2; ++_i) \
;         __builtin_amdgcn_global_load_lds((const unsigned*)((const char*)(gbase) + (voff)[_i]), (LAS unsigned*)(lds + (bufoff) + ldsw + _i * 8192), 16, 0, 0); } while (0)
; #define PG8_LDA(dst, b, h) do { _Pragma("unroll") for (int m = 0; m < 4; ++m) _Pragma("unroll") for (int k = 0; k < 2; ++k) dst[m][k] = *(const LAS bf16x8*)(lds + PG8_SA(b, h) + aoff + m * 2048 + k * 1024); } while (0)
; #define PG8_MMA(ai, bj, At, Bt) do { __builtin_amdgcn_s_setprio(1); _Pragma("unroll") for (int m = 0; m < 4; ++m) _Pragma("unroll") for (int n = 0; n < 2; ++n) _Pragma("unroll") for (int k = 0; k < 2; ++k) \
;         acc[ai][bj][m][n] = __builtin_amdgcn_mfma_f32_16x16x32_bf16(Bt[n][k], At[m][k], acc[ai][bj][m][n], 0, 0, 0); __builtin_amdgcn_s_setprio(0); } while (0)
; #define PG8_WAIT_V(n) asm volatile("s_waitcnt vmcnt(" #n ")" ::: "memory")
; #define PG8_WAIT_L(n) asm volatile("s_waitcnt lgkmcnt(" #n ")" ::: "memory")
; #define PG8_BAR __builtin_amdgcn_s_barrier()
; #define PG8_SCHED __builtin_amdgcn_sched_barrier(0)
; template <class Epi>
; DI void gemm_phase(LAS unsigned char* lds, const Gemm g, const StaticOrder& S, const Epi& E) {
;     ...
;         for (int t = 0; t < nt; t += 2) {
;     ...
;             PG8_WAIT_V(8); PG8_WAIT_L(0); PG8_BAR; PG8_MMA(0, 0, At, B0); PG8_MMA(0, 1, At, B1); PG8_BAR; PG8_SCHED;
;             PG8_LDA(At, 1, 1); PG8_STAGE(PG8_SB(1, 0), b3, voffB); PG8_STAGE(PG8_SB(1, 1), b3 + hstep, voffB); PG8_STAGE(PG8_SA(1, 0), a3, voffA);
;             PG8_WAIT_V(8); PG8_WAIT_L(0); PG8_BAR; PG8_MMA(1, 0, At, B0); PG8_MMA(1, 1, At, B1); PG8_BAR; PG8_SCHED;
;         }
;         if (wr == 0) PG8_BAR;
	s_waitcnt lgkmcnt(0)
	v_mfma_f32_16x16x32_bf16 v[158:161], v[114:117], v[162:165], v[158:161]
	v_mfma_f32_16x16x32_bf16 v[150:153], v[122:125], v[162:165], v[150:153]
	v_mfma_f32_16x16x32_bf16 v[110:113], v[114:117], v[170:173], v[110:113]
	v_mfma_f32_16x16x32_bf16 v[106:109], v[122:125], v[170:173], v[106:109]
	v_mfma_f32_16x16x32_bf16 v[94:97], v[114:117], v[186:189], v[94:97]
	v_mfma_f32_16x16x32_bf16 v[90:93], v[122:125], v[186:189], v[90:93]
	v_mfma_f32_16x16x32_bf16 v[78:81], v[114:117], v[200:203], v[78:81]
	v_mfma_f32_16x16x32_bf16 v[74:77], v[122:125], v[200:203], v[74:77]
	v_mfma_f32_16x16x32_bf16 v[158:161], v[118:121], v[166:169], v[158:161]
	v_mfma_f32_16x16x32_bf16 v[150:153], v[126:129], v[166:169], v[150:153]
	v_mfma_f32_16x16x32_bf16 v[110:113], v[118:121], v[174:177], v[110:113]
	v_mfma_f32_16x16x32_bf16 v[106:109], v[126:129], v[174:177], v[106:109]
	v_mfma_f32_16x16x32_bf16 v[94:97], v[118:121], v[190:193], v[94:97]
	v_mfma_f32_16x16x32_bf16 v[90:93], v[126:129], v[190:193], v[90:93]
	v_mfma_f32_16x16x32_bf16 v[78:81], v[118:121], v[206:209], v[78:81]
	v_mfma_f32_16x16x32_bf16 v[74:77], v[126:129], v[206:209], v[74:77]
	v_mfma_f32_16x16x32_bf16 v[142:145], v[134:137], v[162:165], v[142:145]
	v_mfma_f32_16x16x32_bf16 v[130:133], v[146:149], v[162:165], v[130:133]
	v_mfma_f32_16x16x32_bf16 v[102:105], v[134:137], v[170:173], v[102:105]
	v_mfma_f32_16x16x32_bf16 v[98:101], v[146:149], v[170:173], v[98:101]
	v_mfma_f32_16x16x32_bf16 v[86:89], v[134:137], v[186:189], v[86:89]
	v_mfma_f32_16x16x32_bf16 v[82:85], v[146:149], v[186:189], v[82:85]
	v_mfma_f32_16x16x32_bf16 v[70:73], v[134:137], v[200:203], v[70:73]
	v_mfma_f32_16x16x32_bf16 v[66:69], v[146:149], v[200:203], v[66:69]
	v_mfma_f32_16x16x32_bf16 v[142:145], v[138:141], v[166:169], v[142:145]
	v_mfma_f32_16x16x32_bf16 v[130:133], v[154:157], v[166:169], v[130:133]
	v_mfma_f32_16x16x32_bf16 v[102:105], v[138:141], v[174:177], v[102:105]
	v_mfma_f32_16x16x32_bf16 v[98:101], v[154:157], v[174:177], v[98:101]
	v_mfma_f32_16x16x32_bf16 v[86:89], v[138:141], v[190:193], v[86:89]
	v_mfma_f32_16x16x32_bf16 v[82:85], v[154:157], v[190:193], v[82:85]
	v_mfma_f32_16x16x32_bf16 v[70:73], v[138:141], v[206:209], v[70:73]
	v_mfma_f32_16x16x32_bf16 v[66:69], v[154:157], v[206:209], v[66:69]
	s_barrier
	s_add_i32 s18, s58, s37
	v_lshl_add_u64 v[204:205], v[204:205], 0, s[20:21]
	s_mov_b32 m0, s18
	ds_read_b128 v[162:165], v217 offset:49152
	ds_read_b128 v[166:169], v217 offset:50176
	ds_read_b128 v[170:173], v217 offset:51200
	ds_read_b128 v[174:177], v217 offset:52224
	ds_read_b128 v[186:189], v217 offset:53248
	ds_read_b128 v[190:193], v217 offset:54272
	ds_read_b128 v[200:203], v217 offset:55296
	ds_read_b128 v[206:209], v217 offset:56320
	global_load_lds_dwordx4 v[204:205], off
	s_add_i32 m0, s18, 0x2000
	s_add_u32 s18, s62, 0xb0080
	v_lshl_add_u64 v[204:205], v[210:211], 0, s[20:21]
	s_addc_u32 s19, s63, 0
	s_add_i32 s58, s59, s37
	global_load_lds_dwordx4 v[204:205], off
	v_lshl_add_u64 v[204:205], s[18:19], 0, v[178:179]
	s_mov_b32 m0, s58
	s_nop 0
	global_load_lds_dwordx4 v[204:205], off
	v_lshl_add_u64 v[204:205], s[18:19], 0, v[180:181]
	s_add_i32 m0, s58, 0x2000
	s_nop 0
	global_load_lds_dwordx4 v[204:205], off
	v_lshl_add_u64 v[204:205], v[212:213], 0, s[20:21]
	s_mov_b32 m0, s71
	s_nop 0
	global_load_lds_dwordx4 v[204:205], off
	v_lshl_add_u64 v[204:205], v[214:215], 0, s[20:21]
	s_mov_b32 m0, s17
	s_nop 0
	global_load_lds_dwordx4 v[204:205], off
	s_waitcnt vmcnt(8)
	s_waitcnt lgkmcnt(0)
	s_barrier
	s_waitcnt lgkmcnt(0)
	v_mfma_f32_16x16x32_bf16 v[62:65], v[114:117], v[162:165], v[62:65]
	v_mfma_f32_16x16x32_bf16 v[58:61], v[122:125], v[162:165], v[58:61]
	v_mfma_f32_16x16x32_bf16 v[46:49], v[114:117], v[170:173], v[46:49]
	v_mfma_f32_16x16x32_bf16 v[42:45], v[122:125], v[170:173], v[42:45]
	v_mfma_f32_16x16x32_bf16 v[30:33], v[114:117], v[186:189], v[30:33]
	v_mfma_f32_16x16x32_bf16 v[26:29], v[122:125], v[186:189], v[26:29]
	v_mfma_f32_16x16x32_bf16 v[14:17], v[114:117], v[200:203], v[14:17]
	v_mfma_f32_16x16x32_bf16 v[10:13], v[122:125], v[200:203], v[10:13]
	v_mfma_f32_16x16x32_bf16 v[62:65], v[118:121], v[166:169], v[62:65]
	v_mfma_f32_16x16x32_bf16 v[58:61], v[126:129], v[166:169], v[58:61]
	v_mfma_f32_16x16x32_bf16 v[46:49], v[118:121], v[174:177], v[46:49]
	v_mfma_f32_16x16x32_bf16 v[42:45], v[126:129], v[174:177], v[42:45]
	v_mfma_f32_16x16x32_bf16 v[30:33], v[118:121], v[190:193], v[30:33]
	v_mfma_f32_16x16x32_bf16 v[26:29], v[126:129], v[190:193], v[26:29]
	v_mfma_f32_16x16x32_bf16 v[14:17], v[118:121], v[206:209], v[14:17]
	v_mfma_f32_16x16x32_bf16 v[10:13], v[126:129], v[206:209], v[10:13]
	v_mfma_f32_16x16x32_bf16 v[54:57], v[134:137], v[162:165], v[54:57]
	v_mfma_f32_16x16x32_bf16 v[50:53], v[146:149], v[162:165], v[50:53]
	v_mfma_f32_16x16x32_bf16 v[38:41], v[134:137], v[170:173], v[38:41]
	v_mfma_f32_16x16x32_bf16 v[34:37], v[146:149], v[170:173], v[34:37]
	v_mfma_f32_16x16x32_bf16 v[22:25], v[134:137], v[186:189], v[22:25]
	v_mfma_f32_16x16x32_bf16 v[18:21], v[146:149], v[186:189], v[18:21]
	v_mfma_f32_16x16x32_bf16 v[6:9], v[134:137], v[200:203], v[6:9]
	v_mfma_f32_16x16x32_bf16 v[2:5], v[146:149], v[200:203], v[2:5]
	v_mfma_f32_16x16x32_bf16 v[54:57], v[138:141], v[166:169], v[54:57]
	v_mfma_f32_16x16x32_bf16 v[50:53], v[154:157], v[166:169], v[50:53]
	v_mfma_f32_16x16x32_bf16 v[38:41], v[138:141], v[174:177], v[38:41]
	v_mfma_f32_16x16x32_bf16 v[34:37], v[154:157], v[174:177], v[34:37]
	v_mfma_f32_16x16x32_bf16 v[22:25], v[138:141], v[190:193], v[22:25]
	v_mfma_f32_16x16x32_bf16 v[18:21], v[154:157], v[190:193], v[18:21]
	v_mfma_f32_16x16x32_bf16 v[6:9], v[138:141], v[206:209], v[6:9]
	v_mfma_f32_16x16x32_bf16 v[2:5], v[154:157], v[206:209], v[2:5]
	s_barrier
	s_add_i32 s93, s93, 2
	s_add_u32 s73, s73, 0x100
	s_addc_u32 s91, s91, 0
	s_cmp_gt_u32 s93, 41
	s_mov_b64 s[58:59], s[60:61]
	s_cbranch_scc0 .LBB0_783
	s_setprio 0
	s_and_b64 vcc, exec, s[54:55]
	s_cbranch_vccz .LBB0_786
	s_barrier
